# pooling pass: prompt tasks load all 47 rows up front (counted vmcnt), window sums from registers
# speedup vs baseline: 1.0043x; 1.0043x over previous
; __device__ __forceinline__ void p3_pool(Frame& F) {
;     ...
;         int tk2 = gw + it * NGW;
;         if (remap) { if (it == 1) { if ((int)blockIdx.x < 192 || F.wave >= 4) break; tk2 = 2048 + ((int)blockIdx.x - 192) * 4 + F.wave; } else if (it > 1) break; }
;         if (tk2 >= 2 * (NPR / 32 + DBATCH)) break;
;         const int tk = tk2 >> 1, c0 = (tk2 & 1) * 256 + lane * 4, w = 2 << (c0 >> 7);
;         const bool isP = tk < NPR / 32;
;         const int b = isP ? (tk >> 6) : (tk - NPR / 32), s0 = isP ? ((tk & 63) << 5) : 0, nsteps = isP ? 47 : 23;
;         const size_t mbase = isP ? (size_t)b * SEQ : (size_t)NPR + (size_t)b * 8;
.LBB0_523:
	s_and_b64 vcc, exec, s[8:9]
	s_cbranch_vccz .LBB0_516
	s_cmpk_lt_i32 s24, 0x900
	s_cbranch_scc0 .LBB0_516
	s_ashr_i32 s25, s24, 1
	s_cmpk_lt_i32 s25, 0x400
	s_cbranch_scc1 .Lp3f_entry
	s_cmpk_gt_i32 s25, 0x3ff
	s_cselect_b64 s[6:7], -1, 0
	s_cmpk_lt_i32 s25, 0x400
	s_cselect_b64 s[8:9], -1, 0
	s_add_i32 s20, s25, 0xfffffc00
	s_and_b64 vcc, exec, s[6:7]
	s_cbranch_vccnz .LBB0_527
	s_ashr_i32 s10, s24, 7
	s_ashr_i32 s11, s10, 31
	s_lshl_b64 s[38:39], s[10:11], 11
	s_cbranch_execz .LBB0_528
	s_branch .LBB0_529

; #define U_LD(p) ({ const v2u w_ = *(const v2u*)(p); (f32x4){bflo(w_.x), bfhi(w_.x), bflo(w_.y), bfhi(w_.y)}; })
; __device__ __forceinline__ void p3_pool(Frame& F) {
;     ...
;         const int tk = tk2 >> 1, c0 = (tk2 & 1) * 256 + lane * 4, w = 2 << (c0 >> 7);
;         const bool isP = tk < NPR / 32;
;         const int b = isP ? (tk >> 6) : (tk - NPR / 32), s0 = isP ? ((tk & 63) << 5) : 0, nsteps = isP ? 47 : 23;
;         const size_t mbase = isP ? (size_t)b * SEQ : (size_t)NPR + (size_t)b * 8;
;         f32x4 S0 = (f32x4){0.f, 0.f, 0.f, 0.f};
; #pragma unroll 8
;         for (int i = 0; i < nsteps; ++i) {
;             const int s = s0 - 15 + i;
;             const int so = s - w;
;             f32x4 n0 = (f32x4){0.f, 0.f, 0.f, 0.f}, o0 = n0;
;             if (isP) {
;                 if (s >= 0) n0 = U_LD(U + (mbase + s) * 512 + c0);
;                 if (i >= w && so >= 0) o0 = U_LD(U + (mbase + so) * 512 + c0);
;             } else {
;                 if (s >= 0) n0 = U_LD(U + (mbase + s) * 512 + c0); else n0 = *(const f32x4*)(state_pool + ((size_t)b * 15 + (s + 15)) * 512 + c0);
;                 if (i >= w) { if (so >= 0) o0 = U_LD(U + (mbase + so) * 512 + c0); else o0 = *(const f32x4*)(state_pool + ((size_t)b * 15 + (so + 15)) * 512 + c0); }
;             }
;             S0 += n0 - o0;
;             if (i >= 15) {
.Lp3f_entry:
	s_and_b32 s82, s24, 1
	s_lshr_b32 s83, s24, 7
	s_and_b32 s84, s25, 63
	s_lshl_b32 s85, s83, 11
	s_lshl_b32 s86, s84, 5
	s_add_i32 s85, s85, s86
	v_lshlrev_b32_e32 v36, 1, v32
	s_movk_i32 s87, 0x80
	v_cmp_le_u32_e64 s[94:95], s87, v32
	s_lshl_b32 s87, s82, 9
	s_lshl_b32 s88, s85, 10
	s_add_u32 s88, s88, s87
	s_add_u32 s88, s12, s88
	s_addc_u32 s89, s13, 0
	s_mul_i32 s92, s82, 0x1080000
	s_lshl_b32 s93, s85, 9
	s_add_u32 s92, s92, s93
	s_add_u32 s92, s92, 0xb400000
	s_add_u32 s90, s12, s92
	s_addc_u32 s91, s13, 0
	s_cmp_eq_u32 s84, 0
	s_cbranch_scc1 .Lp3f_ld15
	s_sub_u32 s96, s88, 0x3c00
	s_subb_u32 s97, s89, 0
	global_load_dwordx2 v[40:41], v36, s[96:97]
	global_load_dwordx2 v[42:43], v36, s[96:97] offset:1024
	global_load_dwordx2 v[44:45], v36, s[96:97] offset:2048
	global_load_dwordx2 v[46:47], v36, s[96:97] offset:3072
	s_add_u32 s96, s96, 0x1000
	s_addc_u32 s97, s97, 0
	global_load_dwordx2 v[48:49], v36, s[96:97]
	global_load_dwordx2 v[50:51], v36, s[96:97] offset:1024
	global_load_dwordx2 v[52:53], v36, s[96:97] offset:2048
	global_load_dwordx2 v[54:55], v36, s[96:97] offset:3072
	s_add_u32 s96, s96, 0x1000
	s_addc_u32 s97, s97, 0
	global_load_dwordx2 v[56:57], v36, s[96:97]
	global_load_dwordx2 v[58:59], v36, s[96:97] offset:1024
	global_load_dwordx2 v[60:61], v36, s[96:97] offset:2048
	global_load_dwordx2 v[62:63], v36, s[96:97] offset:3072
	s_add_u32 s96, s96, 0x1000
	s_addc_u32 s97, s97, 0
	global_load_dwordx2 v[64:65], v36, s[96:97]
	global_load_dwordx2 v[66:67], v36, s[96:97] offset:1024
	global_load_dwordx2 v[68:69], v36, s[96:97] offset:2048
.Lp3f_ld15:
	s_mov_b64 s[96:97], s[88:89]
	global_load_dwordx2 v[70:71], v36, s[96:97]
	global_load_dwordx2 v[72:73], v36, s[96:97] offset:1024
	global_load_dwordx2 v[74:75], v36, s[96:97] offset:2048
	global_load_dwordx2 v[76:77], v36, s[96:97] offset:3072
	s_add_u32 s96, s96, 0x1000
	s_addc_u32 s97, s97, 0
	global_load_dwordx2 v[78:79], v36, s[96:97]
	global_load_dwordx2 v[80:81], v36, s[96:97] offset:1024
	global_load_dwordx2 v[82:83], v36, s[96:97] offset:2048
	global_load_dwordx2 v[84:85], v36, s[96:97] offset:3072
	s_add_u32 s96, s96, 0x1000
	s_addc_u32 s97, s97, 0
	global_load_dwordx2 v[86:87], v36, s[96:97]
	global_load_dwordx2 v[88:89], v36, s[96:97] offset:1024
	global_load_dwordx2 v[90:91], v36, s[96:97] offset:2048
	global_load_dwordx2 v[92:93], v36, s[96:97] offset:3072
	s_add_u32 s96, s96, 0x1000
	s_addc_u32 s97, s97, 0
	global_load_dwordx2 v[94:95], v36, s[96:97]
	global_load_dwordx2 v[96:97], v36, s[96:97] offset:1024
	global_load_dwordx2 v[98:99], v36, s[96:97] offset:2048
	global_load_dwordx2 v[100:101], v36, s[96:97] offset:3072
	s_add_u32 s96, s96, 0x1000
	s_addc_u32 s97, s97, 0
	global_load_dwordx2 v[102:103], v36, s[96:97]
	global_load_dwordx2 v[104:105], v36, s[96:97] offset:1024
	global_load_dwordx2 v[106:107], v36, s[96:97] offset:2048
	global_load_dwordx2 v[108:109], v36, s[96:97] offset:3072
	s_add_u32 s96, s96, 0x1000
	s_addc_u32 s97, s97, 0
	global_load_dwordx2 v[110:111], v36, s[96:97]
	global_load_dwordx2 v[112:113], v36, s[96:97] offset:1024
	global_load_dwordx2 v[114:115], v36, s[96:97] offset:2048
	global_load_dwordx2 v[116:117], v36, s[96:97] offset:3072
	s_add_u32 s96, s96, 0x1000
	s_addc_u32 s97, s97, 0
	global_load_dwordx2 v[118:119], v36, s[96:97]
	global_load_dwordx2 v[120:121], v36, s[96:97] offset:1024
	global_load_dwordx2 v[122:123], v36, s[96:97] offset:2048
	global_load_dwordx2 v[124:125], v36, s[96:97] offset:3072
	s_add_u32 s96, s96, 0x1000
	s_addc_u32 s97, s97, 0
	global_load_dwordx2 v[126:127], v36, s[96:97]
	global_load_dwordx2 v[128:129], v36, s[96:97] offset:1024
	global_load_dwordx2 v[130:131], v36, s[96:97] offset:2048
	global_load_dwordx2 v[132:133], v36, s[96:97] offset:3072
	s_cmp_eq_u32 s84, 0
	s_cbranch_scc1 .Lp3f_first
	s_cmp_eq_u32 s82, 0
	s_cbranch_scc0 .Lp3f_n1
	v_mov_b32_e32 v140, 0
	v_mov_b32_e32 v141, 0
	v_mov_b32_e32 v142, 0
	v_mov_b32_e32 v143, 0
	v_mov_b32_e32 v166, 0
	v_mov_b32_e32 v167, 0
	v_mov_b32_e32 v168, 0x3f000000
	v_mov_b32_e32 v169, 0x3e800000
	v_cndmask_b32_e64 v164, v168, v169, s[94:95]
	s_mov_b64 s[96:97], s[90:91]
	s_waitcnt vmcnt(46)
	v_lshlrev_b32_e32 v144, 16, v40
	v_and_b32_e32 v145, 0xffff0000, v40
	v_lshlrev_b32_e32 v146, 16, v41
	v_and_b32_e32 v147, 0xffff0000, v41
	v_pk_add_f32 v[140:141], v[140:141], v[144:145]
	v_pk_add_f32 v[142:143], v[142:143], v[146:147]
	s_waitcnt vmcnt(45)
	v_lshlrev_b32_e32 v144, 16, v42
	v_and_b32_e32 v145, 0xffff0000, v42
	v_lshlrev_b32_e32 v146, 16, v43
	v_and_b32_e32 v147, 0xffff0000, v43
	v_pk_add_f32 v[140:141], v[140:141], v[144:145]
	v_pk_add_f32 v[142:143], v[142:143], v[146:147]
	s_waitcnt vmcnt(44)
	v_lshlrev_b32_e32 v144, 16, v44
	v_and_b32_e32 v145, 0xffff0000, v44
	v_lshlrev_b32_e32 v146, 16, v45
	v_and_b32_e32 v147, 0xffff0000, v45
	v_cndmask_b32_e64 v148, v40, v166, s[94:95]
	v_cndmask_b32_e64 v149, v41, v167, s[94:95]
	v_lshlrev_b32_e32 v150, 16, v148
	v_and_b32_e32 v151, 0xffff0000, v148
	v_lshlrev_b32_e32 v152, 16, v149
	v_and_b32_e32 v153, 0xffff0000, v149
	v_pk_add_f32 v[154:155], v[144:145], v[150:151] neg_lo:[0,1] neg_hi:[0,1]
	v_pk_add_f32 v[156:157], v[146:147], v[152:153] neg_lo:[0,1] neg_hi:[0,1]
	v_pk_add_f32 v[140:141], v[140:141], v[154:155]
	v_pk_add_f32 v[142:143], v[142:143], v[156:157]
	s_waitcnt vmcnt(43)
	v_lshlrev_b32_e32 v144, 16, v46
	v_and_b32_e32 v145, 0xffff0000, v46
	v_lshlrev_b32_e32 v146, 16, v47
	v_and_b32_e32 v147, 0xffff0000, v47
	v_cndmask_b32_e64 v148, v42, v166, s[94:95]
	v_cndmask_b32_e64 v149, v43, v167, s[94:95]
	v_lshlrev_b32_e32 v150, 16, v148
	v_and_b32_e32 v151, 0xffff0000, v148
	v_lshlrev_b32_e32 v152, 16, v149
	v_and_b32_e32 v153, 0xffff0000, v149
	v_pk_add_f32 v[154:155], v[144:145], v[150:151] neg_lo:[0,1] neg_hi:[0,1]
	v_pk_add_f32 v[156:157], v[146:147], v[152:153] neg_lo:[0,1] neg_hi:[0,1]
	v_pk_add_f32 v[140:141], v[140:141], v[154:155]
	v_pk_add_f32 v[142:143], v[142:143], v[156:157]
	s_waitcnt vmcnt(42)
; #define U_LD(p) ({ const v2u w_ = *(const v2u*)(p); (f32x4){bflo(w_.x), bfhi(w_.x), bflo(w_.y), bfhi(w_.y)}; })
; __device__ __forceinline__ void p3_pool(Frame& F) {
;     ...
;         for (int i = 0; i < nsteps; ++i) {
;             const int s = s0 - 15 + i;
;             const int so = s - w;
;             f32x4 n0 = (f32x4){0.f, 0.f, 0.f, 0.f}, o0 = n0;
;             if (isP) {
;                 if (s >= 0) n0 = U_LD(U + (mbase + s) * 512 + c0);
;                 if (i >= w && so >= 0) o0 = U_LD(U + (mbase + so) * 512 + c0);
;             } else {
;                 if (s >= 0) n0 = U_LD(U + (mbase + s) * 512 + c0); else n0 = *(const f32x4*)(state_pool + ((size_t)b * 15 + (s + 15)) * 512 + c0);
;                 if (i >= w) { if (so >= 0) o0 = U_LD(U + (mbase + so) * 512 + c0); else o0 = *(const f32x4*)(state_pool + ((size_t)b * 15 + (so + 15)) * 512 + c0); }
;             }
;             S0 += n0 - o0;
	v_lshlrev_b32_e32 v144, 16, v48
	v_and_b32_e32 v145, 0xffff0000, v48
	v_lshlrev_b32_e32 v146, 16, v49
	v_and_b32_e32 v147, 0xffff0000, v49
	v_cndmask_b32_e64 v148, v44, v40, s[94:95]
	v_cndmask_b32_e64 v149, v45, v41, s[94:95]
	v_lshlrev_b32_e32 v150, 16, v148
	v_and_b32_e32 v151, 0xffff0000, v148
	v_lshlrev_b32_e32 v152, 16, v149
	v_and_b32_e32 v153, 0xffff0000, v149
	v_pk_add_f32 v[154:155], v[144:145], v[150:151] neg_lo:[0,1] neg_hi:[0,1]
	v_pk_add_f32 v[156:157], v[146:147], v[152:153] neg_lo:[0,1] neg_hi:[0,1]
	v_pk_add_f32 v[140:141], v[140:141], v[154:155]
	v_pk_add_f32 v[142:143], v[142:143], v[156:157]
	s_waitcnt vmcnt(41)
	v_lshlrev_b32_e32 v144, 16, v50
	v_and_b32_e32 v145, 0xffff0000, v50
	v_lshlrev_b32_e32 v146, 16, v51
	v_and_b32_e32 v147, 0xffff0000, v51
	v_cndmask_b32_e64 v148, v46, v42, s[94:95]
	v_cndmask_b32_e64 v149, v47, v43, s[94:95]
	v_lshlrev_b32_e32 v150, 16, v148
	v_and_b32_e32 v151, 0xffff0000, v148
	v_lshlrev_b32_e32 v152, 16, v149
	v_and_b32_e32 v153, 0xffff0000, v149
	v_pk_add_f32 v[154:155], v[144:145], v[150:151] neg_lo:[0,1] neg_hi:[0,1]
	v_pk_add_f32 v[156:157], v[146:147], v[152:153] neg_lo:[0,1] neg_hi:[0,1]
	v_pk_add_f32 v[140:141], v[140:141], v[154:155]
	v_pk_add_f32 v[142:143], v[142:143], v[156:157]
	s_waitcnt vmcnt(40)
	v_lshlrev_b32_e32 v144, 16, v52
	v_and_b32_e32 v145, 0xffff0000, v52
	v_lshlrev_b32_e32 v146, 16, v53
	v_and_b32_e32 v147, 0xffff0000, v53
	v_cndmask_b32_e64 v148, v48, v44, s[94:95]
	v_cndmask_b32_e64 v149, v49, v45, s[94:95]
	v_lshlrev_b32_e32 v150, 16, v148
	v_and_b32_e32 v151, 0xffff0000, v148
	v_lshlrev_b32_e32 v152, 16, v149
	v_and_b32_e32 v153, 0xffff0000, v149
	v_pk_add_f32 v[154:155], v[144:145], v[150:151] neg_lo:[0,1] neg_hi:[0,1]
	v_pk_add_f32 v[156:157], v[146:147], v[152:153] neg_lo:[0,1] neg_hi:[0,1]
	v_pk_add_f32 v[140:141], v[140:141], v[154:155]
	v_pk_add_f32 v[142:143], v[142:143], v[156:157]
	s_waitcnt vmcnt(39)
	v_lshlrev_b32_e32 v144, 16, v54
	v_and_b32_e32 v145, 0xffff0000, v54
	v_lshlrev_b32_e32 v146, 16, v55
	v_and_b32_e32 v147, 0xffff0000, v55
	v_cndmask_b32_e64 v148, v50, v46, s[94:95]
	v_cndmask_b32_e64 v149, v51, v47, s[94:95]
	v_lshlrev_b32_e32 v150, 16, v148
	v_and_b32_e32 v151, 0xffff0000, v148
	v_lshlrev_b32_e32 v152, 16, v149
	v_and_b32_e32 v153, 0xffff0000, v149
	v_pk_add_f32 v[154:155], v[144:145], v[150:151] neg_lo:[0,1] neg_hi:[0,1]
	v_pk_add_f32 v[156:157], v[146:147], v[152:153] neg_lo:[0,1] neg_hi:[0,1]
	v_pk_add_f32 v[140:141], v[140:141], v[154:155]
	v_pk_add_f32 v[142:143], v[142:143], v[156:157]
	s_waitcnt vmcnt(38)
	v_lshlrev_b32_e32 v144, 16, v56
	v_and_b32_e32 v145, 0xffff0000, v56
	v_lshlrev_b32_e32 v146, 16, v57
	v_and_b32_e32 v147, 0xffff0000, v57
	v_cndmask_b32_e64 v148, v52, v48, s[94:95]
	v_cndmask_b32_e64 v149, v53, v49, s[94:95]
	v_lshlrev_b32_e32 v150, 16, v148
	v_and_b32_e32 v151, 0xffff0000, v148
	v_lshlrev_b32_e32 v152, 16, v149
	v_and_b32_e32 v153, 0xffff0000, v149
	v_pk_add_f32 v[154:155], v[144:145], v[150:151] neg_lo:[0,1] neg_hi:[0,1]
	v_pk_add_f32 v[156:157], v[146:147], v[152:153] neg_lo:[0,1] neg_hi:[0,1]
	v_pk_add_f32 v[140:141], v[140:141], v[154:155]
	v_pk_add_f32 v[142:143], v[142:143], v[156:157]
	s_waitcnt vmcnt(37)
	v_lshlrev_b32_e32 v144, 16, v58
	v_and_b32_e32 v145, 0xffff0000, v58
	v_lshlrev_b32_e32 v146, 16, v59
	v_and_b32_e32 v147, 0xffff0000, v59
	v_cndmask_b32_e64 v148, v54, v50, s[94:95]
	v_cndmask_b32_e64 v149, v55, v51, s[94:95]
	v_lshlrev_b32_e32 v150, 16, v148
	v_and_b32_e32 v151, 0xffff0000, v148
	v_lshlrev_b32_e32 v152, 16, v149
	v_and_b32_e32 v153, 0xffff0000, v149
	v_pk_add_f32 v[154:155], v[144:145], v[150:151] neg_lo:[0,1] neg_hi:[0,1]
	v_pk_add_f32 v[156:157], v[146:147], v[152:153] neg_lo:[0,1] neg_hi:[0,1]
	v_pk_add_f32 v[140:141], v[140:141], v[154:155]
	v_pk_add_f32 v[142:143], v[142:143], v[156:157]
	s_waitcnt vmcnt(36)
	v_lshlrev_b32_e32 v144, 16, v60
	v_and_b32_e32 v145, 0xffff0000, v60
	v_lshlrev_b32_e32 v146, 16, v61
	v_and_b32_e32 v147, 0xffff0000, v61
	v_cndmask_b32_e64 v148, v56, v52, s[94:95]
	v_cndmask_b32_e64 v149, v57, v53, s[94:95]
	v_lshlrev_b32_e32 v150, 16, v148
	v_and_b32_e32 v151, 0xffff0000, v148
	v_lshlrev_b32_e32 v152, 16, v149
	v_and_b32_e32 v153, 0xffff0000, v149
	v_pk_add_f32 v[154:155], v[144:145], v[150:151] neg_lo:[0,1] neg_hi:[0,1]
	v_pk_add_f32 v[156:157], v[146:147], v[152:153] neg_lo:[0,1] neg_hi:[0,1]
	v_pk_add_f32 v[140:141], v[140:141], v[154:155]
	v_pk_add_f32 v[142:143], v[142:143], v[156:157]
	s_waitcnt vmcnt(35)
	v_lshlrev_b32_e32 v144, 16, v62
	v_and_b32_e32 v145, 0xffff0000, v62
	v_lshlrev_b32_e32 v146, 16, v63
	v_and_b32_e32 v147, 0xffff0000, v63
	v_cndmask_b32_e64 v148, v58, v54, s[94:95]
	v_cndmask_b32_e64 v149, v59, v55, s[94:95]
	v_lshlrev_b32_e32 v150, 16, v148
	v_and_b32_e32 v151, 0xffff0000, v148
	v_lshlrev_b32_e32 v152, 16, v149
	v_and_b32_e32 v153, 0xffff0000, v149
	v_pk_add_f32 v[154:155], v[144:145], v[150:151] neg_lo:[0,1] neg_hi:[0,1]
	v_pk_add_f32 v[156:157], v[146:147], v[152:153] neg_lo:[0,1] neg_hi:[0,1]
	v_pk_add_f32 v[140:141], v[140:141], v[154:155]
	v_pk_add_f32 v[142:143], v[142:143], v[156:157]
	s_waitcnt vmcnt(34)
	v_lshlrev_b32_e32 v144, 16, v64
	v_and_b32_e32 v145, 0xffff0000, v64
	v_lshlrev_b32_e32 v146, 16, v65
	v_and_b32_e32 v147, 0xffff0000, v65
	v_cndmask_b32_e64 v148, v60, v56, s[94:95]
	v_cndmask_b32_e64 v149, v61, v57, s[94:95]
	v_lshlrev_b32_e32 v150, 16, v148
	v_and_b32_e32 v151, 0xffff0000, v148
	v_lshlrev_b32_e32 v152, 16, v149
	v_and_b32_e32 v153, 0xffff0000, v149
	v_pk_add_f32 v[154:155], v[144:145], v[150:151] neg_lo:[0,1] neg_hi:[0,1]
	v_pk_add_f32 v[156:157], v[146:147], v[152:153] neg_lo:[0,1] neg_hi:[0,1]
	v_pk_add_f32 v[140:141], v[140:141], v[154:155]
	v_pk_add_f32 v[142:143], v[142:143], v[156:157]
	s_waitcnt vmcnt(33)
; #define GAS __attribute__((address_space(1)))
; __device__ __forceinline__ unsigned pk2(float lo, float hi) { f32x2_t v = {lo, hi}; bf16x2_t b = __builtin_convertvector(v, bf16x2_t); return __builtin_bit_cast(unsigned, b); }
; #define U_LD(p) ({ const v2u w_ = *(const v2u*)(p); (f32x4){bflo(w_.x), bfhi(w_.x), bflo(w_.y), bfhi(w_.y)}; })
; __device__ __forceinline__ void p3_pool(Frame& F) {
;     ...
;         for (int i = 0; i < nsteps; ++i) {
;             const int s = s0 - 15 + i;
;             const int so = s - w;
;             f32x4 n0 = (f32x4){0.f, 0.f, 0.f, 0.f}, o0 = n0;
;             if (isP) {
;                 if (s >= 0) n0 = U_LD(U + (mbase + s) * 512 + c0);
;                 if (i >= w && so >= 0) o0 = U_LD(U + (mbase + so) * 512 + c0);
;             } else {
;                 if (s >= 0) n0 = U_LD(U + (mbase + s) * 512 + c0); else n0 = *(const f32x4*)(state_pool + ((size_t)b * 15 + (s + 15)) * 512 + c0);
;                 if (i >= w) { if (so >= 0) o0 = U_LD(U + (mbase + so) * 512 + c0); else o0 = *(const f32x4*)(state_pool + ((size_t)b * 15 + (so + 15)) * 512 + c0); }
;             }
;             S0 += n0 - o0;
;             if (i >= 15) {
;                 const int cnt = isP ? (w < s + 1 ? w : s + 1) : w; const float inv = 1.f / (float)cnt;
;                 const f32x4 d0 = S0 * inv - n0;
;                 v2u wv; wv.x = pk2(d0[0], d0[1]); wv.y = pk2(d0[2], d0[3]);
;                 *(GAS v2u*)(D + (size_t)(c0 >> 8) * ((size_t)MT * 256) + (mbase + s) * 256 + (c0 & 255)) = wv;
	v_lshlrev_b32_e32 v144, 16, v66
	v_and_b32_e32 v145, 0xffff0000, v66
	v_lshlrev_b32_e32 v146, 16, v67
	v_and_b32_e32 v147, 0xffff0000, v67
	v_cndmask_b32_e64 v148, v62, v58, s[94:95]
	v_cndmask_b32_e64 v149, v63, v59, s[94:95]
	v_lshlrev_b32_e32 v150, 16, v148
	v_and_b32_e32 v151, 0xffff0000, v148
	v_lshlrev_b32_e32 v152, 16, v149
	v_and_b32_e32 v153, 0xffff0000, v149
	v_pk_add_f32 v[154:155], v[144:145], v[150:151] neg_lo:[0,1] neg_hi:[0,1]
	v_pk_add_f32 v[156:157], v[146:147], v[152:153] neg_lo:[0,1] neg_hi:[0,1]
	v_pk_add_f32 v[140:141], v[140:141], v[154:155]
	v_pk_add_f32 v[142:143], v[142:143], v[156:157]
	s_waitcnt vmcnt(32)
	v_lshlrev_b32_e32 v144, 16, v68
	v_and_b32_e32 v145, 0xffff0000, v68
	v_lshlrev_b32_e32 v146, 16, v69
	v_and_b32_e32 v147, 0xffff0000, v69
	v_cndmask_b32_e64 v148, v64, v60, s[94:95]
	v_cndmask_b32_e64 v149, v65, v61, s[94:95]
	v_lshlrev_b32_e32 v150, 16, v148
	v_and_b32_e32 v151, 0xffff0000, v148
	v_lshlrev_b32_e32 v152, 16, v149
	v_and_b32_e32 v153, 0xffff0000, v149
	v_pk_add_f32 v[154:155], v[144:145], v[150:151] neg_lo:[0,1] neg_hi:[0,1]
	v_pk_add_f32 v[156:157], v[146:147], v[152:153] neg_lo:[0,1] neg_hi:[0,1]
	v_pk_add_f32 v[140:141], v[140:141], v[154:155]
	v_pk_add_f32 v[142:143], v[142:143], v[156:157]
	s_waitcnt vmcnt(31)
	v_lshlrev_b32_e32 v144, 16, v70
	v_and_b32_e32 v145, 0xffff0000, v70
	v_lshlrev_b32_e32 v146, 16, v71
	v_and_b32_e32 v147, 0xffff0000, v71
	v_cndmask_b32_e64 v148, v66, v62, s[94:95]
	v_cndmask_b32_e64 v149, v67, v63, s[94:95]
	v_lshlrev_b32_e32 v150, 16, v148
	v_and_b32_e32 v151, 0xffff0000, v148
	v_lshlrev_b32_e32 v152, 16, v149
	v_and_b32_e32 v153, 0xffff0000, v149
	v_pk_add_f32 v[154:155], v[144:145], v[150:151] neg_lo:[0,1] neg_hi:[0,1]
	v_pk_add_f32 v[156:157], v[146:147], v[152:153] neg_lo:[0,1] neg_hi:[0,1]
	v_pk_add_f32 v[140:141], v[140:141], v[154:155]
	v_pk_add_f32 v[142:143], v[142:143], v[156:157]
	v_pk_fma_f32 v[158:159], v[164:165], v[140:141], v[144:145] op_sel_hi:[0,1,1] neg_lo:[0,0,1] neg_hi:[0,0,1]
	v_pk_fma_f32 v[160:161], v[164:165], v[142:143], v[146:147] op_sel_hi:[0,1,1] neg_lo:[0,0,1] neg_hi:[0,0,1]
	v_cvt_pk_bf16_f32 v162, v158, v159
	v_cvt_pk_bf16_f32 v163, v160, v161
	global_store_dwordx2 v36, v[162:163], s[96:97]
	s_waitcnt vmcnt(31)
	v_lshlrev_b32_e32 v144, 16, v72
	v_and_b32_e32 v145, 0xffff0000, v72
	v_lshlrev_b32_e32 v146, 16, v73
	v_and_b32_e32 v147, 0xffff0000, v73
	v_cndmask_b32_e64 v148, v68, v64, s[94:95]
	v_cndmask_b32_e64 v149, v69, v65, s[94:95]
	v_lshlrev_b32_e32 v150, 16, v148
	v_and_b32_e32 v151, 0xffff0000, v148
	v_lshlrev_b32_e32 v152, 16, v149
	v_and_b32_e32 v153, 0xffff0000, v149
	v_pk_add_f32 v[154:155], v[144:145], v[150:151] neg_lo:[0,1] neg_hi:[0,1]
	v_pk_add_f32 v[156:157], v[146:147], v[152:153] neg_lo:[0,1] neg_hi:[0,1]
	v_pk_add_f32 v[140:141], v[140:141], v[154:155]
	v_pk_add_f32 v[142:143], v[142:143], v[156:157]
	v_pk_fma_f32 v[158:159], v[164:165], v[140:141], v[144:145] op_sel_hi:[0,1,1] neg_lo:[0,0,1] neg_hi:[0,0,1]
	v_pk_fma_f32 v[160:161], v[164:165], v[142:143], v[146:147] op_sel_hi:[0,1,1] neg_lo:[0,0,1] neg_hi:[0,0,1]
	v_cvt_pk_bf16_f32 v162, v158, v159
	v_cvt_pk_bf16_f32 v163, v160, v161
	global_store_dwordx2 v36, v[162:163], s[96:97] offset:512
	s_waitcnt vmcnt(31)
	v_lshlrev_b32_e32 v144, 16, v74
	v_and_b32_e32 v145, 0xffff0000, v74
	v_lshlrev_b32_e32 v146, 16, v75
	v_and_b32_e32 v147, 0xffff0000, v75
	v_cndmask_b32_e64 v148, v70, v66, s[94:95]
	v_cndmask_b32_e64 v149, v71, v67, s[94:95]
	v_lshlrev_b32_e32 v150, 16, v148
	v_and_b32_e32 v151, 0xffff0000, v148
	v_lshlrev_b32_e32 v152, 16, v149
	v_and_b32_e32 v153, 0xffff0000, v149
	v_pk_add_f32 v[154:155], v[144:145], v[150:151] neg_lo:[0,1] neg_hi:[0,1]
	v_pk_add_f32 v[156:157], v[146:147], v[152:153] neg_lo:[0,1] neg_hi:[0,1]
	v_pk_add_f32 v[140:141], v[140:141], v[154:155]
	v_pk_add_f32 v[142:143], v[142:143], v[156:157]
	v_pk_fma_f32 v[158:159], v[164:165], v[140:141], v[144:145] op_sel_hi:[0,1,1] neg_lo:[0,0,1] neg_hi:[0,0,1]
	v_pk_fma_f32 v[160:161], v[164:165], v[142:143], v[146:147] op_sel_hi:[0,1,1] neg_lo:[0,0,1] neg_hi:[0,0,1]
	v_cvt_pk_bf16_f32 v162, v158, v159
	v_cvt_pk_bf16_f32 v163, v160, v161
	global_store_dwordx2 v36, v[162:163], s[96:97] offset:1024
	s_waitcnt vmcnt(31)
	v_lshlrev_b32_e32 v144, 16, v76
	v_and_b32_e32 v145, 0xffff0000, v76
	v_lshlrev_b32_e32 v146, 16, v77
	v_and_b32_e32 v147, 0xffff0000, v77
	v_cndmask_b32_e64 v148, v72, v68, s[94:95]
	v_cndmask_b32_e64 v149, v73, v69, s[94:95]
	v_lshlrev_b32_e32 v150, 16, v148
	v_and_b32_e32 v151, 0xffff0000, v148
	v_lshlrev_b32_e32 v152, 16, v149
	v_and_b32_e32 v153, 0xffff0000, v149
	v_pk_add_f32 v[154:155], v[144:145], v[150:151] neg_lo:[0,1] neg_hi:[0,1]
	v_pk_add_f32 v[156:157], v[146:147], v[152:153] neg_lo:[0,1] neg_hi:[0,1]
	v_pk_add_f32 v[140:141], v[140:141], v[154:155]
	v_pk_add_f32 v[142:143], v[142:143], v[156:157]
	v_pk_fma_f32 v[158:159], v[164:165], v[140:141], v[144:145] op_sel_hi:[0,1,1] neg_lo:[0,0,1] neg_hi:[0,0,1]
	v_pk_fma_f32 v[160:161], v[164:165], v[142:143], v[146:147] op_sel_hi:[0,1,1] neg_lo:[0,0,1] neg_hi:[0,0,1]
	v_cvt_pk_bf16_f32 v162, v158, v159
	v_cvt_pk_bf16_f32 v163, v160, v161
	global_store_dwordx2 v36, v[162:163], s[96:97] offset:1536
	s_waitcnt vmcnt(31)
; #define GAS __attribute__((address_space(1)))
; __device__ __forceinline__ unsigned pk2(float lo, float hi) { f32x2_t v = {lo, hi}; bf16x2_t b = __builtin_convertvector(v, bf16x2_t); return __builtin_bit_cast(unsigned, b); }
; #define U_LD(p) ({ const v2u w_ = *(const v2u*)(p); (f32x4){bflo(w_.x), bfhi(w_.x), bflo(w_.y), bfhi(w_.y)}; })
; __device__ __forceinline__ void p3_pool(Frame& F) {
;     ...
;         for (int i = 0; i < nsteps; ++i) {
;             const int s = s0 - 15 + i;
;             const int so = s - w;
;             f32x4 n0 = (f32x4){0.f, 0.f, 0.f, 0.f}, o0 = n0;
;             if (isP) {
;                 if (s >= 0) n0 = U_LD(U + (mbase + s) * 512 + c0);
;                 if (i >= w && so >= 0) o0 = U_LD(U + (mbase + so) * 512 + c0);
;             } else {
;                 if (s >= 0) n0 = U_LD(U + (mbase + s) * 512 + c0); else n0 = *(const f32x4*)(state_pool + ((size_t)b * 15 + (s + 15)) * 512 + c0);
;                 if (i >= w) { if (so >= 0) o0 = U_LD(U + (mbase + so) * 512 + c0); else o0 = *(const f32x4*)(state_pool + ((size_t)b * 15 + (so + 15)) * 512 + c0); }
;             }
;             S0 += n0 - o0;
;             if (i >= 15) {
;                 const int cnt = isP ? (w < s + 1 ? w : s + 1) : w; const float inv = 1.f / (float)cnt;
;                 const f32x4 d0 = S0 * inv - n0;
;                 v2u wv; wv.x = pk2(d0[0], d0[1]); wv.y = pk2(d0[2], d0[3]);
;                 *(GAS v2u*)(D + (size_t)(c0 >> 8) * ((size_t)MT * 256) + (mbase + s) * 256 + (c0 & 255)) = wv;
	v_lshlrev_b32_e32 v144, 16, v78
	v_and_b32_e32 v145, 0xffff0000, v78
	v_lshlrev_b32_e32 v146, 16, v79
	v_and_b32_e32 v147, 0xffff0000, v79
	v_cndmask_b32_e64 v148, v74, v70, s[94:95]
	v_cndmask_b32_e64 v149, v75, v71, s[94:95]
	v_lshlrev_b32_e32 v150, 16, v148
	v_and_b32_e32 v151, 0xffff0000, v148
	v_lshlrev_b32_e32 v152, 16, v149
	v_and_b32_e32 v153, 0xffff0000, v149
	v_pk_add_f32 v[154:155], v[144:145], v[150:151] neg_lo:[0,1] neg_hi:[0,1]
	v_pk_add_f32 v[156:157], v[146:147], v[152:153] neg_lo:[0,1] neg_hi:[0,1]
	v_pk_add_f32 v[140:141], v[140:141], v[154:155]
	v_pk_add_f32 v[142:143], v[142:143], v[156:157]
	v_pk_fma_f32 v[158:159], v[164:165], v[140:141], v[144:145] op_sel_hi:[0,1,1] neg_lo:[0,0,1] neg_hi:[0,0,1]
	v_pk_fma_f32 v[160:161], v[164:165], v[142:143], v[146:147] op_sel_hi:[0,1,1] neg_lo:[0,0,1] neg_hi:[0,0,1]
	v_cvt_pk_bf16_f32 v162, v158, v159
	v_cvt_pk_bf16_f32 v163, v160, v161
	global_store_dwordx2 v36, v[162:163], s[96:97] offset:2048
	s_waitcnt vmcnt(31)
	v_lshlrev_b32_e32 v144, 16, v80
	v_and_b32_e32 v145, 0xffff0000, v80
	v_lshlrev_b32_e32 v146, 16, v81
	v_and_b32_e32 v147, 0xffff0000, v81
	v_cndmask_b32_e64 v148, v76, v72, s[94:95]
	v_cndmask_b32_e64 v149, v77, v73, s[94:95]
	v_lshlrev_b32_e32 v150, 16, v148
	v_and_b32_e32 v151, 0xffff0000, v148
	v_lshlrev_b32_e32 v152, 16, v149
	v_and_b32_e32 v153, 0xffff0000, v149
	v_pk_add_f32 v[154:155], v[144:145], v[150:151] neg_lo:[0,1] neg_hi:[0,1]
	v_pk_add_f32 v[156:157], v[146:147], v[152:153] neg_lo:[0,1] neg_hi:[0,1]
	v_pk_add_f32 v[140:141], v[140:141], v[154:155]
	v_pk_add_f32 v[142:143], v[142:143], v[156:157]
	v_pk_fma_f32 v[158:159], v[164:165], v[140:141], v[144:145] op_sel_hi:[0,1,1] neg_lo:[0,0,1] neg_hi:[0,0,1]
	v_pk_fma_f32 v[160:161], v[164:165], v[142:143], v[146:147] op_sel_hi:[0,1,1] neg_lo:[0,0,1] neg_hi:[0,0,1]
	v_cvt_pk_bf16_f32 v162, v158, v159
	v_cvt_pk_bf16_f32 v163, v160, v161
	global_store_dwordx2 v36, v[162:163], s[96:97] offset:2560
	s_waitcnt vmcnt(31)
	v_lshlrev_b32_e32 v144, 16, v82
	v_and_b32_e32 v145, 0xffff0000, v82
	v_lshlrev_b32_e32 v146, 16, v83
	v_and_b32_e32 v147, 0xffff0000, v83
	v_cndmask_b32_e64 v148, v78, v74, s[94:95]
	v_cndmask_b32_e64 v149, v79, v75, s[94:95]
	v_lshlrev_b32_e32 v150, 16, v148
	v_and_b32_e32 v151, 0xffff0000, v148
	v_lshlrev_b32_e32 v152, 16, v149
	v_and_b32_e32 v153, 0xffff0000, v149
	v_pk_add_f32 v[154:155], v[144:145], v[150:151] neg_lo:[0,1] neg_hi:[0,1]
	v_pk_add_f32 v[156:157], v[146:147], v[152:153] neg_lo:[0,1] neg_hi:[0,1]
	v_pk_add_f32 v[140:141], v[140:141], v[154:155]
	v_pk_add_f32 v[142:143], v[142:143], v[156:157]
	v_pk_fma_f32 v[158:159], v[164:165], v[140:141], v[144:145] op_sel_hi:[0,1,1] neg_lo:[0,0,1] neg_hi:[0,0,1]
	v_pk_fma_f32 v[160:161], v[164:165], v[142:143], v[146:147] op_sel_hi:[0,1,1] neg_lo:[0,0,1] neg_hi:[0,0,1]
	v_cvt_pk_bf16_f32 v162, v158, v159
	v_cvt_pk_bf16_f32 v163, v160, v161
	global_store_dwordx2 v36, v[162:163], s[96:97] offset:3072
	s_waitcnt vmcnt(31)
	v_lshlrev_b32_e32 v144, 16, v84
	v_and_b32_e32 v145, 0xffff0000, v84
	v_lshlrev_b32_e32 v146, 16, v85
	v_and_b32_e32 v147, 0xffff0000, v85
	v_cndmask_b32_e64 v148, v80, v76, s[94:95]
	v_cndmask_b32_e64 v149, v81, v77, s[94:95]
	v_lshlrev_b32_e32 v150, 16, v148
	v_and_b32_e32 v151, 0xffff0000, v148
	v_lshlrev_b32_e32 v152, 16, v149
	v_and_b32_e32 v153, 0xffff0000, v149
	v_pk_add_f32 v[154:155], v[144:145], v[150:151] neg_lo:[0,1] neg_hi:[0,1]
	v_pk_add_f32 v[156:157], v[146:147], v[152:153] neg_lo:[0,1] neg_hi:[0,1]
	v_pk_add_f32 v[140:141], v[140:141], v[154:155]
	v_pk_add_f32 v[142:143], v[142:143], v[156:157]
	v_pk_fma_f32 v[158:159], v[164:165], v[140:141], v[144:145] op_sel_hi:[0,1,1] neg_lo:[0,0,1] neg_hi:[0,0,1]
	v_pk_fma_f32 v[160:161], v[164:165], v[142:143], v[146:147] op_sel_hi:[0,1,1] neg_lo:[0,0,1] neg_hi:[0,0,1]
	v_cvt_pk_bf16_f32 v162, v158, v159
	v_cvt_pk_bf16_f32 v163, v160, v161
	global_store_dwordx2 v36, v[162:163], s[96:97] offset:3584
	s_add_u32 s96, s96, 0x1000
	s_addc_u32 s97, s97, 0
	s_waitcnt vmcnt(31)
	v_lshlrev_b32_e32 v144, 16, v86
	v_and_b32_e32 v145, 0xffff0000, v86
	v_lshlrev_b32_e32 v146, 16, v87
	v_and_b32_e32 v147, 0xffff0000, v87
	v_cndmask_b32_e64 v148, v82, v78, s[94:95]
	v_cndmask_b32_e64 v149, v83, v79, s[94:95]
	v_lshlrev_b32_e32 v150, 16, v148
	v_and_b32_e32 v151, 0xffff0000, v148
	v_lshlrev_b32_e32 v152, 16, v149
	v_and_b32_e32 v153, 0xffff0000, v149
	v_pk_add_f32 v[154:155], v[144:145], v[150:151] neg_lo:[0,1] neg_hi:[0,1]
	v_pk_add_f32 v[156:157], v[146:147], v[152:153] neg_lo:[0,1] neg_hi:[0,1]
	v_pk_add_f32 v[140:141], v[140:141], v[154:155]
	v_pk_add_f32 v[142:143], v[142:143], v[156:157]
	v_pk_fma_f32 v[158:159], v[164:165], v[140:141], v[144:145] op_sel_hi:[0,1,1] neg_lo:[0,0,1] neg_hi:[0,0,1]
	v_pk_fma_f32 v[160:161], v[164:165], v[142:143], v[146:147] op_sel_hi:[0,1,1] neg_lo:[0,0,1] neg_hi:[0,0,1]
	v_cvt_pk_bf16_f32 v162, v158, v159
	v_cvt_pk_bf16_f32 v163, v160, v161
	global_store_dwordx2 v36, v[162:163], s[96:97]
	s_waitcnt vmcnt(31)
	v_lshlrev_b32_e32 v144, 16, v88
	v_and_b32_e32 v145, 0xffff0000, v88
	v_lshlrev_b32_e32 v146, 16, v89
	v_and_b32_e32 v147, 0xffff0000, v89
	v_cndmask_b32_e64 v148, v84, v80, s[94:95]
	v_cndmask_b32_e64 v149, v85, v81, s[94:95]
	v_lshlrev_b32_e32 v150, 16, v148
	v_and_b32_e32 v151, 0xffff0000, v148
	v_lshlrev_b32_e32 v152, 16, v149
	v_and_b32_e32 v153, 0xffff0000, v149
	v_pk_add_f32 v[154:155], v[144:145], v[150:151] neg_lo:[0,1] neg_hi:[0,1]
	v_pk_add_f32 v[156:157], v[146:147], v[152:153] neg_lo:[0,1] neg_hi:[0,1]
	v_pk_add_f32 v[140:141], v[140:141], v[154:155]
	v_pk_add_f32 v[142:143], v[142:143], v[156:157]
	v_pk_fma_f32 v[158:159], v[164:165], v[140:141], v[144:145] op_sel_hi:[0,1,1] neg_lo:[0,0,1] neg_hi:[0,0,1]
	v_pk_fma_f32 v[160:161], v[164:165], v[142:143], v[146:147] op_sel_hi:[0,1,1] neg_lo:[0,0,1] neg_hi:[0,0,1]
	v_cvt_pk_bf16_f32 v162, v158, v159
	v_cvt_pk_bf16_f32 v163, v160, v161
	global_store_dwordx2 v36, v[162:163], s[96:97] offset:512
	s_waitcnt vmcnt(31)
; #define GAS __attribute__((address_space(1)))
; __device__ __forceinline__ unsigned pk2(float lo, float hi) { f32x2_t v = {lo, hi}; bf16x2_t b = __builtin_convertvector(v, bf16x2_t); return __builtin_bit_cast(unsigned, b); }
; #define U_LD(p) ({ const v2u w_ = *(const v2u*)(p); (f32x4){bflo(w_.x), bfhi(w_.x), bflo(w_.y), bfhi(w_.y)}; })
; __device__ __forceinline__ void p3_pool(Frame& F) {
;     ...
;         for (int i = 0; i < nsteps; ++i) {
;             const int s = s0 - 15 + i;
;             const int so = s - w;
;             f32x4 n0 = (f32x4){0.f, 0.f, 0.f, 0.f}, o0 = n0;
;             if (isP) {
;                 if (s >= 0) n0 = U_LD(U + (mbase + s) * 512 + c0);
;                 if (i >= w && so >= 0) o0 = U_LD(U + (mbase + so) * 512 + c0);
;             } else {
;                 if (s >= 0) n0 = U_LD(U + (mbase + s) * 512 + c0); else n0 = *(const f32x4*)(state_pool + ((size_t)b * 15 + (s + 15)) * 512 + c0);
;                 if (i >= w) { if (so >= 0) o0 = U_LD(U + (mbase + so) * 512 + c0); else o0 = *(const f32x4*)(state_pool + ((size_t)b * 15 + (so + 15)) * 512 + c0); }
;             }
;             S0 += n0 - o0;
;             if (i >= 15) {
;                 const int cnt = isP ? (w < s + 1 ? w : s + 1) : w; const float inv = 1.f / (float)cnt;
;                 const f32x4 d0 = S0 * inv - n0;
;                 v2u wv; wv.x = pk2(d0[0], d0[1]); wv.y = pk2(d0[2], d0[3]);
;                 *(GAS v2u*)(D + (size_t)(c0 >> 8) * ((size_t)MT * 256) + (mbase + s) * 256 + (c0 & 255)) = wv;
	v_lshlrev_b32_e32 v144, 16, v90
	v_and_b32_e32 v145, 0xffff0000, v90
	v_lshlrev_b32_e32 v146, 16, v91
	v_and_b32_e32 v147, 0xffff0000, v91
	v_cndmask_b32_e64 v148, v86, v82, s[94:95]
	v_cndmask_b32_e64 v149, v87, v83, s[94:95]
	v_lshlrev_b32_e32 v150, 16, v148
	v_and_b32_e32 v151, 0xffff0000, v148
	v_lshlrev_b32_e32 v152, 16, v149
	v_and_b32_e32 v153, 0xffff0000, v149
	v_pk_add_f32 v[154:155], v[144:145], v[150:151] neg_lo:[0,1] neg_hi:[0,1]
	v_pk_add_f32 v[156:157], v[146:147], v[152:153] neg_lo:[0,1] neg_hi:[0,1]
	v_pk_add_f32 v[140:141], v[140:141], v[154:155]
	v_pk_add_f32 v[142:143], v[142:143], v[156:157]
	v_pk_fma_f32 v[158:159], v[164:165], v[140:141], v[144:145] op_sel_hi:[0,1,1] neg_lo:[0,0,1] neg_hi:[0,0,1]
	v_pk_fma_f32 v[160:161], v[164:165], v[142:143], v[146:147] op_sel_hi:[0,1,1] neg_lo:[0,0,1] neg_hi:[0,0,1]
	v_cvt_pk_bf16_f32 v162, v158, v159
	v_cvt_pk_bf16_f32 v163, v160, v161
	global_store_dwordx2 v36, v[162:163], s[96:97] offset:1024
	s_waitcnt vmcnt(31)
	v_lshlrev_b32_e32 v144, 16, v92
	v_and_b32_e32 v145, 0xffff0000, v92
	v_lshlrev_b32_e32 v146, 16, v93
	v_and_b32_e32 v147, 0xffff0000, v93
	v_cndmask_b32_e64 v148, v88, v84, s[94:95]
	v_cndmask_b32_e64 v149, v89, v85, s[94:95]
	v_lshlrev_b32_e32 v150, 16, v148
	v_and_b32_e32 v151, 0xffff0000, v148
	v_lshlrev_b32_e32 v152, 16, v149
	v_and_b32_e32 v153, 0xffff0000, v149
	v_pk_add_f32 v[154:155], v[144:145], v[150:151] neg_lo:[0,1] neg_hi:[0,1]
	v_pk_add_f32 v[156:157], v[146:147], v[152:153] neg_lo:[0,1] neg_hi:[0,1]
	v_pk_add_f32 v[140:141], v[140:141], v[154:155]
	v_pk_add_f32 v[142:143], v[142:143], v[156:157]
	v_pk_fma_f32 v[158:159], v[164:165], v[140:141], v[144:145] op_sel_hi:[0,1,1] neg_lo:[0,0,1] neg_hi:[0,0,1]
	v_pk_fma_f32 v[160:161], v[164:165], v[142:143], v[146:147] op_sel_hi:[0,1,1] neg_lo:[0,0,1] neg_hi:[0,0,1]
	v_cvt_pk_bf16_f32 v162, v158, v159
	v_cvt_pk_bf16_f32 v163, v160, v161
	global_store_dwordx2 v36, v[162:163], s[96:97] offset:1536
	s_waitcnt vmcnt(31)
	v_lshlrev_b32_e32 v144, 16, v94
	v_and_b32_e32 v145, 0xffff0000, v94
	v_lshlrev_b32_e32 v146, 16, v95
	v_and_b32_e32 v147, 0xffff0000, v95
	v_cndmask_b32_e64 v148, v90, v86, s[94:95]
	v_cndmask_b32_e64 v149, v91, v87, s[94:95]
	v_lshlrev_b32_e32 v150, 16, v148
	v_and_b32_e32 v151, 0xffff0000, v148
	v_lshlrev_b32_e32 v152, 16, v149
	v_and_b32_e32 v153, 0xffff0000, v149
	v_pk_add_f32 v[154:155], v[144:145], v[150:151] neg_lo:[0,1] neg_hi:[0,1]
	v_pk_add_f32 v[156:157], v[146:147], v[152:153] neg_lo:[0,1] neg_hi:[0,1]
	v_pk_add_f32 v[140:141], v[140:141], v[154:155]
	v_pk_add_f32 v[142:143], v[142:143], v[156:157]
	v_pk_fma_f32 v[158:159], v[164:165], v[140:141], v[144:145] op_sel_hi:[0,1,1] neg_lo:[0,0,1] neg_hi:[0,0,1]
	v_pk_fma_f32 v[160:161], v[164:165], v[142:143], v[146:147] op_sel_hi:[0,1,1] neg_lo:[0,0,1] neg_hi:[0,0,1]
	v_cvt_pk_bf16_f32 v162, v158, v159
	v_cvt_pk_bf16_f32 v163, v160, v161
	global_store_dwordx2 v36, v[162:163], s[96:97] offset:2048
	s_waitcnt vmcnt(31)
	v_lshlrev_b32_e32 v144, 16, v96
	v_and_b32_e32 v145, 0xffff0000, v96
	v_lshlrev_b32_e32 v146, 16, v97
	v_and_b32_e32 v147, 0xffff0000, v97
	v_cndmask_b32_e64 v148, v92, v88, s[94:95]
	v_cndmask_b32_e64 v149, v93, v89, s[94:95]
	v_lshlrev_b32_e32 v150, 16, v148
	v_and_b32_e32 v151, 0xffff0000, v148
	v_lshlrev_b32_e32 v152, 16, v149
	v_and_b32_e32 v153, 0xffff0000, v149
	v_pk_add_f32 v[154:155], v[144:145], v[150:151] neg_lo:[0,1] neg_hi:[0,1]
	v_pk_add_f32 v[156:157], v[146:147], v[152:153] neg_lo:[0,1] neg_hi:[0,1]
	v_pk_add_f32 v[140:141], v[140:141], v[154:155]
	v_pk_add_f32 v[142:143], v[142:143], v[156:157]
	v_pk_fma_f32 v[158:159], v[164:165], v[140:141], v[144:145] op_sel_hi:[0,1,1] neg_lo:[0,0,1] neg_hi:[0,0,1]
	v_pk_fma_f32 v[160:161], v[164:165], v[142:143], v[146:147] op_sel_hi:[0,1,1] neg_lo:[0,0,1] neg_hi:[0,0,1]
	v_cvt_pk_bf16_f32 v162, v158, v159
	v_cvt_pk_bf16_f32 v163, v160, v161
	global_store_dwordx2 v36, v[162:163], s[96:97] offset:2560
	s_waitcnt vmcnt(31)
	v_lshlrev_b32_e32 v144, 16, v98
	v_and_b32_e32 v145, 0xffff0000, v98
	v_lshlrev_b32_e32 v146, 16, v99
	v_and_b32_e32 v147, 0xffff0000, v99
	v_cndmask_b32_e64 v148, v94, v90, s[94:95]
	v_cndmask_b32_e64 v149, v95, v91, s[94:95]
	v_lshlrev_b32_e32 v150, 16, v148
	v_and_b32_e32 v151, 0xffff0000, v148
	v_lshlrev_b32_e32 v152, 16, v149
	v_and_b32_e32 v153, 0xffff0000, v149
	v_pk_add_f32 v[154:155], v[144:145], v[150:151] neg_lo:[0,1] neg_hi:[0,1]
	v_pk_add_f32 v[156:157], v[146:147], v[152:153] neg_lo:[0,1] neg_hi:[0,1]
	v_pk_add_f32 v[140:141], v[140:141], v[154:155]
	v_pk_add_f32 v[142:143], v[142:143], v[156:157]
	v_pk_fma_f32 v[158:159], v[164:165], v[140:141], v[144:145] op_sel_hi:[0,1,1] neg_lo:[0,0,1] neg_hi:[0,0,1]
	v_pk_fma_f32 v[160:161], v[164:165], v[142:143], v[146:147] op_sel_hi:[0,1,1] neg_lo:[0,0,1] neg_hi:[0,0,1]
	v_cvt_pk_bf16_f32 v162, v158, v159
	v_cvt_pk_bf16_f32 v163, v160, v161
	global_store_dwordx2 v36, v[162:163], s[96:97] offset:3072
	s_waitcnt vmcnt(31)
	v_lshlrev_b32_e32 v144, 16, v100
	v_and_b32_e32 v145, 0xffff0000, v100
	v_lshlrev_b32_e32 v146, 16, v101
	v_and_b32_e32 v147, 0xffff0000, v101
	v_cndmask_b32_e64 v148, v96, v92, s[94:95]
	v_cndmask_b32_e64 v149, v97, v93, s[94:95]
	v_lshlrev_b32_e32 v150, 16, v148
	v_and_b32_e32 v151, 0xffff0000, v148
	v_lshlrev_b32_e32 v152, 16, v149
	v_and_b32_e32 v153, 0xffff0000, v149
	v_pk_add_f32 v[154:155], v[144:145], v[150:151] neg_lo:[0,1] neg_hi:[0,1]
	v_pk_add_f32 v[156:157], v[146:147], v[152:153] neg_lo:[0,1] neg_hi:[0,1]
	v_pk_add_f32 v[140:141], v[140:141], v[154:155]
	v_pk_add_f32 v[142:143], v[142:143], v[156:157]
	v_pk_fma_f32 v[158:159], v[164:165], v[140:141], v[144:145] op_sel_hi:[0,1,1] neg_lo:[0,0,1] neg_hi:[0,0,1]
	v_pk_fma_f32 v[160:161], v[164:165], v[142:143], v[146:147] op_sel_hi:[0,1,1] neg_lo:[0,0,1] neg_hi:[0,0,1]
	v_cvt_pk_bf16_f32 v162, v158, v159
	v_cvt_pk_bf16_f32 v163, v160, v161
	global_store_dwordx2 v36, v[162:163], s[96:97] offset:3584
	s_add_u32 s96, s96, 0x1000
	s_addc_u32 s97, s97, 0
	s_waitcnt vmcnt(31)
; #define GAS __attribute__((address_space(1)))
; __device__ __forceinline__ unsigned pk2(float lo, float hi) { f32x2_t v = {lo, hi}; bf16x2_t b = __builtin_convertvector(v, bf16x2_t); return __builtin_bit_cast(unsigned, b); }
; #define U_LD(p) ({ const v2u w_ = *(const v2u*)(p); (f32x4){bflo(w_.x), bfhi(w_.x), bflo(w_.y), bfhi(w_.y)}; })
; __device__ __forceinline__ void p3_pool(Frame& F) {
;     ...
;         for (int i = 0; i < nsteps; ++i) {
;             const int s = s0 - 15 + i;
;             const int so = s - w;
;             f32x4 n0 = (f32x4){0.f, 0.f, 0.f, 0.f}, o0 = n0;
;             if (isP) {
;                 if (s >= 0) n0 = U_LD(U + (mbase + s) * 512 + c0);
;                 if (i >= w && so >= 0) o0 = U_LD(U + (mbase + so) * 512 + c0);
;             } else {
;                 if (s >= 0) n0 = U_LD(U + (mbase + s) * 512 + c0); else n0 = *(const f32x4*)(state_pool + ((size_t)b * 15 + (s + 15)) * 512 + c0);
;                 if (i >= w) { if (so >= 0) o0 = U_LD(U + (mbase + so) * 512 + c0); else o0 = *(const f32x4*)(state_pool + ((size_t)b * 15 + (so + 15)) * 512 + c0); }
;             }
;             S0 += n0 - o0;
;             if (i >= 15) {
;                 const int cnt = isP ? (w < s + 1 ? w : s + 1) : w; const float inv = 1.f / (float)cnt;
;                 const f32x4 d0 = S0 * inv - n0;
;                 v2u wv; wv.x = pk2(d0[0], d0[1]); wv.y = pk2(d0[2], d0[3]);
;                 *(GAS v2u*)(D + (size_t)(c0 >> 8) * ((size_t)MT * 256) + (mbase + s) * 256 + (c0 & 255)) = wv;
	v_lshlrev_b32_e32 v144, 16, v102
	v_and_b32_e32 v145, 0xffff0000, v102
	v_lshlrev_b32_e32 v146, 16, v103
	v_and_b32_e32 v147, 0xffff0000, v103
	v_cndmask_b32_e64 v148, v98, v94, s[94:95]
	v_cndmask_b32_e64 v149, v99, v95, s[94:95]
	v_lshlrev_b32_e32 v150, 16, v148
	v_and_b32_e32 v151, 0xffff0000, v148
	v_lshlrev_b32_e32 v152, 16, v149
	v_and_b32_e32 v153, 0xffff0000, v149
	v_pk_add_f32 v[154:155], v[144:145], v[150:151] neg_lo:[0,1] neg_hi:[0,1]
	v_pk_add_f32 v[156:157], v[146:147], v[152:153] neg_lo:[0,1] neg_hi:[0,1]
	v_pk_add_f32 v[140:141], v[140:141], v[154:155]
	v_pk_add_f32 v[142:143], v[142:143], v[156:157]
	v_pk_fma_f32 v[158:159], v[164:165], v[140:141], v[144:145] op_sel_hi:[0,1,1] neg_lo:[0,0,1] neg_hi:[0,0,1]
	v_pk_fma_f32 v[160:161], v[164:165], v[142:143], v[146:147] op_sel_hi:[0,1,1] neg_lo:[0,0,1] neg_hi:[0,0,1]
	v_cvt_pk_bf16_f32 v162, v158, v159
	v_cvt_pk_bf16_f32 v163, v160, v161
	global_store_dwordx2 v36, v[162:163], s[96:97]
	s_waitcnt vmcnt(31)
	v_lshlrev_b32_e32 v144, 16, v104
	v_and_b32_e32 v145, 0xffff0000, v104
	v_lshlrev_b32_e32 v146, 16, v105
	v_and_b32_e32 v147, 0xffff0000, v105
	v_cndmask_b32_e64 v148, v100, v96, s[94:95]
	v_cndmask_b32_e64 v149, v101, v97, s[94:95]
	v_lshlrev_b32_e32 v150, 16, v148
	v_and_b32_e32 v151, 0xffff0000, v148
	v_lshlrev_b32_e32 v152, 16, v149
	v_and_b32_e32 v153, 0xffff0000, v149
	v_pk_add_f32 v[154:155], v[144:145], v[150:151] neg_lo:[0,1] neg_hi:[0,1]
	v_pk_add_f32 v[156:157], v[146:147], v[152:153] neg_lo:[0,1] neg_hi:[0,1]
	v_pk_add_f32 v[140:141], v[140:141], v[154:155]
	v_pk_add_f32 v[142:143], v[142:143], v[156:157]
	v_pk_fma_f32 v[158:159], v[164:165], v[140:141], v[144:145] op_sel_hi:[0,1,1] neg_lo:[0,0,1] neg_hi:[0,0,1]
	v_pk_fma_f32 v[160:161], v[164:165], v[142:143], v[146:147] op_sel_hi:[0,1,1] neg_lo:[0,0,1] neg_hi:[0,0,1]
	v_cvt_pk_bf16_f32 v162, v158, v159
	v_cvt_pk_bf16_f32 v163, v160, v161
	global_store_dwordx2 v36, v[162:163], s[96:97] offset:512
	s_waitcnt vmcnt(31)
	v_lshlrev_b32_e32 v144, 16, v106
	v_and_b32_e32 v145, 0xffff0000, v106
	v_lshlrev_b32_e32 v146, 16, v107
	v_and_b32_e32 v147, 0xffff0000, v107
	v_cndmask_b32_e64 v148, v102, v98, s[94:95]
	v_cndmask_b32_e64 v149, v103, v99, s[94:95]
	v_lshlrev_b32_e32 v150, 16, v148
	v_and_b32_e32 v151, 0xffff0000, v148
	v_lshlrev_b32_e32 v152, 16, v149
	v_and_b32_e32 v153, 0xffff0000, v149
	v_pk_add_f32 v[154:155], v[144:145], v[150:151] neg_lo:[0,1] neg_hi:[0,1]
	v_pk_add_f32 v[156:157], v[146:147], v[152:153] neg_lo:[0,1] neg_hi:[0,1]
	v_pk_add_f32 v[140:141], v[140:141], v[154:155]
	v_pk_add_f32 v[142:143], v[142:143], v[156:157]
	v_pk_fma_f32 v[158:159], v[164:165], v[140:141], v[144:145] op_sel_hi:[0,1,1] neg_lo:[0,0,1] neg_hi:[0,0,1]
	v_pk_fma_f32 v[160:161], v[164:165], v[142:143], v[146:147] op_sel_hi:[0,1,1] neg_lo:[0,0,1] neg_hi:[0,0,1]
	v_cvt_pk_bf16_f32 v162, v158, v159
	v_cvt_pk_bf16_f32 v163, v160, v161
	global_store_dwordx2 v36, v[162:163], s[96:97] offset:1024
	s_waitcnt vmcnt(31)
	v_lshlrev_b32_e32 v144, 16, v108
	v_and_b32_e32 v145, 0xffff0000, v108
	v_lshlrev_b32_e32 v146, 16, v109
	v_and_b32_e32 v147, 0xffff0000, v109
	v_cndmask_b32_e64 v148, v104, v100, s[94:95]
	v_cndmask_b32_e64 v149, v105, v101, s[94:95]
	v_lshlrev_b32_e32 v150, 16, v148
	v_and_b32_e32 v151, 0xffff0000, v148
	v_lshlrev_b32_e32 v152, 16, v149
	v_and_b32_e32 v153, 0xffff0000, v149
	v_pk_add_f32 v[154:155], v[144:145], v[150:151] neg_lo:[0,1] neg_hi:[0,1]
	v_pk_add_f32 v[156:157], v[146:147], v[152:153] neg_lo:[0,1] neg_hi:[0,1]
	v_pk_add_f32 v[140:141], v[140:141], v[154:155]
	v_pk_add_f32 v[142:143], v[142:143], v[156:157]
	v_pk_fma_f32 v[158:159], v[164:165], v[140:141], v[144:145] op_sel_hi:[0,1,1] neg_lo:[0,0,1] neg_hi:[0,0,1]
	v_pk_fma_f32 v[160:161], v[164:165], v[142:143], v[146:147] op_sel_hi:[0,1,1] neg_lo:[0,0,1] neg_hi:[0,0,1]
	v_cvt_pk_bf16_f32 v162, v158, v159
	v_cvt_pk_bf16_f32 v163, v160, v161
	global_store_dwordx2 v36, v[162:163], s[96:97] offset:1536
	s_waitcnt vmcnt(31)
	v_lshlrev_b32_e32 v144, 16, v110
	v_and_b32_e32 v145, 0xffff0000, v110
	v_lshlrev_b32_e32 v146, 16, v111
	v_and_b32_e32 v147, 0xffff0000, v111
	v_cndmask_b32_e64 v148, v106, v102, s[94:95]
	v_cndmask_b32_e64 v149, v107, v103, s[94:95]
	v_lshlrev_b32_e32 v150, 16, v148
	v_and_b32_e32 v151, 0xffff0000, v148
	v_lshlrev_b32_e32 v152, 16, v149
	v_and_b32_e32 v153, 0xffff0000, v149
	v_pk_add_f32 v[154:155], v[144:145], v[150:151] neg_lo:[0,1] neg_hi:[0,1]
	v_pk_add_f32 v[156:157], v[146:147], v[152:153] neg_lo:[0,1] neg_hi:[0,1]
	v_pk_add_f32 v[140:141], v[140:141], v[154:155]
	v_pk_add_f32 v[142:143], v[142:143], v[156:157]
	v_pk_fma_f32 v[158:159], v[164:165], v[140:141], v[144:145] op_sel_hi:[0,1,1] neg_lo:[0,0,1] neg_hi:[0,0,1]
	v_pk_fma_f32 v[160:161], v[164:165], v[142:143], v[146:147] op_sel_hi:[0,1,1] neg_lo:[0,0,1] neg_hi:[0,0,1]
	v_cvt_pk_bf16_f32 v162, v158, v159
	v_cvt_pk_bf16_f32 v163, v160, v161
	global_store_dwordx2 v36, v[162:163], s[96:97] offset:2048
	s_waitcnt vmcnt(31)
	v_lshlrev_b32_e32 v144, 16, v112
	v_and_b32_e32 v145, 0xffff0000, v112
	v_lshlrev_b32_e32 v146, 16, v113
	v_and_b32_e32 v147, 0xffff0000, v113
	v_cndmask_b32_e64 v148, v108, v104, s[94:95]
	v_cndmask_b32_e64 v149, v109, v105, s[94:95]
	v_lshlrev_b32_e32 v150, 16, v148
	v_and_b32_e32 v151, 0xffff0000, v148
	v_lshlrev_b32_e32 v152, 16, v149
	v_and_b32_e32 v153, 0xffff0000, v149
	v_pk_add_f32 v[154:155], v[144:145], v[150:151] neg_lo:[0,1] neg_hi:[0,1]
	v_pk_add_f32 v[156:157], v[146:147], v[152:153] neg_lo:[0,1] neg_hi:[0,1]
	v_pk_add_f32 v[140:141], v[140:141], v[154:155]
	v_pk_add_f32 v[142:143], v[142:143], v[156:157]
	v_pk_fma_f32 v[158:159], v[164:165], v[140:141], v[144:145] op_sel_hi:[0,1,1] neg_lo:[0,0,1] neg_hi:[0,0,1]
	v_pk_fma_f32 v[160:161], v[164:165], v[142:143], v[146:147] op_sel_hi:[0,1,1] neg_lo:[0,0,1] neg_hi:[0,0,1]
	v_cvt_pk_bf16_f32 v162, v158, v159
	v_cvt_pk_bf16_f32 v163, v160, v161
	global_store_dwordx2 v36, v[162:163], s[96:97] offset:2560
	s_waitcnt vmcnt(31)
; #define GAS __attribute__((address_space(1)))
; __device__ __forceinline__ unsigned pk2(float lo, float hi) { f32x2_t v = {lo, hi}; bf16x2_t b = __builtin_convertvector(v, bf16x2_t); return __builtin_bit_cast(unsigned, b); }
; #define U_LD(p) ({ const v2u w_ = *(const v2u*)(p); (f32x4){bflo(w_.x), bfhi(w_.x), bflo(w_.y), bfhi(w_.y)}; })
; __device__ __forceinline__ void p3_pool(Frame& F) {
;     ...
;         for (int i = 0; i < nsteps; ++i) {
;             const int s = s0 - 15 + i;
;             const int so = s - w;
;             f32x4 n0 = (f32x4){0.f, 0.f, 0.f, 0.f}, o0 = n0;
;             if (isP) {
;                 if (s >= 0) n0 = U_LD(U + (mbase + s) * 512 + c0);
;                 if (i >= w && so >= 0) o0 = U_LD(U + (mbase + so) * 512 + c0);
;             } else {
;                 if (s >= 0) n0 = U_LD(U + (mbase + s) * 512 + c0); else n0 = *(const f32x4*)(state_pool + ((size_t)b * 15 + (s + 15)) * 512 + c0);
;                 if (i >= w) { if (so >= 0) o0 = U_LD(U + (mbase + so) * 512 + c0); else o0 = *(const f32x4*)(state_pool + ((size_t)b * 15 + (so + 15)) * 512 + c0); }
;             }
;             S0 += n0 - o0;
;             if (i >= 15) {
;                 const int cnt = isP ? (w < s + 1 ? w : s + 1) : w; const float inv = 1.f / (float)cnt;
;                 const f32x4 d0 = S0 * inv - n0;
;                 v2u wv; wv.x = pk2(d0[0], d0[1]); wv.y = pk2(d0[2], d0[3]);
;                 *(GAS v2u*)(D + (size_t)(c0 >> 8) * ((size_t)MT * 256) + (mbase + s) * 256 + (c0 & 255)) = wv;
	v_lshlrev_b32_e32 v144, 16, v114
	v_and_b32_e32 v145, 0xffff0000, v114
	v_lshlrev_b32_e32 v146, 16, v115
	v_and_b32_e32 v147, 0xffff0000, v115
	v_cndmask_b32_e64 v148, v110, v106, s[94:95]
	v_cndmask_b32_e64 v149, v111, v107, s[94:95]
	v_lshlrev_b32_e32 v150, 16, v148
	v_and_b32_e32 v151, 0xffff0000, v148
	v_lshlrev_b32_e32 v152, 16, v149
	v_and_b32_e32 v153, 0xffff0000, v149
	v_pk_add_f32 v[154:155], v[144:145], v[150:151] neg_lo:[0,1] neg_hi:[0,1]
	v_pk_add_f32 v[156:157], v[146:147], v[152:153] neg_lo:[0,1] neg_hi:[0,1]
	v_pk_add_f32 v[140:141], v[140:141], v[154:155]
	v_pk_add_f32 v[142:143], v[142:143], v[156:157]
	v_pk_fma_f32 v[158:159], v[164:165], v[140:141], v[144:145] op_sel_hi:[0,1,1] neg_lo:[0,0,1] neg_hi:[0,0,1]
	v_pk_fma_f32 v[160:161], v[164:165], v[142:143], v[146:147] op_sel_hi:[0,1,1] neg_lo:[0,0,1] neg_hi:[0,0,1]
	v_cvt_pk_bf16_f32 v162, v158, v159
	v_cvt_pk_bf16_f32 v163, v160, v161
	global_store_dwordx2 v36, v[162:163], s[96:97] offset:3072
	s_waitcnt vmcnt(31)
	v_lshlrev_b32_e32 v144, 16, v116
	v_and_b32_e32 v145, 0xffff0000, v116
	v_lshlrev_b32_e32 v146, 16, v117
	v_and_b32_e32 v147, 0xffff0000, v117
	v_cndmask_b32_e64 v148, v112, v108, s[94:95]
	v_cndmask_b32_e64 v149, v113, v109, s[94:95]
	v_lshlrev_b32_e32 v150, 16, v148
	v_and_b32_e32 v151, 0xffff0000, v148
	v_lshlrev_b32_e32 v152, 16, v149
	v_and_b32_e32 v153, 0xffff0000, v149
	v_pk_add_f32 v[154:155], v[144:145], v[150:151] neg_lo:[0,1] neg_hi:[0,1]
	v_pk_add_f32 v[156:157], v[146:147], v[152:153] neg_lo:[0,1] neg_hi:[0,1]
	v_pk_add_f32 v[140:141], v[140:141], v[154:155]
	v_pk_add_f32 v[142:143], v[142:143], v[156:157]
	v_pk_fma_f32 v[158:159], v[164:165], v[140:141], v[144:145] op_sel_hi:[0,1,1] neg_lo:[0,0,1] neg_hi:[0,0,1]
	v_pk_fma_f32 v[160:161], v[164:165], v[142:143], v[146:147] op_sel_hi:[0,1,1] neg_lo:[0,0,1] neg_hi:[0,0,1]
	v_cvt_pk_bf16_f32 v162, v158, v159
	v_cvt_pk_bf16_f32 v163, v160, v161
	global_store_dwordx2 v36, v[162:163], s[96:97] offset:3584
	s_add_u32 s96, s96, 0x1000
	s_addc_u32 s97, s97, 0
	s_waitcnt vmcnt(31)
	v_lshlrev_b32_e32 v144, 16, v118
	v_and_b32_e32 v145, 0xffff0000, v118
	v_lshlrev_b32_e32 v146, 16, v119
	v_and_b32_e32 v147, 0xffff0000, v119
	v_cndmask_b32_e64 v148, v114, v110, s[94:95]
	v_cndmask_b32_e64 v149, v115, v111, s[94:95]
	v_lshlrev_b32_e32 v150, 16, v148
	v_and_b32_e32 v151, 0xffff0000, v148
	v_lshlrev_b32_e32 v152, 16, v149
	v_and_b32_e32 v153, 0xffff0000, v149
	v_pk_add_f32 v[154:155], v[144:145], v[150:151] neg_lo:[0,1] neg_hi:[0,1]
	v_pk_add_f32 v[156:157], v[146:147], v[152:153] neg_lo:[0,1] neg_hi:[0,1]
	v_pk_add_f32 v[140:141], v[140:141], v[154:155]
	v_pk_add_f32 v[142:143], v[142:143], v[156:157]
	v_pk_fma_f32 v[158:159], v[164:165], v[140:141], v[144:145] op_sel_hi:[0,1,1] neg_lo:[0,0,1] neg_hi:[0,0,1]
	v_pk_fma_f32 v[160:161], v[164:165], v[142:143], v[146:147] op_sel_hi:[0,1,1] neg_lo:[0,0,1] neg_hi:[0,0,1]
	v_cvt_pk_bf16_f32 v162, v158, v159
	v_cvt_pk_bf16_f32 v163, v160, v161
	global_store_dwordx2 v36, v[162:163], s[96:97]
	s_waitcnt vmcnt(31)
	v_lshlrev_b32_e32 v144, 16, v120
	v_and_b32_e32 v145, 0xffff0000, v120
	v_lshlrev_b32_e32 v146, 16, v121
	v_and_b32_e32 v147, 0xffff0000, v121
	v_cndmask_b32_e64 v148, v116, v112, s[94:95]
	v_cndmask_b32_e64 v149, v117, v113, s[94:95]
	v_lshlrev_b32_e32 v150, 16, v148
	v_and_b32_e32 v151, 0xffff0000, v148
	v_lshlrev_b32_e32 v152, 16, v149
	v_and_b32_e32 v153, 0xffff0000, v149
	v_pk_add_f32 v[154:155], v[144:145], v[150:151] neg_lo:[0,1] neg_hi:[0,1]
	v_pk_add_f32 v[156:157], v[146:147], v[152:153] neg_lo:[0,1] neg_hi:[0,1]
	v_pk_add_f32 v[140:141], v[140:141], v[154:155]
	v_pk_add_f32 v[142:143], v[142:143], v[156:157]
	v_pk_fma_f32 v[158:159], v[164:165], v[140:141], v[144:145] op_sel_hi:[0,1,1] neg_lo:[0,0,1] neg_hi:[0,0,1]
	v_pk_fma_f32 v[160:161], v[164:165], v[142:143], v[146:147] op_sel_hi:[0,1,1] neg_lo:[0,0,1] neg_hi:[0,0,1]
	v_cvt_pk_bf16_f32 v162, v158, v159
	v_cvt_pk_bf16_f32 v163, v160, v161
	global_store_dwordx2 v36, v[162:163], s[96:97] offset:512
	s_waitcnt vmcnt(31)
	v_lshlrev_b32_e32 v144, 16, v122
	v_and_b32_e32 v145, 0xffff0000, v122
	v_lshlrev_b32_e32 v146, 16, v123
	v_and_b32_e32 v147, 0xffff0000, v123
	v_cndmask_b32_e64 v148, v118, v114, s[94:95]
	v_cndmask_b32_e64 v149, v119, v115, s[94:95]
	v_lshlrev_b32_e32 v150, 16, v148
	v_and_b32_e32 v151, 0xffff0000, v148
	v_lshlrev_b32_e32 v152, 16, v149
	v_and_b32_e32 v153, 0xffff0000, v149
	v_pk_add_f32 v[154:155], v[144:145], v[150:151] neg_lo:[0,1] neg_hi:[0,1]
	v_pk_add_f32 v[156:157], v[146:147], v[152:153] neg_lo:[0,1] neg_hi:[0,1]
	v_pk_add_f32 v[140:141], v[140:141], v[154:155]
	v_pk_add_f32 v[142:143], v[142:143], v[156:157]
	v_pk_fma_f32 v[158:159], v[164:165], v[140:141], v[144:145] op_sel_hi:[0,1,1] neg_lo:[0,0,1] neg_hi:[0,0,1]
	v_pk_fma_f32 v[160:161], v[164:165], v[142:143], v[146:147] op_sel_hi:[0,1,1] neg_lo:[0,0,1] neg_hi:[0,0,1]
	v_cvt_pk_bf16_f32 v162, v158, v159
	v_cvt_pk_bf16_f32 v163, v160, v161
	global_store_dwordx2 v36, v[162:163], s[96:97] offset:1024
	s_waitcnt vmcnt(31)
	v_lshlrev_b32_e32 v144, 16, v124
	v_and_b32_e32 v145, 0xffff0000, v124
	v_lshlrev_b32_e32 v146, 16, v125
	v_and_b32_e32 v147, 0xffff0000, v125
	v_cndmask_b32_e64 v148, v120, v116, s[94:95]
	v_cndmask_b32_e64 v149, v121, v117, s[94:95]
	v_lshlrev_b32_e32 v150, 16, v148
	v_and_b32_e32 v151, 0xffff0000, v148
	v_lshlrev_b32_e32 v152, 16, v149
	v_and_b32_e32 v153, 0xffff0000, v149
	v_pk_add_f32 v[154:155], v[144:145], v[150:151] neg_lo:[0,1] neg_hi:[0,1]
	v_pk_add_f32 v[156:157], v[146:147], v[152:153] neg_lo:[0,1] neg_hi:[0,1]
	v_pk_add_f32 v[140:141], v[140:141], v[154:155]
	v_pk_add_f32 v[142:143], v[142:143], v[156:157]
	v_pk_fma_f32 v[158:159], v[164:165], v[140:141], v[144:145] op_sel_hi:[0,1,1] neg_lo:[0,0,1] neg_hi:[0,0,1]
	v_pk_fma_f32 v[160:161], v[164:165], v[142:143], v[146:147] op_sel_hi:[0,1,1] neg_lo:[0,0,1] neg_hi:[0,0,1]
	v_cvt_pk_bf16_f32 v162, v158, v159
	v_cvt_pk_bf16_f32 v163, v160, v161
	global_store_dwordx2 v36, v[162:163], s[96:97] offset:1536
	s_waitcnt vmcnt(31)
; #define GAS __attribute__((address_space(1)))
; __device__ __forceinline__ unsigned pk2(float lo, float hi) { f32x2_t v = {lo, hi}; bf16x2_t b = __builtin_convertvector(v, bf16x2_t); return __builtin_bit_cast(unsigned, b); }
; #define U_LD(p) ({ const v2u w_ = *(const v2u*)(p); (f32x4){bflo(w_.x), bfhi(w_.x), bflo(w_.y), bfhi(w_.y)}; })
; __device__ __forceinline__ void p3_pool(Frame& F) {
;     ...
;         for (int i = 0; i < nsteps; ++i) {
;             const int s = s0 - 15 + i;
;             const int so = s - w;
;             f32x4 n0 = (f32x4){0.f, 0.f, 0.f, 0.f}, o0 = n0;
;             if (isP) {
;                 if (s >= 0) n0 = U_LD(U + (mbase + s) * 512 + c0);
;                 if (i >= w && so >= 0) o0 = U_LD(U + (mbase + so) * 512 + c0);
;             } else {
;                 if (s >= 0) n0 = U_LD(U + (mbase + s) * 512 + c0); else n0 = *(const f32x4*)(state_pool + ((size_t)b * 15 + (s + 15)) * 512 + c0);
;                 if (i >= w) { if (so >= 0) o0 = U_LD(U + (mbase + so) * 512 + c0); else o0 = *(const f32x4*)(state_pool + ((size_t)b * 15 + (so + 15)) * 512 + c0); }
;             }
;             S0 += n0 - o0;
;             if (i >= 15) {
;                 const int cnt = isP ? (w < s + 1 ? w : s + 1) : w; const float inv = 1.f / (float)cnt;
;                 const f32x4 d0 = S0 * inv - n0;
;                 v2u wv; wv.x = pk2(d0[0], d0[1]); wv.y = pk2(d0[2], d0[3]);
;                 *(GAS v2u*)(D + (size_t)(c0 >> 8) * ((size_t)MT * 256) + (mbase + s) * 256 + (c0 & 255)) = wv;
	v_lshlrev_b32_e32 v144, 16, v126
	v_and_b32_e32 v145, 0xffff0000, v126
	v_lshlrev_b32_e32 v146, 16, v127
	v_and_b32_e32 v147, 0xffff0000, v127
	v_cndmask_b32_e64 v148, v122, v118, s[94:95]
	v_cndmask_b32_e64 v149, v123, v119, s[94:95]
	v_lshlrev_b32_e32 v150, 16, v148
	v_and_b32_e32 v151, 0xffff0000, v148
	v_lshlrev_b32_e32 v152, 16, v149
	v_and_b32_e32 v153, 0xffff0000, v149
	v_pk_add_f32 v[154:155], v[144:145], v[150:151] neg_lo:[0,1] neg_hi:[0,1]
	v_pk_add_f32 v[156:157], v[146:147], v[152:153] neg_lo:[0,1] neg_hi:[0,1]
	v_pk_add_f32 v[140:141], v[140:141], v[154:155]
	v_pk_add_f32 v[142:143], v[142:143], v[156:157]
	v_pk_fma_f32 v[158:159], v[164:165], v[140:141], v[144:145] op_sel_hi:[0,1,1] neg_lo:[0,0,1] neg_hi:[0,0,1]
	v_pk_fma_f32 v[160:161], v[164:165], v[142:143], v[146:147] op_sel_hi:[0,1,1] neg_lo:[0,0,1] neg_hi:[0,0,1]
	v_cvt_pk_bf16_f32 v162, v158, v159
	v_cvt_pk_bf16_f32 v163, v160, v161
	global_store_dwordx2 v36, v[162:163], s[96:97] offset:2048
	s_waitcnt vmcnt(31)
	v_lshlrev_b32_e32 v144, 16, v128
	v_and_b32_e32 v145, 0xffff0000, v128
	v_lshlrev_b32_e32 v146, 16, v129
	v_and_b32_e32 v147, 0xffff0000, v129
	v_cndmask_b32_e64 v148, v124, v120, s[94:95]
	v_cndmask_b32_e64 v149, v125, v121, s[94:95]
	v_lshlrev_b32_e32 v150, 16, v148
	v_and_b32_e32 v151, 0xffff0000, v148
	v_lshlrev_b32_e32 v152, 16, v149
	v_and_b32_e32 v153, 0xffff0000, v149
	v_pk_add_f32 v[154:155], v[144:145], v[150:151] neg_lo:[0,1] neg_hi:[0,1]
	v_pk_add_f32 v[156:157], v[146:147], v[152:153] neg_lo:[0,1] neg_hi:[0,1]
	v_pk_add_f32 v[140:141], v[140:141], v[154:155]
	v_pk_add_f32 v[142:143], v[142:143], v[156:157]
	v_pk_fma_f32 v[158:159], v[164:165], v[140:141], v[144:145] op_sel_hi:[0,1,1] neg_lo:[0,0,1] neg_hi:[0,0,1]
	v_pk_fma_f32 v[160:161], v[164:165], v[142:143], v[146:147] op_sel_hi:[0,1,1] neg_lo:[0,0,1] neg_hi:[0,0,1]
	v_cvt_pk_bf16_f32 v162, v158, v159
	v_cvt_pk_bf16_f32 v163, v160, v161
	global_store_dwordx2 v36, v[162:163], s[96:97] offset:2560
	s_waitcnt vmcnt(31)
	v_lshlrev_b32_e32 v144, 16, v130
	v_and_b32_e32 v145, 0xffff0000, v130
	v_lshlrev_b32_e32 v146, 16, v131
	v_and_b32_e32 v147, 0xffff0000, v131
	v_cndmask_b32_e64 v148, v126, v122, s[94:95]
	v_cndmask_b32_e64 v149, v127, v123, s[94:95]
	v_lshlrev_b32_e32 v150, 16, v148
	v_and_b32_e32 v151, 0xffff0000, v148
	v_lshlrev_b32_e32 v152, 16, v149
	v_and_b32_e32 v153, 0xffff0000, v149
	v_pk_add_f32 v[154:155], v[144:145], v[150:151] neg_lo:[0,1] neg_hi:[0,1]
	v_pk_add_f32 v[156:157], v[146:147], v[152:153] neg_lo:[0,1] neg_hi:[0,1]
	v_pk_add_f32 v[140:141], v[140:141], v[154:155]
	v_pk_add_f32 v[142:143], v[142:143], v[156:157]
	v_pk_fma_f32 v[158:159], v[164:165], v[140:141], v[144:145] op_sel_hi:[0,1,1] neg_lo:[0,0,1] neg_hi:[0,0,1]
	v_pk_fma_f32 v[160:161], v[164:165], v[142:143], v[146:147] op_sel_hi:[0,1,1] neg_lo:[0,0,1] neg_hi:[0,0,1]
	v_cvt_pk_bf16_f32 v162, v158, v159
	v_cvt_pk_bf16_f32 v163, v160, v161
	global_store_dwordx2 v36, v[162:163], s[96:97] offset:3072
	s_waitcnt vmcnt(31)
	v_lshlrev_b32_e32 v144, 16, v132
	v_and_b32_e32 v145, 0xffff0000, v132
	v_lshlrev_b32_e32 v146, 16, v133
	v_and_b32_e32 v147, 0xffff0000, v133
	v_cndmask_b32_e64 v148, v128, v124, s[94:95]
	v_cndmask_b32_e64 v149, v129, v125, s[94:95]
	v_lshlrev_b32_e32 v150, 16, v148
	v_and_b32_e32 v151, 0xffff0000, v148
	v_lshlrev_b32_e32 v152, 16, v149
	v_and_b32_e32 v153, 0xffff0000, v149
	v_pk_add_f32 v[154:155], v[144:145], v[150:151] neg_lo:[0,1] neg_hi:[0,1]
	v_pk_add_f32 v[156:157], v[146:147], v[152:153] neg_lo:[0,1] neg_hi:[0,1]
	v_pk_add_f32 v[140:141], v[140:141], v[154:155]
	v_pk_add_f32 v[142:143], v[142:143], v[156:157]
	v_pk_fma_f32 v[158:159], v[164:165], v[140:141], v[144:145] op_sel_hi:[0,1,1] neg_lo:[0,0,1] neg_hi:[0,0,1]
	v_pk_fma_f32 v[160:161], v[164:165], v[142:143], v[146:147] op_sel_hi:[0,1,1] neg_lo:[0,0,1] neg_hi:[0,0,1]
	v_cvt_pk_bf16_f32 v162, v158, v159
	v_cvt_pk_bf16_f32 v163, v160, v161
	global_store_dwordx2 v36, v[162:163], s[96:97] offset:3584
	s_branch .LBB0_515
.Lp3f_n1:
	v_mov_b32_e32 v140, 0
	v_mov_b32_e32 v141, 0
	v_mov_b32_e32 v142, 0
	v_mov_b32_e32 v143, 0
	v_mov_b32_e32 v166, 0
	v_mov_b32_e32 v167, 0
	v_mov_b32_e32 v168, 0x3e000000
	v_mov_b32_e32 v169, 0x3d800000
	v_cndmask_b32_e64 v164, v168, v169, s[94:95]
	s_mov_b64 s[96:97], s[90:91]
	s_waitcnt vmcnt(46)
	v_lshlrev_b32_e32 v144, 16, v40
	v_and_b32_e32 v145, 0xffff0000, v40
	v_lshlrev_b32_e32 v146, 16, v41
	v_and_b32_e32 v147, 0xffff0000, v41
	v_pk_add_f32 v[140:141], v[140:141], v[144:145]
	v_pk_add_f32 v[142:143], v[142:143], v[146:147]
	s_waitcnt vmcnt(45)
	v_lshlrev_b32_e32 v144, 16, v42
	v_and_b32_e32 v145, 0xffff0000, v42
	v_lshlrev_b32_e32 v146, 16, v43
	v_and_b32_e32 v147, 0xffff0000, v43
	v_pk_add_f32 v[140:141], v[140:141], v[144:145]
	v_pk_add_f32 v[142:143], v[142:143], v[146:147]
	s_waitcnt vmcnt(44)
	v_lshlrev_b32_e32 v144, 16, v44
	v_and_b32_e32 v145, 0xffff0000, v44
	v_lshlrev_b32_e32 v146, 16, v45
	v_and_b32_e32 v147, 0xffff0000, v45
	v_pk_add_f32 v[140:141], v[140:141], v[144:145]
	v_pk_add_f32 v[142:143], v[142:143], v[146:147]
	s_waitcnt vmcnt(43)
	v_lshlrev_b32_e32 v144, 16, v46
	v_and_b32_e32 v145, 0xffff0000, v46
	v_lshlrev_b32_e32 v146, 16, v47
	v_and_b32_e32 v147, 0xffff0000, v47
	v_pk_add_f32 v[140:141], v[140:141], v[144:145]
	v_pk_add_f32 v[142:143], v[142:143], v[146:147]
	s_waitcnt vmcnt(42)
	v_lshlrev_b32_e32 v144, 16, v48
	v_and_b32_e32 v145, 0xffff0000, v48
	v_lshlrev_b32_e32 v146, 16, v49
	v_and_b32_e32 v147, 0xffff0000, v49
	v_pk_add_f32 v[140:141], v[140:141], v[144:145]
	v_pk_add_f32 v[142:143], v[142:143], v[146:147]
	s_waitcnt vmcnt(41)
; #define U_LD(p) ({ const v2u w_ = *(const v2u*)(p); (f32x4){bflo(w_.x), bfhi(w_.x), bflo(w_.y), bfhi(w_.y)}; })
; __device__ __forceinline__ void p3_pool(Frame& F) {
;     ...
;         for (int i = 0; i < nsteps; ++i) {
;             const int s = s0 - 15 + i;
;             const int so = s - w;
;             f32x4 n0 = (f32x4){0.f, 0.f, 0.f, 0.f}, o0 = n0;
;             if (isP) {
;                 if (s >= 0) n0 = U_LD(U + (mbase + s) * 512 + c0);
;                 if (i >= w && so >= 0) o0 = U_LD(U + (mbase + so) * 512 + c0);
;             } else {
;                 if (s >= 0) n0 = U_LD(U + (mbase + s) * 512 + c0); else n0 = *(const f32x4*)(state_pool + ((size_t)b * 15 + (s + 15)) * 512 + c0);
;                 if (i >= w) { if (so >= 0) o0 = U_LD(U + (mbase + so) * 512 + c0); else o0 = *(const f32x4*)(state_pool + ((size_t)b * 15 + (so + 15)) * 512 + c0); }
;             }
;             S0 += n0 - o0;
	v_lshlrev_b32_e32 v144, 16, v50
	v_and_b32_e32 v145, 0xffff0000, v50
	v_lshlrev_b32_e32 v146, 16, v51
	v_and_b32_e32 v147, 0xffff0000, v51
	v_pk_add_f32 v[140:141], v[140:141], v[144:145]
	v_pk_add_f32 v[142:143], v[142:143], v[146:147]
	s_waitcnt vmcnt(40)
	v_lshlrev_b32_e32 v144, 16, v52
	v_and_b32_e32 v145, 0xffff0000, v52
	v_lshlrev_b32_e32 v146, 16, v53
	v_and_b32_e32 v147, 0xffff0000, v53
	v_pk_add_f32 v[140:141], v[140:141], v[144:145]
	v_pk_add_f32 v[142:143], v[142:143], v[146:147]
	s_waitcnt vmcnt(39)
	v_lshlrev_b32_e32 v144, 16, v54
	v_and_b32_e32 v145, 0xffff0000, v54
	v_lshlrev_b32_e32 v146, 16, v55
	v_and_b32_e32 v147, 0xffff0000, v55
	v_pk_add_f32 v[140:141], v[140:141], v[144:145]
	v_pk_add_f32 v[142:143], v[142:143], v[146:147]
	s_waitcnt vmcnt(38)
	v_lshlrev_b32_e32 v144, 16, v56
	v_and_b32_e32 v145, 0xffff0000, v56
	v_lshlrev_b32_e32 v146, 16, v57
	v_and_b32_e32 v147, 0xffff0000, v57
	v_cndmask_b32_e64 v148, v40, v166, s[94:95]
	v_cndmask_b32_e64 v149, v41, v167, s[94:95]
	v_lshlrev_b32_e32 v150, 16, v148
	v_and_b32_e32 v151, 0xffff0000, v148
	v_lshlrev_b32_e32 v152, 16, v149
	v_and_b32_e32 v153, 0xffff0000, v149
	v_pk_add_f32 v[154:155], v[144:145], v[150:151] neg_lo:[0,1] neg_hi:[0,1]
	v_pk_add_f32 v[156:157], v[146:147], v[152:153] neg_lo:[0,1] neg_hi:[0,1]
	v_pk_add_f32 v[140:141], v[140:141], v[154:155]
	v_pk_add_f32 v[142:143], v[142:143], v[156:157]
	s_waitcnt vmcnt(37)
	v_lshlrev_b32_e32 v144, 16, v58
	v_and_b32_e32 v145, 0xffff0000, v58
	v_lshlrev_b32_e32 v146, 16, v59
	v_and_b32_e32 v147, 0xffff0000, v59
	v_cndmask_b32_e64 v148, v42, v166, s[94:95]
	v_cndmask_b32_e64 v149, v43, v167, s[94:95]
	v_lshlrev_b32_e32 v150, 16, v148
	v_and_b32_e32 v151, 0xffff0000, v148
	v_lshlrev_b32_e32 v152, 16, v149
	v_and_b32_e32 v153, 0xffff0000, v149
	v_pk_add_f32 v[154:155], v[144:145], v[150:151] neg_lo:[0,1] neg_hi:[0,1]
	v_pk_add_f32 v[156:157], v[146:147], v[152:153] neg_lo:[0,1] neg_hi:[0,1]
	v_pk_add_f32 v[140:141], v[140:141], v[154:155]
	v_pk_add_f32 v[142:143], v[142:143], v[156:157]
	s_waitcnt vmcnt(36)
	v_lshlrev_b32_e32 v144, 16, v60
	v_and_b32_e32 v145, 0xffff0000, v60
	v_lshlrev_b32_e32 v146, 16, v61
	v_and_b32_e32 v147, 0xffff0000, v61
	v_cndmask_b32_e64 v148, v44, v166, s[94:95]
	v_cndmask_b32_e64 v149, v45, v167, s[94:95]
	v_lshlrev_b32_e32 v150, 16, v148
	v_and_b32_e32 v151, 0xffff0000, v148
	v_lshlrev_b32_e32 v152, 16, v149
	v_and_b32_e32 v153, 0xffff0000, v149
	v_pk_add_f32 v[154:155], v[144:145], v[150:151] neg_lo:[0,1] neg_hi:[0,1]
	v_pk_add_f32 v[156:157], v[146:147], v[152:153] neg_lo:[0,1] neg_hi:[0,1]
	v_pk_add_f32 v[140:141], v[140:141], v[154:155]
	v_pk_add_f32 v[142:143], v[142:143], v[156:157]
	s_waitcnt vmcnt(35)
	v_lshlrev_b32_e32 v144, 16, v62
	v_and_b32_e32 v145, 0xffff0000, v62
	v_lshlrev_b32_e32 v146, 16, v63
	v_and_b32_e32 v147, 0xffff0000, v63
	v_cndmask_b32_e64 v148, v46, v166, s[94:95]
	v_cndmask_b32_e64 v149, v47, v167, s[94:95]
	v_lshlrev_b32_e32 v150, 16, v148
	v_and_b32_e32 v151, 0xffff0000, v148
	v_lshlrev_b32_e32 v152, 16, v149
	v_and_b32_e32 v153, 0xffff0000, v149
	v_pk_add_f32 v[154:155], v[144:145], v[150:151] neg_lo:[0,1] neg_hi:[0,1]
	v_pk_add_f32 v[156:157], v[146:147], v[152:153] neg_lo:[0,1] neg_hi:[0,1]
	v_pk_add_f32 v[140:141], v[140:141], v[154:155]
	v_pk_add_f32 v[142:143], v[142:143], v[156:157]
	s_waitcnt vmcnt(34)
	v_lshlrev_b32_e32 v144, 16, v64
	v_and_b32_e32 v145, 0xffff0000, v64
	v_lshlrev_b32_e32 v146, 16, v65
	v_and_b32_e32 v147, 0xffff0000, v65
	v_cndmask_b32_e64 v148, v48, v166, s[94:95]
	v_cndmask_b32_e64 v149, v49, v167, s[94:95]
	v_lshlrev_b32_e32 v150, 16, v148
	v_and_b32_e32 v151, 0xffff0000, v148
	v_lshlrev_b32_e32 v152, 16, v149
	v_and_b32_e32 v153, 0xffff0000, v149
	v_pk_add_f32 v[154:155], v[144:145], v[150:151] neg_lo:[0,1] neg_hi:[0,1]
	v_pk_add_f32 v[156:157], v[146:147], v[152:153] neg_lo:[0,1] neg_hi:[0,1]
	v_pk_add_f32 v[140:141], v[140:141], v[154:155]
	v_pk_add_f32 v[142:143], v[142:143], v[156:157]
	s_waitcnt vmcnt(33)
	v_lshlrev_b32_e32 v144, 16, v66
	v_and_b32_e32 v145, 0xffff0000, v66
	v_lshlrev_b32_e32 v146, 16, v67
	v_and_b32_e32 v147, 0xffff0000, v67
	v_cndmask_b32_e64 v148, v50, v166, s[94:95]
	v_cndmask_b32_e64 v149, v51, v167, s[94:95]
	v_lshlrev_b32_e32 v150, 16, v148
	v_and_b32_e32 v151, 0xffff0000, v148
	v_lshlrev_b32_e32 v152, 16, v149
	v_and_b32_e32 v153, 0xffff0000, v149
	v_pk_add_f32 v[154:155], v[144:145], v[150:151] neg_lo:[0,1] neg_hi:[0,1]
	v_pk_add_f32 v[156:157], v[146:147], v[152:153] neg_lo:[0,1] neg_hi:[0,1]
	v_pk_add_f32 v[140:141], v[140:141], v[154:155]
	v_pk_add_f32 v[142:143], v[142:143], v[156:157]
	s_waitcnt vmcnt(32)
	v_lshlrev_b32_e32 v144, 16, v68
	v_and_b32_e32 v145, 0xffff0000, v68
	v_lshlrev_b32_e32 v146, 16, v69
	v_and_b32_e32 v147, 0xffff0000, v69
	v_cndmask_b32_e64 v148, v52, v166, s[94:95]
	v_cndmask_b32_e64 v149, v53, v167, s[94:95]
	v_lshlrev_b32_e32 v150, 16, v148
	v_and_b32_e32 v151, 0xffff0000, v148
	v_lshlrev_b32_e32 v152, 16, v149
	v_and_b32_e32 v153, 0xffff0000, v149
	v_pk_add_f32 v[154:155], v[144:145], v[150:151] neg_lo:[0,1] neg_hi:[0,1]
	v_pk_add_f32 v[156:157], v[146:147], v[152:153] neg_lo:[0,1] neg_hi:[0,1]
	v_pk_add_f32 v[140:141], v[140:141], v[154:155]
	v_pk_add_f32 v[142:143], v[142:143], v[156:157]
	s_waitcnt vmcnt(31)
; #define GAS __attribute__((address_space(1)))
; __device__ __forceinline__ unsigned pk2(float lo, float hi) { f32x2_t v = {lo, hi}; bf16x2_t b = __builtin_convertvector(v, bf16x2_t); return __builtin_bit_cast(unsigned, b); }
; #define U_LD(p) ({ const v2u w_ = *(const v2u*)(p); (f32x4){bflo(w_.x), bfhi(w_.x), bflo(w_.y), bfhi(w_.y)}; })
; __device__ __forceinline__ void p3_pool(Frame& F) {
;     ...
;         for (int i = 0; i < nsteps; ++i) {
;             const int s = s0 - 15 + i;
;             const int so = s - w;
;             f32x4 n0 = (f32x4){0.f, 0.f, 0.f, 0.f}, o0 = n0;
;             if (isP) {
;                 if (s >= 0) n0 = U_LD(U + (mbase + s) * 512 + c0);
;                 if (i >= w && so >= 0) o0 = U_LD(U + (mbase + so) * 512 + c0);
;             } else {
;                 if (s >= 0) n0 = U_LD(U + (mbase + s) * 512 + c0); else n0 = *(const f32x4*)(state_pool + ((size_t)b * 15 + (s + 15)) * 512 + c0);
;                 if (i >= w) { if (so >= 0) o0 = U_LD(U + (mbase + so) * 512 + c0); else o0 = *(const f32x4*)(state_pool + ((size_t)b * 15 + (so + 15)) * 512 + c0); }
;             }
;             S0 += n0 - o0;
;             if (i >= 15) {
;                 const int cnt = isP ? (w < s + 1 ? w : s + 1) : w; const float inv = 1.f / (float)cnt;
;                 const f32x4 d0 = S0 * inv - n0;
;                 v2u wv; wv.x = pk2(d0[0], d0[1]); wv.y = pk2(d0[2], d0[3]);
;                 *(GAS v2u*)(D + (size_t)(c0 >> 8) * ((size_t)MT * 256) + (mbase + s) * 256 + (c0 & 255)) = wv;
	v_lshlrev_b32_e32 v144, 16, v70
	v_and_b32_e32 v145, 0xffff0000, v70
	v_lshlrev_b32_e32 v146, 16, v71
	v_and_b32_e32 v147, 0xffff0000, v71
	v_cndmask_b32_e64 v148, v54, v166, s[94:95]
	v_cndmask_b32_e64 v149, v55, v167, s[94:95]
	v_lshlrev_b32_e32 v150, 16, v148
	v_and_b32_e32 v151, 0xffff0000, v148
	v_lshlrev_b32_e32 v152, 16, v149
	v_and_b32_e32 v153, 0xffff0000, v149
	v_pk_add_f32 v[154:155], v[144:145], v[150:151] neg_lo:[0,1] neg_hi:[0,1]
	v_pk_add_f32 v[156:157], v[146:147], v[152:153] neg_lo:[0,1] neg_hi:[0,1]
	v_pk_add_f32 v[140:141], v[140:141], v[154:155]
	v_pk_add_f32 v[142:143], v[142:143], v[156:157]
	v_pk_fma_f32 v[158:159], v[164:165], v[140:141], v[144:145] op_sel_hi:[0,1,1] neg_lo:[0,0,1] neg_hi:[0,0,1]
	v_pk_fma_f32 v[160:161], v[164:165], v[142:143], v[146:147] op_sel_hi:[0,1,1] neg_lo:[0,0,1] neg_hi:[0,0,1]
	v_cvt_pk_bf16_f32 v162, v158, v159
	v_cvt_pk_bf16_f32 v163, v160, v161
	global_store_dwordx2 v36, v[162:163], s[96:97]
	s_waitcnt vmcnt(31)
	v_lshlrev_b32_e32 v144, 16, v72
	v_and_b32_e32 v145, 0xffff0000, v72
	v_lshlrev_b32_e32 v146, 16, v73
	v_and_b32_e32 v147, 0xffff0000, v73
	v_cndmask_b32_e64 v148, v56, v40, s[94:95]
	v_cndmask_b32_e64 v149, v57, v41, s[94:95]
	v_lshlrev_b32_e32 v150, 16, v148
	v_and_b32_e32 v151, 0xffff0000, v148
	v_lshlrev_b32_e32 v152, 16, v149
	v_and_b32_e32 v153, 0xffff0000, v149
	v_pk_add_f32 v[154:155], v[144:145], v[150:151] neg_lo:[0,1] neg_hi:[0,1]
	v_pk_add_f32 v[156:157], v[146:147], v[152:153] neg_lo:[0,1] neg_hi:[0,1]
	v_pk_add_f32 v[140:141], v[140:141], v[154:155]
	v_pk_add_f32 v[142:143], v[142:143], v[156:157]
	v_pk_fma_f32 v[158:159], v[164:165], v[140:141], v[144:145] op_sel_hi:[0,1,1] neg_lo:[0,0,1] neg_hi:[0,0,1]
	v_pk_fma_f32 v[160:161], v[164:165], v[142:143], v[146:147] op_sel_hi:[0,1,1] neg_lo:[0,0,1] neg_hi:[0,0,1]
	v_cvt_pk_bf16_f32 v162, v158, v159
	v_cvt_pk_bf16_f32 v163, v160, v161
	global_store_dwordx2 v36, v[162:163], s[96:97] offset:512
	s_waitcnt vmcnt(31)
	v_lshlrev_b32_e32 v144, 16, v74
	v_and_b32_e32 v145, 0xffff0000, v74
	v_lshlrev_b32_e32 v146, 16, v75
	v_and_b32_e32 v147, 0xffff0000, v75
	v_cndmask_b32_e64 v148, v58, v42, s[94:95]
	v_cndmask_b32_e64 v149, v59, v43, s[94:95]
	v_lshlrev_b32_e32 v150, 16, v148
	v_and_b32_e32 v151, 0xffff0000, v148
	v_lshlrev_b32_e32 v152, 16, v149
	v_and_b32_e32 v153, 0xffff0000, v149
	v_pk_add_f32 v[154:155], v[144:145], v[150:151] neg_lo:[0,1] neg_hi:[0,1]
	v_pk_add_f32 v[156:157], v[146:147], v[152:153] neg_lo:[0,1] neg_hi:[0,1]
	v_pk_add_f32 v[140:141], v[140:141], v[154:155]
	v_pk_add_f32 v[142:143], v[142:143], v[156:157]
	v_pk_fma_f32 v[158:159], v[164:165], v[140:141], v[144:145] op_sel_hi:[0,1,1] neg_lo:[0,0,1] neg_hi:[0,0,1]
	v_pk_fma_f32 v[160:161], v[164:165], v[142:143], v[146:147] op_sel_hi:[0,1,1] neg_lo:[0,0,1] neg_hi:[0,0,1]
	v_cvt_pk_bf16_f32 v162, v158, v159
	v_cvt_pk_bf16_f32 v163, v160, v161
	global_store_dwordx2 v36, v[162:163], s[96:97] offset:1024
	s_waitcnt vmcnt(31)
	v_lshlrev_b32_e32 v144, 16, v76
	v_and_b32_e32 v145, 0xffff0000, v76
	v_lshlrev_b32_e32 v146, 16, v77
	v_and_b32_e32 v147, 0xffff0000, v77
	v_cndmask_b32_e64 v148, v60, v44, s[94:95]
	v_cndmask_b32_e64 v149, v61, v45, s[94:95]
	v_lshlrev_b32_e32 v150, 16, v148
	v_and_b32_e32 v151, 0xffff0000, v148
	v_lshlrev_b32_e32 v152, 16, v149
	v_and_b32_e32 v153, 0xffff0000, v149
	v_pk_add_f32 v[154:155], v[144:145], v[150:151] neg_lo:[0,1] neg_hi:[0,1]
	v_pk_add_f32 v[156:157], v[146:147], v[152:153] neg_lo:[0,1] neg_hi:[0,1]
	v_pk_add_f32 v[140:141], v[140:141], v[154:155]
	v_pk_add_f32 v[142:143], v[142:143], v[156:157]
	v_pk_fma_f32 v[158:159], v[164:165], v[140:141], v[144:145] op_sel_hi:[0,1,1] neg_lo:[0,0,1] neg_hi:[0,0,1]
	v_pk_fma_f32 v[160:161], v[164:165], v[142:143], v[146:147] op_sel_hi:[0,1,1] neg_lo:[0,0,1] neg_hi:[0,0,1]
	v_cvt_pk_bf16_f32 v162, v158, v159
	v_cvt_pk_bf16_f32 v163, v160, v161
	global_store_dwordx2 v36, v[162:163], s[96:97] offset:1536
	s_waitcnt vmcnt(31)
	v_lshlrev_b32_e32 v144, 16, v78
	v_and_b32_e32 v145, 0xffff0000, v78
	v_lshlrev_b32_e32 v146, 16, v79
	v_and_b32_e32 v147, 0xffff0000, v79
	v_cndmask_b32_e64 v148, v62, v46, s[94:95]
	v_cndmask_b32_e64 v149, v63, v47, s[94:95]
	v_lshlrev_b32_e32 v150, 16, v148
	v_and_b32_e32 v151, 0xffff0000, v148
	v_lshlrev_b32_e32 v152, 16, v149
	v_and_b32_e32 v153, 0xffff0000, v149
	v_pk_add_f32 v[154:155], v[144:145], v[150:151] neg_lo:[0,1] neg_hi:[0,1]
	v_pk_add_f32 v[156:157], v[146:147], v[152:153] neg_lo:[0,1] neg_hi:[0,1]
	v_pk_add_f32 v[140:141], v[140:141], v[154:155]
	v_pk_add_f32 v[142:143], v[142:143], v[156:157]
	v_pk_fma_f32 v[158:159], v[164:165], v[140:141], v[144:145] op_sel_hi:[0,1,1] neg_lo:[0,0,1] neg_hi:[0,0,1]
	v_pk_fma_f32 v[160:161], v[164:165], v[142:143], v[146:147] op_sel_hi:[0,1,1] neg_lo:[0,0,1] neg_hi:[0,0,1]
	v_cvt_pk_bf16_f32 v162, v158, v159
	v_cvt_pk_bf16_f32 v163, v160, v161
	global_store_dwordx2 v36, v[162:163], s[96:97] offset:2048
	s_waitcnt vmcnt(31)
	v_lshlrev_b32_e32 v144, 16, v80
	v_and_b32_e32 v145, 0xffff0000, v80
	v_lshlrev_b32_e32 v146, 16, v81
	v_and_b32_e32 v147, 0xffff0000, v81
	v_cndmask_b32_e64 v148, v64, v48, s[94:95]
	v_cndmask_b32_e64 v149, v65, v49, s[94:95]
	v_lshlrev_b32_e32 v150, 16, v148
	v_and_b32_e32 v151, 0xffff0000, v148
	v_lshlrev_b32_e32 v152, 16, v149
	v_and_b32_e32 v153, 0xffff0000, v149
	v_pk_add_f32 v[154:155], v[144:145], v[150:151] neg_lo:[0,1] neg_hi:[0,1]
	v_pk_add_f32 v[156:157], v[146:147], v[152:153] neg_lo:[0,1] neg_hi:[0,1]
	v_pk_add_f32 v[140:141], v[140:141], v[154:155]
	v_pk_add_f32 v[142:143], v[142:143], v[156:157]
	v_pk_fma_f32 v[158:159], v[164:165], v[140:141], v[144:145] op_sel_hi:[0,1,1] neg_lo:[0,0,1] neg_hi:[0,0,1]
	v_pk_fma_f32 v[160:161], v[164:165], v[142:143], v[146:147] op_sel_hi:[0,1,1] neg_lo:[0,0,1] neg_hi:[0,0,1]
	v_cvt_pk_bf16_f32 v162, v158, v159
	v_cvt_pk_bf16_f32 v163, v160, v161
	global_store_dwordx2 v36, v[162:163], s[96:97] offset:2560
	s_waitcnt vmcnt(31)
; #define GAS __attribute__((address_space(1)))
; __device__ __forceinline__ unsigned pk2(float lo, float hi) { f32x2_t v = {lo, hi}; bf16x2_t b = __builtin_convertvector(v, bf16x2_t); return __builtin_bit_cast(unsigned, b); }
; #define U_LD(p) ({ const v2u w_ = *(const v2u*)(p); (f32x4){bflo(w_.x), bfhi(w_.x), bflo(w_.y), bfhi(w_.y)}; })
; __device__ __forceinline__ void p3_pool(Frame& F) {
;     ...
;         for (int i = 0; i < nsteps; ++i) {
;             const int s = s0 - 15 + i;
;             const int so = s - w;
;             f32x4 n0 = (f32x4){0.f, 0.f, 0.f, 0.f}, o0 = n0;
;             if (isP) {
;                 if (s >= 0) n0 = U_LD(U + (mbase + s) * 512 + c0);
;                 if (i >= w && so >= 0) o0 = U_LD(U + (mbase + so) * 512 + c0);
;             } else {
;                 if (s >= 0) n0 = U_LD(U + (mbase + s) * 512 + c0); else n0 = *(const f32x4*)(state_pool + ((size_t)b * 15 + (s + 15)) * 512 + c0);
;                 if (i >= w) { if (so >= 0) o0 = U_LD(U + (mbase + so) * 512 + c0); else o0 = *(const f32x4*)(state_pool + ((size_t)b * 15 + (so + 15)) * 512 + c0); }
;             }
;             S0 += n0 - o0;
;             if (i >= 15) {
;                 const int cnt = isP ? (w < s + 1 ? w : s + 1) : w; const float inv = 1.f / (float)cnt;
;                 const f32x4 d0 = S0 * inv - n0;
;                 v2u wv; wv.x = pk2(d0[0], d0[1]); wv.y = pk2(d0[2], d0[3]);
;                 *(GAS v2u*)(D + (size_t)(c0 >> 8) * ((size_t)MT * 256) + (mbase + s) * 256 + (c0 & 255)) = wv;
	v_lshlrev_b32_e32 v144, 16, v82
	v_and_b32_e32 v145, 0xffff0000, v82
	v_lshlrev_b32_e32 v146, 16, v83
	v_and_b32_e32 v147, 0xffff0000, v83
	v_cndmask_b32_e64 v148, v66, v50, s[94:95]
	v_cndmask_b32_e64 v149, v67, v51, s[94:95]
	v_lshlrev_b32_e32 v150, 16, v148
	v_and_b32_e32 v151, 0xffff0000, v148
	v_lshlrev_b32_e32 v152, 16, v149
	v_and_b32_e32 v153, 0xffff0000, v149
	v_pk_add_f32 v[154:155], v[144:145], v[150:151] neg_lo:[0,1] neg_hi:[0,1]
	v_pk_add_f32 v[156:157], v[146:147], v[152:153] neg_lo:[0,1] neg_hi:[0,1]
	v_pk_add_f32 v[140:141], v[140:141], v[154:155]
	v_pk_add_f32 v[142:143], v[142:143], v[156:157]
	v_pk_fma_f32 v[158:159], v[164:165], v[140:141], v[144:145] op_sel_hi:[0,1,1] neg_lo:[0,0,1] neg_hi:[0,0,1]
	v_pk_fma_f32 v[160:161], v[164:165], v[142:143], v[146:147] op_sel_hi:[0,1,1] neg_lo:[0,0,1] neg_hi:[0,0,1]
	v_cvt_pk_bf16_f32 v162, v158, v159
	v_cvt_pk_bf16_f32 v163, v160, v161
	global_store_dwordx2 v36, v[162:163], s[96:97] offset:3072
	s_waitcnt vmcnt(31)
	v_lshlrev_b32_e32 v144, 16, v84
	v_and_b32_e32 v145, 0xffff0000, v84
	v_lshlrev_b32_e32 v146, 16, v85
	v_and_b32_e32 v147, 0xffff0000, v85
	v_cndmask_b32_e64 v148, v68, v52, s[94:95]
	v_cndmask_b32_e64 v149, v69, v53, s[94:95]
	v_lshlrev_b32_e32 v150, 16, v148
	v_and_b32_e32 v151, 0xffff0000, v148
	v_lshlrev_b32_e32 v152, 16, v149
	v_and_b32_e32 v153, 0xffff0000, v149
	v_pk_add_f32 v[154:155], v[144:145], v[150:151] neg_lo:[0,1] neg_hi:[0,1]
	v_pk_add_f32 v[156:157], v[146:147], v[152:153] neg_lo:[0,1] neg_hi:[0,1]
	v_pk_add_f32 v[140:141], v[140:141], v[154:155]
	v_pk_add_f32 v[142:143], v[142:143], v[156:157]
	v_pk_fma_f32 v[158:159], v[164:165], v[140:141], v[144:145] op_sel_hi:[0,1,1] neg_lo:[0,0,1] neg_hi:[0,0,1]
	v_pk_fma_f32 v[160:161], v[164:165], v[142:143], v[146:147] op_sel_hi:[0,1,1] neg_lo:[0,0,1] neg_hi:[0,0,1]
	v_cvt_pk_bf16_f32 v162, v158, v159
	v_cvt_pk_bf16_f32 v163, v160, v161
	global_store_dwordx2 v36, v[162:163], s[96:97] offset:3584
	s_add_u32 s96, s96, 0x1000
	s_addc_u32 s97, s97, 0
	s_waitcnt vmcnt(31)
	v_lshlrev_b32_e32 v144, 16, v86
	v_and_b32_e32 v145, 0xffff0000, v86
	v_lshlrev_b32_e32 v146, 16, v87
	v_and_b32_e32 v147, 0xffff0000, v87
	v_cndmask_b32_e64 v148, v70, v54, s[94:95]
	v_cndmask_b32_e64 v149, v71, v55, s[94:95]
	v_lshlrev_b32_e32 v150, 16, v148
	v_and_b32_e32 v151, 0xffff0000, v148
	v_lshlrev_b32_e32 v152, 16, v149
	v_and_b32_e32 v153, 0xffff0000, v149
	v_pk_add_f32 v[154:155], v[144:145], v[150:151] neg_lo:[0,1] neg_hi:[0,1]
	v_pk_add_f32 v[156:157], v[146:147], v[152:153] neg_lo:[0,1] neg_hi:[0,1]
	v_pk_add_f32 v[140:141], v[140:141], v[154:155]
	v_pk_add_f32 v[142:143], v[142:143], v[156:157]
	v_pk_fma_f32 v[158:159], v[164:165], v[140:141], v[144:145] op_sel_hi:[0,1,1] neg_lo:[0,0,1] neg_hi:[0,0,1]
	v_pk_fma_f32 v[160:161], v[164:165], v[142:143], v[146:147] op_sel_hi:[0,1,1] neg_lo:[0,0,1] neg_hi:[0,0,1]
	v_cvt_pk_bf16_f32 v162, v158, v159
	v_cvt_pk_bf16_f32 v163, v160, v161
	global_store_dwordx2 v36, v[162:163], s[96:97]
	s_waitcnt vmcnt(31)
	v_lshlrev_b32_e32 v144, 16, v88
	v_and_b32_e32 v145, 0xffff0000, v88
	v_lshlrev_b32_e32 v146, 16, v89
	v_and_b32_e32 v147, 0xffff0000, v89
	v_cndmask_b32_e64 v148, v72, v56, s[94:95]
	v_cndmask_b32_e64 v149, v73, v57, s[94:95]
	v_lshlrev_b32_e32 v150, 16, v148
	v_and_b32_e32 v151, 0xffff0000, v148
	v_lshlrev_b32_e32 v152, 16, v149
	v_and_b32_e32 v153, 0xffff0000, v149
	v_pk_add_f32 v[154:155], v[144:145], v[150:151] neg_lo:[0,1] neg_hi:[0,1]
	v_pk_add_f32 v[156:157], v[146:147], v[152:153] neg_lo:[0,1] neg_hi:[0,1]
	v_pk_add_f32 v[140:141], v[140:141], v[154:155]
	v_pk_add_f32 v[142:143], v[142:143], v[156:157]
	v_pk_fma_f32 v[158:159], v[164:165], v[140:141], v[144:145] op_sel_hi:[0,1,1] neg_lo:[0,0,1] neg_hi:[0,0,1]
	v_pk_fma_f32 v[160:161], v[164:165], v[142:143], v[146:147] op_sel_hi:[0,1,1] neg_lo:[0,0,1] neg_hi:[0,0,1]
	v_cvt_pk_bf16_f32 v162, v158, v159
	v_cvt_pk_bf16_f32 v163, v160, v161
	global_store_dwordx2 v36, v[162:163], s[96:97] offset:512
	s_waitcnt vmcnt(31)
	v_lshlrev_b32_e32 v144, 16, v90
	v_and_b32_e32 v145, 0xffff0000, v90
	v_lshlrev_b32_e32 v146, 16, v91
	v_and_b32_e32 v147, 0xffff0000, v91
	v_cndmask_b32_e64 v148, v74, v58, s[94:95]
	v_cndmask_b32_e64 v149, v75, v59, s[94:95]
	v_lshlrev_b32_e32 v150, 16, v148
	v_and_b32_e32 v151, 0xffff0000, v148
	v_lshlrev_b32_e32 v152, 16, v149
	v_and_b32_e32 v153, 0xffff0000, v149
	v_pk_add_f32 v[154:155], v[144:145], v[150:151] neg_lo:[0,1] neg_hi:[0,1]
	v_pk_add_f32 v[156:157], v[146:147], v[152:153] neg_lo:[0,1] neg_hi:[0,1]
	v_pk_add_f32 v[140:141], v[140:141], v[154:155]
	v_pk_add_f32 v[142:143], v[142:143], v[156:157]
	v_pk_fma_f32 v[158:159], v[164:165], v[140:141], v[144:145] op_sel_hi:[0,1,1] neg_lo:[0,0,1] neg_hi:[0,0,1]
	v_pk_fma_f32 v[160:161], v[164:165], v[142:143], v[146:147] op_sel_hi:[0,1,1] neg_lo:[0,0,1] neg_hi:[0,0,1]
	v_cvt_pk_bf16_f32 v162, v158, v159
	v_cvt_pk_bf16_f32 v163, v160, v161
	global_store_dwordx2 v36, v[162:163], s[96:97] offset:1024
	s_waitcnt vmcnt(31)
	v_lshlrev_b32_e32 v144, 16, v92
	v_and_b32_e32 v145, 0xffff0000, v92
	v_lshlrev_b32_e32 v146, 16, v93
	v_and_b32_e32 v147, 0xffff0000, v93
	v_cndmask_b32_e64 v148, v76, v60, s[94:95]
	v_cndmask_b32_e64 v149, v77, v61, s[94:95]
	v_lshlrev_b32_e32 v150, 16, v148
	v_and_b32_e32 v151, 0xffff0000, v148
	v_lshlrev_b32_e32 v152, 16, v149
	v_and_b32_e32 v153, 0xffff0000, v149
	v_pk_add_f32 v[154:155], v[144:145], v[150:151] neg_lo:[0,1] neg_hi:[0,1]
	v_pk_add_f32 v[156:157], v[146:147], v[152:153] neg_lo:[0,1] neg_hi:[0,1]
	v_pk_add_f32 v[140:141], v[140:141], v[154:155]
	v_pk_add_f32 v[142:143], v[142:143], v[156:157]
	v_pk_fma_f32 v[158:159], v[164:165], v[140:141], v[144:145] op_sel_hi:[0,1,1] neg_lo:[0,0,1] neg_hi:[0,0,1]
	v_pk_fma_f32 v[160:161], v[164:165], v[142:143], v[146:147] op_sel_hi:[0,1,1] neg_lo:[0,0,1] neg_hi:[0,0,1]
	v_cvt_pk_bf16_f32 v162, v158, v159
	v_cvt_pk_bf16_f32 v163, v160, v161
	global_store_dwordx2 v36, v[162:163], s[96:97] offset:1536
	s_waitcnt vmcnt(31)
; #define GAS __attribute__((address_space(1)))
; __device__ __forceinline__ unsigned pk2(float lo, float hi) { f32x2_t v = {lo, hi}; bf16x2_t b = __builtin_convertvector(v, bf16x2_t); return __builtin_bit_cast(unsigned, b); }
; #define U_LD(p) ({ const v2u w_ = *(const v2u*)(p); (f32x4){bflo(w_.x), bfhi(w_.x), bflo(w_.y), bfhi(w_.y)}; })
; __device__ __forceinline__ void p3_pool(Frame& F) {
;     ...
;         for (int i = 0; i < nsteps; ++i) {
;             const int s = s0 - 15 + i;
;             const int so = s - w;
;             f32x4 n0 = (f32x4){0.f, 0.f, 0.f, 0.f}, o0 = n0;
;             if (isP) {
;                 if (s >= 0) n0 = U_LD(U + (mbase + s) * 512 + c0);
;                 if (i >= w && so >= 0) o0 = U_LD(U + (mbase + so) * 512 + c0);
;             } else {
;                 if (s >= 0) n0 = U_LD(U + (mbase + s) * 512 + c0); else n0 = *(const f32x4*)(state_pool + ((size_t)b * 15 + (s + 15)) * 512 + c0);
;                 if (i >= w) { if (so >= 0) o0 = U_LD(U + (mbase + so) * 512 + c0); else o0 = *(const f32x4*)(state_pool + ((size_t)b * 15 + (so + 15)) * 512 + c0); }
;             }
;             S0 += n0 - o0;
;             if (i >= 15) {
;                 const int cnt = isP ? (w < s + 1 ? w : s + 1) : w; const float inv = 1.f / (float)cnt;
;                 const f32x4 d0 = S0 * inv - n0;
;                 v2u wv; wv.x = pk2(d0[0], d0[1]); wv.y = pk2(d0[2], d0[3]);
;                 *(GAS v2u*)(D + (size_t)(c0 >> 8) * ((size_t)MT * 256) + (mbase + s) * 256 + (c0 & 255)) = wv;
	v_lshlrev_b32_e32 v144, 16, v94
	v_and_b32_e32 v145, 0xffff0000, v94
	v_lshlrev_b32_e32 v146, 16, v95
	v_and_b32_e32 v147, 0xffff0000, v95
	v_cndmask_b32_e64 v148, v78, v62, s[94:95]
	v_cndmask_b32_e64 v149, v79, v63, s[94:95]
	v_lshlrev_b32_e32 v150, 16, v148
	v_and_b32_e32 v151, 0xffff0000, v148
	v_lshlrev_b32_e32 v152, 16, v149
	v_and_b32_e32 v153, 0xffff0000, v149
	v_pk_add_f32 v[154:155], v[144:145], v[150:151] neg_lo:[0,1] neg_hi:[0,1]
	v_pk_add_f32 v[156:157], v[146:147], v[152:153] neg_lo:[0,1] neg_hi:[0,1]
	v_pk_add_f32 v[140:141], v[140:141], v[154:155]
	v_pk_add_f32 v[142:143], v[142:143], v[156:157]
	v_pk_fma_f32 v[158:159], v[164:165], v[140:141], v[144:145] op_sel_hi:[0,1,1] neg_lo:[0,0,1] neg_hi:[0,0,1]
	v_pk_fma_f32 v[160:161], v[164:165], v[142:143], v[146:147] op_sel_hi:[0,1,1] neg_lo:[0,0,1] neg_hi:[0,0,1]
	v_cvt_pk_bf16_f32 v162, v158, v159
	v_cvt_pk_bf16_f32 v163, v160, v161
	global_store_dwordx2 v36, v[162:163], s[96:97] offset:2048
	s_waitcnt vmcnt(31)
	v_lshlrev_b32_e32 v144, 16, v96
	v_and_b32_e32 v145, 0xffff0000, v96
	v_lshlrev_b32_e32 v146, 16, v97
	v_and_b32_e32 v147, 0xffff0000, v97
	v_cndmask_b32_e64 v148, v80, v64, s[94:95]
	v_cndmask_b32_e64 v149, v81, v65, s[94:95]
	v_lshlrev_b32_e32 v150, 16, v148
	v_and_b32_e32 v151, 0xffff0000, v148
	v_lshlrev_b32_e32 v152, 16, v149
	v_and_b32_e32 v153, 0xffff0000, v149
	v_pk_add_f32 v[154:155], v[144:145], v[150:151] neg_lo:[0,1] neg_hi:[0,1]
	v_pk_add_f32 v[156:157], v[146:147], v[152:153] neg_lo:[0,1] neg_hi:[0,1]
	v_pk_add_f32 v[140:141], v[140:141], v[154:155]
	v_pk_add_f32 v[142:143], v[142:143], v[156:157]
	v_pk_fma_f32 v[158:159], v[164:165], v[140:141], v[144:145] op_sel_hi:[0,1,1] neg_lo:[0,0,1] neg_hi:[0,0,1]
	v_pk_fma_f32 v[160:161], v[164:165], v[142:143], v[146:147] op_sel_hi:[0,1,1] neg_lo:[0,0,1] neg_hi:[0,0,1]
	v_cvt_pk_bf16_f32 v162, v158, v159
	v_cvt_pk_bf16_f32 v163, v160, v161
	global_store_dwordx2 v36, v[162:163], s[96:97] offset:2560
	s_waitcnt vmcnt(31)
	v_lshlrev_b32_e32 v144, 16, v98
	v_and_b32_e32 v145, 0xffff0000, v98
	v_lshlrev_b32_e32 v146, 16, v99
	v_and_b32_e32 v147, 0xffff0000, v99
	v_cndmask_b32_e64 v148, v82, v66, s[94:95]
	v_cndmask_b32_e64 v149, v83, v67, s[94:95]
	v_lshlrev_b32_e32 v150, 16, v148
	v_and_b32_e32 v151, 0xffff0000, v148
	v_lshlrev_b32_e32 v152, 16, v149
	v_and_b32_e32 v153, 0xffff0000, v149
	v_pk_add_f32 v[154:155], v[144:145], v[150:151] neg_lo:[0,1] neg_hi:[0,1]
	v_pk_add_f32 v[156:157], v[146:147], v[152:153] neg_lo:[0,1] neg_hi:[0,1]
	v_pk_add_f32 v[140:141], v[140:141], v[154:155]
	v_pk_add_f32 v[142:143], v[142:143], v[156:157]
	v_pk_fma_f32 v[158:159], v[164:165], v[140:141], v[144:145] op_sel_hi:[0,1,1] neg_lo:[0,0,1] neg_hi:[0,0,1]
	v_pk_fma_f32 v[160:161], v[164:165], v[142:143], v[146:147] op_sel_hi:[0,1,1] neg_lo:[0,0,1] neg_hi:[0,0,1]
	v_cvt_pk_bf16_f32 v162, v158, v159
	v_cvt_pk_bf16_f32 v163, v160, v161
	global_store_dwordx2 v36, v[162:163], s[96:97] offset:3072
	s_waitcnt vmcnt(31)
	v_lshlrev_b32_e32 v144, 16, v100
	v_and_b32_e32 v145, 0xffff0000, v100
	v_lshlrev_b32_e32 v146, 16, v101
	v_and_b32_e32 v147, 0xffff0000, v101
	v_cndmask_b32_e64 v148, v84, v68, s[94:95]
	v_cndmask_b32_e64 v149, v85, v69, s[94:95]
	v_lshlrev_b32_e32 v150, 16, v148
	v_and_b32_e32 v151, 0xffff0000, v148
	v_lshlrev_b32_e32 v152, 16, v149
	v_and_b32_e32 v153, 0xffff0000, v149
	v_pk_add_f32 v[154:155], v[144:145], v[150:151] neg_lo:[0,1] neg_hi:[0,1]
	v_pk_add_f32 v[156:157], v[146:147], v[152:153] neg_lo:[0,1] neg_hi:[0,1]
	v_pk_add_f32 v[140:141], v[140:141], v[154:155]
	v_pk_add_f32 v[142:143], v[142:143], v[156:157]
	v_pk_fma_f32 v[158:159], v[164:165], v[140:141], v[144:145] op_sel_hi:[0,1,1] neg_lo:[0,0,1] neg_hi:[0,0,1]
	v_pk_fma_f32 v[160:161], v[164:165], v[142:143], v[146:147] op_sel_hi:[0,1,1] neg_lo:[0,0,1] neg_hi:[0,0,1]
	v_cvt_pk_bf16_f32 v162, v158, v159
	v_cvt_pk_bf16_f32 v163, v160, v161
	global_store_dwordx2 v36, v[162:163], s[96:97] offset:3584
	s_add_u32 s96, s96, 0x1000
	s_addc_u32 s97, s97, 0
	s_waitcnt vmcnt(31)
	v_lshlrev_b32_e32 v144, 16, v102
	v_and_b32_e32 v145, 0xffff0000, v102
	v_lshlrev_b32_e32 v146, 16, v103
	v_and_b32_e32 v147, 0xffff0000, v103
	v_cndmask_b32_e64 v148, v86, v70, s[94:95]
	v_cndmask_b32_e64 v149, v87, v71, s[94:95]
	v_lshlrev_b32_e32 v150, 16, v148
	v_and_b32_e32 v151, 0xffff0000, v148
	v_lshlrev_b32_e32 v152, 16, v149
	v_and_b32_e32 v153, 0xffff0000, v149
	v_pk_add_f32 v[154:155], v[144:145], v[150:151] neg_lo:[0,1] neg_hi:[0,1]
	v_pk_add_f32 v[156:157], v[146:147], v[152:153] neg_lo:[0,1] neg_hi:[0,1]
	v_pk_add_f32 v[140:141], v[140:141], v[154:155]
	v_pk_add_f32 v[142:143], v[142:143], v[156:157]
	v_pk_fma_f32 v[158:159], v[164:165], v[140:141], v[144:145] op_sel_hi:[0,1,1] neg_lo:[0,0,1] neg_hi:[0,0,1]
	v_pk_fma_f32 v[160:161], v[164:165], v[142:143], v[146:147] op_sel_hi:[0,1,1] neg_lo:[0,0,1] neg_hi:[0,0,1]
	v_cvt_pk_bf16_f32 v162, v158, v159
	v_cvt_pk_bf16_f32 v163, v160, v161
	global_store_dwordx2 v36, v[162:163], s[96:97]
	s_waitcnt vmcnt(31)
	v_lshlrev_b32_e32 v144, 16, v104
	v_and_b32_e32 v145, 0xffff0000, v104
	v_lshlrev_b32_e32 v146, 16, v105
	v_and_b32_e32 v147, 0xffff0000, v105
	v_cndmask_b32_e64 v148, v88, v72, s[94:95]
	v_cndmask_b32_e64 v149, v89, v73, s[94:95]
	v_lshlrev_b32_e32 v150, 16, v148
	v_and_b32_e32 v151, 0xffff0000, v148
	v_lshlrev_b32_e32 v152, 16, v149
	v_and_b32_e32 v153, 0xffff0000, v149
	v_pk_add_f32 v[154:155], v[144:145], v[150:151] neg_lo:[0,1] neg_hi:[0,1]
	v_pk_add_f32 v[156:157], v[146:147], v[152:153] neg_lo:[0,1] neg_hi:[0,1]
	v_pk_add_f32 v[140:141], v[140:141], v[154:155]
	v_pk_add_f32 v[142:143], v[142:143], v[156:157]
	v_pk_fma_f32 v[158:159], v[164:165], v[140:141], v[144:145] op_sel_hi:[0,1,1] neg_lo:[0,0,1] neg_hi:[0,0,1]
	v_pk_fma_f32 v[160:161], v[164:165], v[142:143], v[146:147] op_sel_hi:[0,1,1] neg_lo:[0,0,1] neg_hi:[0,0,1]
	v_cvt_pk_bf16_f32 v162, v158, v159
	v_cvt_pk_bf16_f32 v163, v160, v161
	global_store_dwordx2 v36, v[162:163], s[96:97] offset:512
	s_waitcnt vmcnt(31)
; #define GAS __attribute__((address_space(1)))
; __device__ __forceinline__ unsigned pk2(float lo, float hi) { f32x2_t v = {lo, hi}; bf16x2_t b = __builtin_convertvector(v, bf16x2_t); return __builtin_bit_cast(unsigned, b); }
; #define U_LD(p) ({ const v2u w_ = *(const v2u*)(p); (f32x4){bflo(w_.x), bfhi(w_.x), bflo(w_.y), bfhi(w_.y)}; })
; __device__ __forceinline__ void p3_pool(Frame& F) {
;     ...
;         for (int i = 0; i < nsteps; ++i) {
;             const int s = s0 - 15 + i;
;             const int so = s - w;
;             f32x4 n0 = (f32x4){0.f, 0.f, 0.f, 0.f}, o0 = n0;
;             if (isP) {
;                 if (s >= 0) n0 = U_LD(U + (mbase + s) * 512 + c0);
;                 if (i >= w && so >= 0) o0 = U_LD(U + (mbase + so) * 512 + c0);
;             } else {
;                 if (s >= 0) n0 = U_LD(U + (mbase + s) * 512 + c0); else n0 = *(const f32x4*)(state_pool + ((size_t)b * 15 + (s + 15)) * 512 + c0);
;                 if (i >= w) { if (so >= 0) o0 = U_LD(U + (mbase + so) * 512 + c0); else o0 = *(const f32x4*)(state_pool + ((size_t)b * 15 + (so + 15)) * 512 + c0); }
;             }
;             S0 += n0 - o0;
;             if (i >= 15) {
;                 const int cnt = isP ? (w < s + 1 ? w : s + 1) : w; const float inv = 1.f / (float)cnt;
;                 const f32x4 d0 = S0 * inv - n0;
;                 v2u wv; wv.x = pk2(d0[0], d0[1]); wv.y = pk2(d0[2], d0[3]);
;                 *(GAS v2u*)(D + (size_t)(c0 >> 8) * ((size_t)MT * 256) + (mbase + s) * 256 + (c0 & 255)) = wv;
	v_lshlrev_b32_e32 v144, 16, v106
	v_and_b32_e32 v145, 0xffff0000, v106
	v_lshlrev_b32_e32 v146, 16, v107
	v_and_b32_e32 v147, 0xffff0000, v107
	v_cndmask_b32_e64 v148, v90, v74, s[94:95]
	v_cndmask_b32_e64 v149, v91, v75, s[94:95]
	v_lshlrev_b32_e32 v150, 16, v148
	v_and_b32_e32 v151, 0xffff0000, v148
	v_lshlrev_b32_e32 v152, 16, v149
	v_and_b32_e32 v153, 0xffff0000, v149
	v_pk_add_f32 v[154:155], v[144:145], v[150:151] neg_lo:[0,1] neg_hi:[0,1]
	v_pk_add_f32 v[156:157], v[146:147], v[152:153] neg_lo:[0,1] neg_hi:[0,1]
	v_pk_add_f32 v[140:141], v[140:141], v[154:155]
	v_pk_add_f32 v[142:143], v[142:143], v[156:157]
	v_pk_fma_f32 v[158:159], v[164:165], v[140:141], v[144:145] op_sel_hi:[0,1,1] neg_lo:[0,0,1] neg_hi:[0,0,1]
	v_pk_fma_f32 v[160:161], v[164:165], v[142:143], v[146:147] op_sel_hi:[0,1,1] neg_lo:[0,0,1] neg_hi:[0,0,1]
	v_cvt_pk_bf16_f32 v162, v158, v159
	v_cvt_pk_bf16_f32 v163, v160, v161
	global_store_dwordx2 v36, v[162:163], s[96:97] offset:1024
	s_waitcnt vmcnt(31)
	v_lshlrev_b32_e32 v144, 16, v108
	v_and_b32_e32 v145, 0xffff0000, v108
	v_lshlrev_b32_e32 v146, 16, v109
	v_and_b32_e32 v147, 0xffff0000, v109
	v_cndmask_b32_e64 v148, v92, v76, s[94:95]
	v_cndmask_b32_e64 v149, v93, v77, s[94:95]
	v_lshlrev_b32_e32 v150, 16, v148
	v_and_b32_e32 v151, 0xffff0000, v148
	v_lshlrev_b32_e32 v152, 16, v149
	v_and_b32_e32 v153, 0xffff0000, v149
	v_pk_add_f32 v[154:155], v[144:145], v[150:151] neg_lo:[0,1] neg_hi:[0,1]
	v_pk_add_f32 v[156:157], v[146:147], v[152:153] neg_lo:[0,1] neg_hi:[0,1]
	v_pk_add_f32 v[140:141], v[140:141], v[154:155]
	v_pk_add_f32 v[142:143], v[142:143], v[156:157]
	v_pk_fma_f32 v[158:159], v[164:165], v[140:141], v[144:145] op_sel_hi:[0,1,1] neg_lo:[0,0,1] neg_hi:[0,0,1]
	v_pk_fma_f32 v[160:161], v[164:165], v[142:143], v[146:147] op_sel_hi:[0,1,1] neg_lo:[0,0,1] neg_hi:[0,0,1]
	v_cvt_pk_bf16_f32 v162, v158, v159
	v_cvt_pk_bf16_f32 v163, v160, v161
	global_store_dwordx2 v36, v[162:163], s[96:97] offset:1536
	s_waitcnt vmcnt(31)
	v_lshlrev_b32_e32 v144, 16, v110
	v_and_b32_e32 v145, 0xffff0000, v110
	v_lshlrev_b32_e32 v146, 16, v111
	v_and_b32_e32 v147, 0xffff0000, v111
	v_cndmask_b32_e64 v148, v94, v78, s[94:95]
	v_cndmask_b32_e64 v149, v95, v79, s[94:95]
	v_lshlrev_b32_e32 v150, 16, v148
	v_and_b32_e32 v151, 0xffff0000, v148
	v_lshlrev_b32_e32 v152, 16, v149
	v_and_b32_e32 v153, 0xffff0000, v149
	v_pk_add_f32 v[154:155], v[144:145], v[150:151] neg_lo:[0,1] neg_hi:[0,1]
	v_pk_add_f32 v[156:157], v[146:147], v[152:153] neg_lo:[0,1] neg_hi:[0,1]
	v_pk_add_f32 v[140:141], v[140:141], v[154:155]
	v_pk_add_f32 v[142:143], v[142:143], v[156:157]
	v_pk_fma_f32 v[158:159], v[164:165], v[140:141], v[144:145] op_sel_hi:[0,1,1] neg_lo:[0,0,1] neg_hi:[0,0,1]
	v_pk_fma_f32 v[160:161], v[164:165], v[142:143], v[146:147] op_sel_hi:[0,1,1] neg_lo:[0,0,1] neg_hi:[0,0,1]
	v_cvt_pk_bf16_f32 v162, v158, v159
	v_cvt_pk_bf16_f32 v163, v160, v161
	global_store_dwordx2 v36, v[162:163], s[96:97] offset:2048
	s_waitcnt vmcnt(31)
	v_lshlrev_b32_e32 v144, 16, v112
	v_and_b32_e32 v145, 0xffff0000, v112
	v_lshlrev_b32_e32 v146, 16, v113
	v_and_b32_e32 v147, 0xffff0000, v113
	v_cndmask_b32_e64 v148, v96, v80, s[94:95]
	v_cndmask_b32_e64 v149, v97, v81, s[94:95]
	v_lshlrev_b32_e32 v150, 16, v148
	v_and_b32_e32 v151, 0xffff0000, v148
	v_lshlrev_b32_e32 v152, 16, v149
	v_and_b32_e32 v153, 0xffff0000, v149
	v_pk_add_f32 v[154:155], v[144:145], v[150:151] neg_lo:[0,1] neg_hi:[0,1]
	v_pk_add_f32 v[156:157], v[146:147], v[152:153] neg_lo:[0,1] neg_hi:[0,1]
	v_pk_add_f32 v[140:141], v[140:141], v[154:155]
	v_pk_add_f32 v[142:143], v[142:143], v[156:157]
	v_pk_fma_f32 v[158:159], v[164:165], v[140:141], v[144:145] op_sel_hi:[0,1,1] neg_lo:[0,0,1] neg_hi:[0,0,1]
	v_pk_fma_f32 v[160:161], v[164:165], v[142:143], v[146:147] op_sel_hi:[0,1,1] neg_lo:[0,0,1] neg_hi:[0,0,1]
	v_cvt_pk_bf16_f32 v162, v158, v159
	v_cvt_pk_bf16_f32 v163, v160, v161
	global_store_dwordx2 v36, v[162:163], s[96:97] offset:2560
	s_waitcnt vmcnt(31)
	v_lshlrev_b32_e32 v144, 16, v114
	v_and_b32_e32 v145, 0xffff0000, v114
	v_lshlrev_b32_e32 v146, 16, v115
	v_and_b32_e32 v147, 0xffff0000, v115
	v_cndmask_b32_e64 v148, v98, v82, s[94:95]
	v_cndmask_b32_e64 v149, v99, v83, s[94:95]
	v_lshlrev_b32_e32 v150, 16, v148
	v_and_b32_e32 v151, 0xffff0000, v148
	v_lshlrev_b32_e32 v152, 16, v149
	v_and_b32_e32 v153, 0xffff0000, v149
	v_pk_add_f32 v[154:155], v[144:145], v[150:151] neg_lo:[0,1] neg_hi:[0,1]
	v_pk_add_f32 v[156:157], v[146:147], v[152:153] neg_lo:[0,1] neg_hi:[0,1]
	v_pk_add_f32 v[140:141], v[140:141], v[154:155]
	v_pk_add_f32 v[142:143], v[142:143], v[156:157]
	v_pk_fma_f32 v[158:159], v[164:165], v[140:141], v[144:145] op_sel_hi:[0,1,1] neg_lo:[0,0,1] neg_hi:[0,0,1]
	v_pk_fma_f32 v[160:161], v[164:165], v[142:143], v[146:147] op_sel_hi:[0,1,1] neg_lo:[0,0,1] neg_hi:[0,0,1]
	v_cvt_pk_bf16_f32 v162, v158, v159
	v_cvt_pk_bf16_f32 v163, v160, v161
	global_store_dwordx2 v36, v[162:163], s[96:97] offset:3072
	s_waitcnt vmcnt(31)
	v_lshlrev_b32_e32 v144, 16, v116
	v_and_b32_e32 v145, 0xffff0000, v116
	v_lshlrev_b32_e32 v146, 16, v117
	v_and_b32_e32 v147, 0xffff0000, v117
	v_cndmask_b32_e64 v148, v100, v84, s[94:95]
	v_cndmask_b32_e64 v149, v101, v85, s[94:95]
	v_lshlrev_b32_e32 v150, 16, v148
	v_and_b32_e32 v151, 0xffff0000, v148
	v_lshlrev_b32_e32 v152, 16, v149
	v_and_b32_e32 v153, 0xffff0000, v149
	v_pk_add_f32 v[154:155], v[144:145], v[150:151] neg_lo:[0,1] neg_hi:[0,1]
	v_pk_add_f32 v[156:157], v[146:147], v[152:153] neg_lo:[0,1] neg_hi:[0,1]
	v_pk_add_f32 v[140:141], v[140:141], v[154:155]
	v_pk_add_f32 v[142:143], v[142:143], v[156:157]
	v_pk_fma_f32 v[158:159], v[164:165], v[140:141], v[144:145] op_sel_hi:[0,1,1] neg_lo:[0,0,1] neg_hi:[0,0,1]
	v_pk_fma_f32 v[160:161], v[164:165], v[142:143], v[146:147] op_sel_hi:[0,1,1] neg_lo:[0,0,1] neg_hi:[0,0,1]
	v_cvt_pk_bf16_f32 v162, v158, v159
	v_cvt_pk_bf16_f32 v163, v160, v161
	global_store_dwordx2 v36, v[162:163], s[96:97] offset:3584
	s_add_u32 s96, s96, 0x1000
	s_addc_u32 s97, s97, 0
	s_waitcnt vmcnt(31)
; #define GAS __attribute__((address_space(1)))
; __device__ __forceinline__ unsigned pk2(float lo, float hi) { f32x2_t v = {lo, hi}; bf16x2_t b = __builtin_convertvector(v, bf16x2_t); return __builtin_bit_cast(unsigned, b); }
; #define U_LD(p) ({ const v2u w_ = *(const v2u*)(p); (f32x4){bflo(w_.x), bfhi(w_.x), bflo(w_.y), bfhi(w_.y)}; })
; __device__ __forceinline__ void p3_pool(Frame& F) {
;     ...
;         for (int i = 0; i < nsteps; ++i) {
;             const int s = s0 - 15 + i;
;             const int so = s - w;
;             f32x4 n0 = (f32x4){0.f, 0.f, 0.f, 0.f}, o0 = n0;
;             if (isP) {
;                 if (s >= 0) n0 = U_LD(U + (mbase + s) * 512 + c0);
;                 if (i >= w && so >= 0) o0 = U_LD(U + (mbase + so) * 512 + c0);
;             } else {
;                 if (s >= 0) n0 = U_LD(U + (mbase + s) * 512 + c0); else n0 = *(const f32x4*)(state_pool + ((size_t)b * 15 + (s + 15)) * 512 + c0);
;                 if (i >= w) { if (so >= 0) o0 = U_LD(U + (mbase + so) * 512 + c0); else o0 = *(const f32x4*)(state_pool + ((size_t)b * 15 + (so + 15)) * 512 + c0); }
;             }
;             S0 += n0 - o0;
;             if (i >= 15) {
;                 const int cnt = isP ? (w < s + 1 ? w : s + 1) : w; const float inv = 1.f / (float)cnt;
;                 const f32x4 d0 = S0 * inv - n0;
;                 v2u wv; wv.x = pk2(d0[0], d0[1]); wv.y = pk2(d0[2], d0[3]);
;                 *(GAS v2u*)(D + (size_t)(c0 >> 8) * ((size_t)MT * 256) + (mbase + s) * 256 + (c0 & 255)) = wv;
	v_lshlrev_b32_e32 v144, 16, v118
	v_and_b32_e32 v145, 0xffff0000, v118
	v_lshlrev_b32_e32 v146, 16, v119
	v_and_b32_e32 v147, 0xffff0000, v119
	v_cndmask_b32_e64 v148, v102, v86, s[94:95]
	v_cndmask_b32_e64 v149, v103, v87, s[94:95]
	v_lshlrev_b32_e32 v150, 16, v148
	v_and_b32_e32 v151, 0xffff0000, v148
	v_lshlrev_b32_e32 v152, 16, v149
	v_and_b32_e32 v153, 0xffff0000, v149
	v_pk_add_f32 v[154:155], v[144:145], v[150:151] neg_lo:[0,1] neg_hi:[0,1]
	v_pk_add_f32 v[156:157], v[146:147], v[152:153] neg_lo:[0,1] neg_hi:[0,1]
	v_pk_add_f32 v[140:141], v[140:141], v[154:155]
	v_pk_add_f32 v[142:143], v[142:143], v[156:157]
	v_pk_fma_f32 v[158:159], v[164:165], v[140:141], v[144:145] op_sel_hi:[0,1,1] neg_lo:[0,0,1] neg_hi:[0,0,1]
	v_pk_fma_f32 v[160:161], v[164:165], v[142:143], v[146:147] op_sel_hi:[0,1,1] neg_lo:[0,0,1] neg_hi:[0,0,1]
	v_cvt_pk_bf16_f32 v162, v158, v159
	v_cvt_pk_bf16_f32 v163, v160, v161
	global_store_dwordx2 v36, v[162:163], s[96:97]
	s_waitcnt vmcnt(31)
	v_lshlrev_b32_e32 v144, 16, v120
	v_and_b32_e32 v145, 0xffff0000, v120
	v_lshlrev_b32_e32 v146, 16, v121
	v_and_b32_e32 v147, 0xffff0000, v121
	v_cndmask_b32_e64 v148, v104, v88, s[94:95]
	v_cndmask_b32_e64 v149, v105, v89, s[94:95]
	v_lshlrev_b32_e32 v150, 16, v148
	v_and_b32_e32 v151, 0xffff0000, v148
	v_lshlrev_b32_e32 v152, 16, v149
	v_and_b32_e32 v153, 0xffff0000, v149
	v_pk_add_f32 v[154:155], v[144:145], v[150:151] neg_lo:[0,1] neg_hi:[0,1]
	v_pk_add_f32 v[156:157], v[146:147], v[152:153] neg_lo:[0,1] neg_hi:[0,1]
	v_pk_add_f32 v[140:141], v[140:141], v[154:155]
	v_pk_add_f32 v[142:143], v[142:143], v[156:157]
	v_pk_fma_f32 v[158:159], v[164:165], v[140:141], v[144:145] op_sel_hi:[0,1,1] neg_lo:[0,0,1] neg_hi:[0,0,1]
	v_pk_fma_f32 v[160:161], v[164:165], v[142:143], v[146:147] op_sel_hi:[0,1,1] neg_lo:[0,0,1] neg_hi:[0,0,1]
	v_cvt_pk_bf16_f32 v162, v158, v159
	v_cvt_pk_bf16_f32 v163, v160, v161
	global_store_dwordx2 v36, v[162:163], s[96:97] offset:512
	s_waitcnt vmcnt(31)
	v_lshlrev_b32_e32 v144, 16, v122
	v_and_b32_e32 v145, 0xffff0000, v122
	v_lshlrev_b32_e32 v146, 16, v123
	v_and_b32_e32 v147, 0xffff0000, v123
	v_cndmask_b32_e64 v148, v106, v90, s[94:95]
	v_cndmask_b32_e64 v149, v107, v91, s[94:95]
	v_lshlrev_b32_e32 v150, 16, v148
	v_and_b32_e32 v151, 0xffff0000, v148
	v_lshlrev_b32_e32 v152, 16, v149
	v_and_b32_e32 v153, 0xffff0000, v149
	v_pk_add_f32 v[154:155], v[144:145], v[150:151] neg_lo:[0,1] neg_hi:[0,1]
	v_pk_add_f32 v[156:157], v[146:147], v[152:153] neg_lo:[0,1] neg_hi:[0,1]
	v_pk_add_f32 v[140:141], v[140:141], v[154:155]
	v_pk_add_f32 v[142:143], v[142:143], v[156:157]
	v_pk_fma_f32 v[158:159], v[164:165], v[140:141], v[144:145] op_sel_hi:[0,1,1] neg_lo:[0,0,1] neg_hi:[0,0,1]
	v_pk_fma_f32 v[160:161], v[164:165], v[142:143], v[146:147] op_sel_hi:[0,1,1] neg_lo:[0,0,1] neg_hi:[0,0,1]
	v_cvt_pk_bf16_f32 v162, v158, v159
	v_cvt_pk_bf16_f32 v163, v160, v161
	global_store_dwordx2 v36, v[162:163], s[96:97] offset:1024
	s_waitcnt vmcnt(31)
	v_lshlrev_b32_e32 v144, 16, v124
	v_and_b32_e32 v145, 0xffff0000, v124
	v_lshlrev_b32_e32 v146, 16, v125
	v_and_b32_e32 v147, 0xffff0000, v125
	v_cndmask_b32_e64 v148, v108, v92, s[94:95]
	v_cndmask_b32_e64 v149, v109, v93, s[94:95]
	v_lshlrev_b32_e32 v150, 16, v148
	v_and_b32_e32 v151, 0xffff0000, v148
	v_lshlrev_b32_e32 v152, 16, v149
	v_and_b32_e32 v153, 0xffff0000, v149
	v_pk_add_f32 v[154:155], v[144:145], v[150:151] neg_lo:[0,1] neg_hi:[0,1]
	v_pk_add_f32 v[156:157], v[146:147], v[152:153] neg_lo:[0,1] neg_hi:[0,1]
	v_pk_add_f32 v[140:141], v[140:141], v[154:155]
	v_pk_add_f32 v[142:143], v[142:143], v[156:157]
	v_pk_fma_f32 v[158:159], v[164:165], v[140:141], v[144:145] op_sel_hi:[0,1,1] neg_lo:[0,0,1] neg_hi:[0,0,1]
	v_pk_fma_f32 v[160:161], v[164:165], v[142:143], v[146:147] op_sel_hi:[0,1,1] neg_lo:[0,0,1] neg_hi:[0,0,1]
	v_cvt_pk_bf16_f32 v162, v158, v159
	v_cvt_pk_bf16_f32 v163, v160, v161
	global_store_dwordx2 v36, v[162:163], s[96:97] offset:1536
	s_waitcnt vmcnt(31)
	v_lshlrev_b32_e32 v144, 16, v126
	v_and_b32_e32 v145, 0xffff0000, v126
	v_lshlrev_b32_e32 v146, 16, v127
	v_and_b32_e32 v147, 0xffff0000, v127
	v_cndmask_b32_e64 v148, v110, v94, s[94:95]
	v_cndmask_b32_e64 v149, v111, v95, s[94:95]
	v_lshlrev_b32_e32 v150, 16, v148
	v_and_b32_e32 v151, 0xffff0000, v148
	v_lshlrev_b32_e32 v152, 16, v149
	v_and_b32_e32 v153, 0xffff0000, v149
	v_pk_add_f32 v[154:155], v[144:145], v[150:151] neg_lo:[0,1] neg_hi:[0,1]
	v_pk_add_f32 v[156:157], v[146:147], v[152:153] neg_lo:[0,1] neg_hi:[0,1]
	v_pk_add_f32 v[140:141], v[140:141], v[154:155]
	v_pk_add_f32 v[142:143], v[142:143], v[156:157]
	v_pk_fma_f32 v[158:159], v[164:165], v[140:141], v[144:145] op_sel_hi:[0,1,1] neg_lo:[0,0,1] neg_hi:[0,0,1]
	v_pk_fma_f32 v[160:161], v[164:165], v[142:143], v[146:147] op_sel_hi:[0,1,1] neg_lo:[0,0,1] neg_hi:[0,0,1]
	v_cvt_pk_bf16_f32 v162, v158, v159
	v_cvt_pk_bf16_f32 v163, v160, v161
	global_store_dwordx2 v36, v[162:163], s[96:97] offset:2048
	s_waitcnt vmcnt(31)
	v_lshlrev_b32_e32 v144, 16, v128
	v_and_b32_e32 v145, 0xffff0000, v128
	v_lshlrev_b32_e32 v146, 16, v129
	v_and_b32_e32 v147, 0xffff0000, v129
	v_cndmask_b32_e64 v148, v112, v96, s[94:95]
	v_cndmask_b32_e64 v149, v113, v97, s[94:95]
	v_lshlrev_b32_e32 v150, 16, v148
	v_and_b32_e32 v151, 0xffff0000, v148
	v_lshlrev_b32_e32 v152, 16, v149
	v_and_b32_e32 v153, 0xffff0000, v149
	v_pk_add_f32 v[154:155], v[144:145], v[150:151] neg_lo:[0,1] neg_hi:[0,1]
	v_pk_add_f32 v[156:157], v[146:147], v[152:153] neg_lo:[0,1] neg_hi:[0,1]
	v_pk_add_f32 v[140:141], v[140:141], v[154:155]
	v_pk_add_f32 v[142:143], v[142:143], v[156:157]
	v_pk_fma_f32 v[158:159], v[164:165], v[140:141], v[144:145] op_sel_hi:[0,1,1] neg_lo:[0,0,1] neg_hi:[0,0,1]
	v_pk_fma_f32 v[160:161], v[164:165], v[142:143], v[146:147] op_sel_hi:[0,1,1] neg_lo:[0,0,1] neg_hi:[0,0,1]
	v_cvt_pk_bf16_f32 v162, v158, v159
	v_cvt_pk_bf16_f32 v163, v160, v161
	global_store_dwordx2 v36, v[162:163], s[96:97] offset:2560
	s_waitcnt vmcnt(31)
; #define GAS __attribute__((address_space(1)))
; __device__ __forceinline__ unsigned pk2(float lo, float hi) { f32x2_t v = {lo, hi}; bf16x2_t b = __builtin_convertvector(v, bf16x2_t); return __builtin_bit_cast(unsigned, b); }
; #define U_LD(p) ({ const v2u w_ = *(const v2u*)(p); (f32x4){bflo(w_.x), bfhi(w_.x), bflo(w_.y), bfhi(w_.y)}; })
; __device__ __forceinline__ void p3_pool(Frame& F) {
;     ...
;         const int tk = tk2 >> 1, c0 = (tk2 & 1) * 256 + lane * 4, w = 2 << (c0 >> 7);
;         const bool isP = tk < NPR / 32;
;         const int b = isP ? (tk >> 6) : (tk - NPR / 32), s0 = isP ? ((tk & 63) << 5) : 0, nsteps = isP ? 47 : 23;
;         const size_t mbase = isP ? (size_t)b * SEQ : (size_t)NPR + (size_t)b * 8;
;     ...
;         for (int i = 0; i < nsteps; ++i) {
;             const int s = s0 - 15 + i;
;             const int so = s - w;
;             f32x4 n0 = (f32x4){0.f, 0.f, 0.f, 0.f}, o0 = n0;
;             if (isP) {
;                 if (s >= 0) n0 = U_LD(U + (mbase + s) * 512 + c0);
;                 if (i >= w && so >= 0) o0 = U_LD(U + (mbase + so) * 512 + c0);
;             } else {
;                 if (s >= 0) n0 = U_LD(U + (mbase + s) * 512 + c0); else n0 = *(const f32x4*)(state_pool + ((size_t)b * 15 + (s + 15)) * 512 + c0);
;                 if (i >= w) { if (so >= 0) o0 = U_LD(U + (mbase + so) * 512 + c0); else o0 = *(const f32x4*)(state_pool + ((size_t)b * 15 + (so + 15)) * 512 + c0); }
;             }
;             S0 += n0 - o0;
;             if (i >= 15) {
;                 const int cnt = isP ? (w < s + 1 ? w : s + 1) : w; const float inv = 1.f / (float)cnt;
;                 const f32x4 d0 = S0 * inv - n0;
;                 v2u wv; wv.x = pk2(d0[0], d0[1]); wv.y = pk2(d0[2], d0[3]);
;                 *(GAS v2u*)(D + (size_t)(c0 >> 8) * ((size_t)MT * 256) + (mbase + s) * 256 + (c0 & 255)) = wv;
	v_lshlrev_b32_e32 v144, 16, v130
	v_and_b32_e32 v145, 0xffff0000, v130
	v_lshlrev_b32_e32 v146, 16, v131
	v_and_b32_e32 v147, 0xffff0000, v131
	v_cndmask_b32_e64 v148, v114, v98, s[94:95]
	v_cndmask_b32_e64 v149, v115, v99, s[94:95]
	v_lshlrev_b32_e32 v150, 16, v148
	v_and_b32_e32 v151, 0xffff0000, v148
	v_lshlrev_b32_e32 v152, 16, v149
	v_and_b32_e32 v153, 0xffff0000, v149
	v_pk_add_f32 v[154:155], v[144:145], v[150:151] neg_lo:[0,1] neg_hi:[0,1]
	v_pk_add_f32 v[156:157], v[146:147], v[152:153] neg_lo:[0,1] neg_hi:[0,1]
	v_pk_add_f32 v[140:141], v[140:141], v[154:155]
	v_pk_add_f32 v[142:143], v[142:143], v[156:157]
	v_pk_fma_f32 v[158:159], v[164:165], v[140:141], v[144:145] op_sel_hi:[0,1,1] neg_lo:[0,0,1] neg_hi:[0,0,1]
	v_pk_fma_f32 v[160:161], v[164:165], v[142:143], v[146:147] op_sel_hi:[0,1,1] neg_lo:[0,0,1] neg_hi:[0,0,1]
	v_cvt_pk_bf16_f32 v162, v158, v159
	v_cvt_pk_bf16_f32 v163, v160, v161
	global_store_dwordx2 v36, v[162:163], s[96:97] offset:3072
	s_waitcnt vmcnt(31)
	v_lshlrev_b32_e32 v144, 16, v132
	v_and_b32_e32 v145, 0xffff0000, v132
	v_lshlrev_b32_e32 v146, 16, v133
	v_and_b32_e32 v147, 0xffff0000, v133
	v_cndmask_b32_e64 v148, v116, v100, s[94:95]
	v_cndmask_b32_e64 v149, v117, v101, s[94:95]
	v_lshlrev_b32_e32 v150, 16, v148
	v_and_b32_e32 v151, 0xffff0000, v148
	v_lshlrev_b32_e32 v152, 16, v149
	v_and_b32_e32 v153, 0xffff0000, v149
	v_pk_add_f32 v[154:155], v[144:145], v[150:151] neg_lo:[0,1] neg_hi:[0,1]
	v_pk_add_f32 v[156:157], v[146:147], v[152:153] neg_lo:[0,1] neg_hi:[0,1]
	v_pk_add_f32 v[140:141], v[140:141], v[154:155]
	v_pk_add_f32 v[142:143], v[142:143], v[156:157]
	v_pk_fma_f32 v[158:159], v[164:165], v[140:141], v[144:145] op_sel_hi:[0,1,1] neg_lo:[0,0,1] neg_hi:[0,0,1]
	v_pk_fma_f32 v[160:161], v[164:165], v[142:143], v[146:147] op_sel_hi:[0,1,1] neg_lo:[0,0,1] neg_hi:[0,0,1]
	v_cvt_pk_bf16_f32 v162, v158, v159
	v_cvt_pk_bf16_f32 v163, v160, v161
	global_store_dwordx2 v36, v[162:163], s[96:97] offset:3584
	s_branch .LBB0_515
.Lp3f_first:
	s_cmp_eq_u32 s82, 0
	s_cbranch_scc0 .Lp3f_f1
	v_mov_b32_e32 v140, 0
	v_mov_b32_e32 v141, 0
	v_mov_b32_e32 v142, 0
	v_mov_b32_e32 v143, 0
	v_mov_b32_e32 v166, 0
	v_mov_b32_e32 v167, 0
	s_mov_b64 s[96:97], s[90:91]
	s_waitcnt vmcnt(31)
	v_lshlrev_b32_e32 v144, 16, v70
	v_and_b32_e32 v145, 0xffff0000, v70
	v_lshlrev_b32_e32 v146, 16, v71
	v_and_b32_e32 v147, 0xffff0000, v71
	v_pk_add_f32 v[140:141], v[140:141], v[144:145]
	v_pk_add_f32 v[142:143], v[142:143], v[146:147]
	v_mov_b32_e32 v164, 0x3f800000
	v_pk_fma_f32 v[158:159], v[164:165], v[140:141], v[144:145] op_sel_hi:[0,1,1] neg_lo:[0,0,1] neg_hi:[0,0,1]
	v_pk_fma_f32 v[160:161], v[164:165], v[142:143], v[146:147] op_sel_hi:[0,1,1] neg_lo:[0,0,1] neg_hi:[0,0,1]
	v_cvt_pk_bf16_f32 v162, v158, v159
	v_cvt_pk_bf16_f32 v163, v160, v161
	global_store_dwordx2 v36, v[162:163], s[96:97]
	s_waitcnt vmcnt(31)
	v_lshlrev_b32_e32 v144, 16, v72
	v_and_b32_e32 v145, 0xffff0000, v72
	v_lshlrev_b32_e32 v146, 16, v73
	v_and_b32_e32 v147, 0xffff0000, v73
	v_pk_add_f32 v[140:141], v[140:141], v[144:145]
	v_pk_add_f32 v[142:143], v[142:143], v[146:147]
	v_mov_b32_e32 v164, 0x3f000000
	v_pk_fma_f32 v[158:159], v[164:165], v[140:141], v[144:145] op_sel_hi:[0,1,1] neg_lo:[0,0,1] neg_hi:[0,0,1]
	v_pk_fma_f32 v[160:161], v[164:165], v[142:143], v[146:147] op_sel_hi:[0,1,1] neg_lo:[0,0,1] neg_hi:[0,0,1]
	v_cvt_pk_bf16_f32 v162, v158, v159
	v_cvt_pk_bf16_f32 v163, v160, v161
	global_store_dwordx2 v36, v[162:163], s[96:97] offset:512
	s_waitcnt vmcnt(31)
	v_lshlrev_b32_e32 v144, 16, v74
	v_and_b32_e32 v145, 0xffff0000, v74
	v_lshlrev_b32_e32 v146, 16, v75
	v_and_b32_e32 v147, 0xffff0000, v75
	v_cndmask_b32_e64 v148, v70, v166, s[94:95]
	v_cndmask_b32_e64 v149, v71, v167, s[94:95]
	v_lshlrev_b32_e32 v150, 16, v148
	v_and_b32_e32 v151, 0xffff0000, v148
	v_lshlrev_b32_e32 v152, 16, v149
	v_and_b32_e32 v153, 0xffff0000, v149
	v_pk_add_f32 v[154:155], v[144:145], v[150:151] neg_lo:[0,1] neg_hi:[0,1]
	v_pk_add_f32 v[156:157], v[146:147], v[152:153] neg_lo:[0,1] neg_hi:[0,1]
	v_pk_add_f32 v[140:141], v[140:141], v[154:155]
	v_pk_add_f32 v[142:143], v[142:143], v[156:157]
	v_mov_b32_e32 v168, 0x3f000000
	v_mov_b32_e32 v169, 0x3eaaaaab
	v_cndmask_b32_e64 v164, v168, v169, s[94:95]
	v_pk_fma_f32 v[158:159], v[164:165], v[140:141], v[144:145] op_sel_hi:[0,1,1] neg_lo:[0,0,1] neg_hi:[0,0,1]
	v_pk_fma_f32 v[160:161], v[164:165], v[142:143], v[146:147] op_sel_hi:[0,1,1] neg_lo:[0,0,1] neg_hi:[0,0,1]
	v_cvt_pk_bf16_f32 v162, v158, v159
	v_cvt_pk_bf16_f32 v163, v160, v161
	global_store_dwordx2 v36, v[162:163], s[96:97] offset:1024
	s_waitcnt vmcnt(31)
	v_lshlrev_b32_e32 v144, 16, v76
	v_and_b32_e32 v145, 0xffff0000, v76
	v_lshlrev_b32_e32 v146, 16, v77
	v_and_b32_e32 v147, 0xffff0000, v77
	v_cndmask_b32_e64 v148, v72, v166, s[94:95]
	v_cndmask_b32_e64 v149, v73, v167, s[94:95]
	v_lshlrev_b32_e32 v150, 16, v148
	v_and_b32_e32 v151, 0xffff0000, v148
	v_lshlrev_b32_e32 v152, 16, v149
	v_and_b32_e32 v153, 0xffff0000, v149
	v_pk_add_f32 v[154:155], v[144:145], v[150:151] neg_lo:[0,1] neg_hi:[0,1]
	v_pk_add_f32 v[156:157], v[146:147], v[152:153] neg_lo:[0,1] neg_hi:[0,1]
	v_pk_add_f32 v[140:141], v[140:141], v[154:155]
	v_pk_add_f32 v[142:143], v[142:143], v[156:157]
	v_mov_b32_e32 v168, 0x3f000000
	v_mov_b32_e32 v169, 0x3e800000
	v_cndmask_b32_e64 v164, v168, v169, s[94:95]
	v_pk_fma_f32 v[158:159], v[164:165], v[140:141], v[144:145] op_sel_hi:[0,1,1] neg_lo:[0,0,1] neg_hi:[0,0,1]
	v_pk_fma_f32 v[160:161], v[164:165], v[142:143], v[146:147] op_sel_hi:[0,1,1] neg_lo:[0,0,1] neg_hi:[0,0,1]
	v_cvt_pk_bf16_f32 v162, v158, v159
	v_cvt_pk_bf16_f32 v163, v160, v161
	global_store_dwordx2 v36, v[162:163], s[96:97] offset:1536
	s_waitcnt vmcnt(31)
; #define GAS __attribute__((address_space(1)))
; __device__ __forceinline__ unsigned pk2(float lo, float hi) { f32x2_t v = {lo, hi}; bf16x2_t b = __builtin_convertvector(v, bf16x2_t); return __builtin_bit_cast(unsigned, b); }
; #define U_LD(p) ({ const v2u w_ = *(const v2u*)(p); (f32x4){bflo(w_.x), bfhi(w_.x), bflo(w_.y), bfhi(w_.y)}; })
; __device__ __forceinline__ void p3_pool(Frame& F) {
;     ...
;         for (int i = 0; i < nsteps; ++i) {
;             const int s = s0 - 15 + i;
;             const int so = s - w;
;             f32x4 n0 = (f32x4){0.f, 0.f, 0.f, 0.f}, o0 = n0;
;             if (isP) {
;                 if (s >= 0) n0 = U_LD(U + (mbase + s) * 512 + c0);
;                 if (i >= w && so >= 0) o0 = U_LD(U + (mbase + so) * 512 + c0);
;             } else {
;                 if (s >= 0) n0 = U_LD(U + (mbase + s) * 512 + c0); else n0 = *(const f32x4*)(state_pool + ((size_t)b * 15 + (s + 15)) * 512 + c0);
;                 if (i >= w) { if (so >= 0) o0 = U_LD(U + (mbase + so) * 512 + c0); else o0 = *(const f32x4*)(state_pool + ((size_t)b * 15 + (so + 15)) * 512 + c0); }
;             }
;             S0 += n0 - o0;
;             if (i >= 15) {
;                 const int cnt = isP ? (w < s + 1 ? w : s + 1) : w; const float inv = 1.f / (float)cnt;
;                 const f32x4 d0 = S0 * inv - n0;
;                 v2u wv; wv.x = pk2(d0[0], d0[1]); wv.y = pk2(d0[2], d0[3]);
;                 *(GAS v2u*)(D + (size_t)(c0 >> 8) * ((size_t)MT * 256) + (mbase + s) * 256 + (c0 & 255)) = wv;
	v_lshlrev_b32_e32 v144, 16, v78
	v_and_b32_e32 v145, 0xffff0000, v78
	v_lshlrev_b32_e32 v146, 16, v79
	v_and_b32_e32 v147, 0xffff0000, v79
	v_cndmask_b32_e64 v148, v74, v70, s[94:95]
	v_cndmask_b32_e64 v149, v75, v71, s[94:95]
	v_lshlrev_b32_e32 v150, 16, v148
	v_and_b32_e32 v151, 0xffff0000, v148
	v_lshlrev_b32_e32 v152, 16, v149
	v_and_b32_e32 v153, 0xffff0000, v149
	v_pk_add_f32 v[154:155], v[144:145], v[150:151] neg_lo:[0,1] neg_hi:[0,1]
	v_pk_add_f32 v[156:157], v[146:147], v[152:153] neg_lo:[0,1] neg_hi:[0,1]
	v_pk_add_f32 v[140:141], v[140:141], v[154:155]
	v_pk_add_f32 v[142:143], v[142:143], v[156:157]
	v_mov_b32_e32 v168, 0x3f000000
	v_mov_b32_e32 v169, 0x3e800000
	v_cndmask_b32_e64 v164, v168, v169, s[94:95]
	v_pk_fma_f32 v[158:159], v[164:165], v[140:141], v[144:145] op_sel_hi:[0,1,1] neg_lo:[0,0,1] neg_hi:[0,0,1]
	v_pk_fma_f32 v[160:161], v[164:165], v[142:143], v[146:147] op_sel_hi:[0,1,1] neg_lo:[0,0,1] neg_hi:[0,0,1]
	v_cvt_pk_bf16_f32 v162, v158, v159
	v_cvt_pk_bf16_f32 v163, v160, v161
	global_store_dwordx2 v36, v[162:163], s[96:97] offset:2048
	s_waitcnt vmcnt(31)
	v_lshlrev_b32_e32 v144, 16, v80
	v_and_b32_e32 v145, 0xffff0000, v80
	v_lshlrev_b32_e32 v146, 16, v81
	v_and_b32_e32 v147, 0xffff0000, v81
	v_cndmask_b32_e64 v148, v76, v72, s[94:95]
	v_cndmask_b32_e64 v149, v77, v73, s[94:95]
	v_lshlrev_b32_e32 v150, 16, v148
	v_and_b32_e32 v151, 0xffff0000, v148
	v_lshlrev_b32_e32 v152, 16, v149
	v_and_b32_e32 v153, 0xffff0000, v149
	v_pk_add_f32 v[154:155], v[144:145], v[150:151] neg_lo:[0,1] neg_hi:[0,1]
	v_pk_add_f32 v[156:157], v[146:147], v[152:153] neg_lo:[0,1] neg_hi:[0,1]
	v_pk_add_f32 v[140:141], v[140:141], v[154:155]
	v_pk_add_f32 v[142:143], v[142:143], v[156:157]
	v_mov_b32_e32 v168, 0x3f000000
	v_mov_b32_e32 v169, 0x3e800000
	v_cndmask_b32_e64 v164, v168, v169, s[94:95]
	v_pk_fma_f32 v[158:159], v[164:165], v[140:141], v[144:145] op_sel_hi:[0,1,1] neg_lo:[0,0,1] neg_hi:[0,0,1]
	v_pk_fma_f32 v[160:161], v[164:165], v[142:143], v[146:147] op_sel_hi:[0,1,1] neg_lo:[0,0,1] neg_hi:[0,0,1]
	v_cvt_pk_bf16_f32 v162, v158, v159
	v_cvt_pk_bf16_f32 v163, v160, v161
	global_store_dwordx2 v36, v[162:163], s[96:97] offset:2560
	s_waitcnt vmcnt(31)
	v_lshlrev_b32_e32 v144, 16, v82
	v_and_b32_e32 v145, 0xffff0000, v82
	v_lshlrev_b32_e32 v146, 16, v83
	v_and_b32_e32 v147, 0xffff0000, v83
	v_cndmask_b32_e64 v148, v78, v74, s[94:95]
	v_cndmask_b32_e64 v149, v79, v75, s[94:95]
	v_lshlrev_b32_e32 v150, 16, v148
	v_and_b32_e32 v151, 0xffff0000, v148
	v_lshlrev_b32_e32 v152, 16, v149
	v_and_b32_e32 v153, 0xffff0000, v149
	v_pk_add_f32 v[154:155], v[144:145], v[150:151] neg_lo:[0,1] neg_hi:[0,1]
	v_pk_add_f32 v[156:157], v[146:147], v[152:153] neg_lo:[0,1] neg_hi:[0,1]
	v_pk_add_f32 v[140:141], v[140:141], v[154:155]
	v_pk_add_f32 v[142:143], v[142:143], v[156:157]
	v_mov_b32_e32 v168, 0x3f000000
	v_mov_b32_e32 v169, 0x3e800000
	v_cndmask_b32_e64 v164, v168, v169, s[94:95]
	v_pk_fma_f32 v[158:159], v[164:165], v[140:141], v[144:145] op_sel_hi:[0,1,1] neg_lo:[0,0,1] neg_hi:[0,0,1]
	v_pk_fma_f32 v[160:161], v[164:165], v[142:143], v[146:147] op_sel_hi:[0,1,1] neg_lo:[0,0,1] neg_hi:[0,0,1]
	v_cvt_pk_bf16_f32 v162, v158, v159
	v_cvt_pk_bf16_f32 v163, v160, v161
	global_store_dwordx2 v36, v[162:163], s[96:97] offset:3072
	s_waitcnt vmcnt(31)
	v_lshlrev_b32_e32 v144, 16, v84
	v_and_b32_e32 v145, 0xffff0000, v84
	v_lshlrev_b32_e32 v146, 16, v85
	v_and_b32_e32 v147, 0xffff0000, v85
	v_cndmask_b32_e64 v148, v80, v76, s[94:95]
	v_cndmask_b32_e64 v149, v81, v77, s[94:95]
	v_lshlrev_b32_e32 v150, 16, v148
	v_and_b32_e32 v151, 0xffff0000, v148
	v_lshlrev_b32_e32 v152, 16, v149
	v_and_b32_e32 v153, 0xffff0000, v149
	v_pk_add_f32 v[154:155], v[144:145], v[150:151] neg_lo:[0,1] neg_hi:[0,1]
	v_pk_add_f32 v[156:157], v[146:147], v[152:153] neg_lo:[0,1] neg_hi:[0,1]
	v_pk_add_f32 v[140:141], v[140:141], v[154:155]
	v_pk_add_f32 v[142:143], v[142:143], v[156:157]
	v_mov_b32_e32 v168, 0x3f000000
	v_mov_b32_e32 v169, 0x3e800000
	v_cndmask_b32_e64 v164, v168, v169, s[94:95]
	v_pk_fma_f32 v[158:159], v[164:165], v[140:141], v[144:145] op_sel_hi:[0,1,1] neg_lo:[0,0,1] neg_hi:[0,0,1]
	v_pk_fma_f32 v[160:161], v[164:165], v[142:143], v[146:147] op_sel_hi:[0,1,1] neg_lo:[0,0,1] neg_hi:[0,0,1]
	v_cvt_pk_bf16_f32 v162, v158, v159
	v_cvt_pk_bf16_f32 v163, v160, v161
	global_store_dwordx2 v36, v[162:163], s[96:97] offset:3584
	s_add_u32 s96, s96, 0x1000
	s_addc_u32 s97, s97, 0
	s_waitcnt vmcnt(31)
	v_lshlrev_b32_e32 v144, 16, v86
	v_and_b32_e32 v145, 0xffff0000, v86
	v_lshlrev_b32_e32 v146, 16, v87
	v_and_b32_e32 v147, 0xffff0000, v87
	v_cndmask_b32_e64 v148, v82, v78, s[94:95]
	v_cndmask_b32_e64 v149, v83, v79, s[94:95]
	v_lshlrev_b32_e32 v150, 16, v148
	v_and_b32_e32 v151, 0xffff0000, v148
	v_lshlrev_b32_e32 v152, 16, v149
	v_and_b32_e32 v153, 0xffff0000, v149
	v_pk_add_f32 v[154:155], v[144:145], v[150:151] neg_lo:[0,1] neg_hi:[0,1]
	v_pk_add_f32 v[156:157], v[146:147], v[152:153] neg_lo:[0,1] neg_hi:[0,1]
	v_pk_add_f32 v[140:141], v[140:141], v[154:155]
	v_pk_add_f32 v[142:143], v[142:143], v[156:157]
	v_mov_b32_e32 v168, 0x3f000000
	v_mov_b32_e32 v169, 0x3e800000
	v_cndmask_b32_e64 v164, v168, v169, s[94:95]
	v_pk_fma_f32 v[158:159], v[164:165], v[140:141], v[144:145] op_sel_hi:[0,1,1] neg_lo:[0,0,1] neg_hi:[0,0,1]
	v_pk_fma_f32 v[160:161], v[164:165], v[142:143], v[146:147] op_sel_hi:[0,1,1] neg_lo:[0,0,1] neg_hi:[0,0,1]
	v_cvt_pk_bf16_f32 v162, v158, v159
	v_cvt_pk_bf16_f32 v163, v160, v161
	global_store_dwordx2 v36, v[162:163], s[96:97]
	s_waitcnt vmcnt(31)
; #define GAS __attribute__((address_space(1)))
; __device__ __forceinline__ unsigned pk2(float lo, float hi) { f32x2_t v = {lo, hi}; bf16x2_t b = __builtin_convertvector(v, bf16x2_t); return __builtin_bit_cast(unsigned, b); }
; #define U_LD(p) ({ const v2u w_ = *(const v2u*)(p); (f32x4){bflo(w_.x), bfhi(w_.x), bflo(w_.y), bfhi(w_.y)}; })
; __device__ __forceinline__ void p3_pool(Frame& F) {
;     ...
;         for (int i = 0; i < nsteps; ++i) {
;             const int s = s0 - 15 + i;
;             const int so = s - w;
;             f32x4 n0 = (f32x4){0.f, 0.f, 0.f, 0.f}, o0 = n0;
;             if (isP) {
;                 if (s >= 0) n0 = U_LD(U + (mbase + s) * 512 + c0);
;                 if (i >= w && so >= 0) o0 = U_LD(U + (mbase + so) * 512 + c0);
;             } else {
;                 if (s >= 0) n0 = U_LD(U + (mbase + s) * 512 + c0); else n0 = *(const f32x4*)(state_pool + ((size_t)b * 15 + (s + 15)) * 512 + c0);
;                 if (i >= w) { if (so >= 0) o0 = U_LD(U + (mbase + so) * 512 + c0); else o0 = *(const f32x4*)(state_pool + ((size_t)b * 15 + (so + 15)) * 512 + c0); }
;             }
;             S0 += n0 - o0;
;             if (i >= 15) {
;                 const int cnt = isP ? (w < s + 1 ? w : s + 1) : w; const float inv = 1.f / (float)cnt;
;                 const f32x4 d0 = S0 * inv - n0;
;                 v2u wv; wv.x = pk2(d0[0], d0[1]); wv.y = pk2(d0[2], d0[3]);
;                 *(GAS v2u*)(D + (size_t)(c0 >> 8) * ((size_t)MT * 256) + (mbase + s) * 256 + (c0 & 255)) = wv;
	v_lshlrev_b32_e32 v144, 16, v88
	v_and_b32_e32 v145, 0xffff0000, v88
	v_lshlrev_b32_e32 v146, 16, v89
	v_and_b32_e32 v147, 0xffff0000, v89
	v_cndmask_b32_e64 v148, v84, v80, s[94:95]
	v_cndmask_b32_e64 v149, v85, v81, s[94:95]
	v_lshlrev_b32_e32 v150, 16, v148
	v_and_b32_e32 v151, 0xffff0000, v148
	v_lshlrev_b32_e32 v152, 16, v149
	v_and_b32_e32 v153, 0xffff0000, v149
	v_pk_add_f32 v[154:155], v[144:145], v[150:151] neg_lo:[0,1] neg_hi:[0,1]
	v_pk_add_f32 v[156:157], v[146:147], v[152:153] neg_lo:[0,1] neg_hi:[0,1]
	v_pk_add_f32 v[140:141], v[140:141], v[154:155]
	v_pk_add_f32 v[142:143], v[142:143], v[156:157]
	v_mov_b32_e32 v168, 0x3f000000
	v_mov_b32_e32 v169, 0x3e800000
	v_cndmask_b32_e64 v164, v168, v169, s[94:95]
	v_pk_fma_f32 v[158:159], v[164:165], v[140:141], v[144:145] op_sel_hi:[0,1,1] neg_lo:[0,0,1] neg_hi:[0,0,1]
	v_pk_fma_f32 v[160:161], v[164:165], v[142:143], v[146:147] op_sel_hi:[0,1,1] neg_lo:[0,0,1] neg_hi:[0,0,1]
	v_cvt_pk_bf16_f32 v162, v158, v159
	v_cvt_pk_bf16_f32 v163, v160, v161
	global_store_dwordx2 v36, v[162:163], s[96:97] offset:512
	s_waitcnt vmcnt(31)
	v_lshlrev_b32_e32 v144, 16, v90
	v_and_b32_e32 v145, 0xffff0000, v90
	v_lshlrev_b32_e32 v146, 16, v91
	v_and_b32_e32 v147, 0xffff0000, v91
	v_cndmask_b32_e64 v148, v86, v82, s[94:95]
	v_cndmask_b32_e64 v149, v87, v83, s[94:95]
	v_lshlrev_b32_e32 v150, 16, v148
	v_and_b32_e32 v151, 0xffff0000, v148
	v_lshlrev_b32_e32 v152, 16, v149
	v_and_b32_e32 v153, 0xffff0000, v149
	v_pk_add_f32 v[154:155], v[144:145], v[150:151] neg_lo:[0,1] neg_hi:[0,1]
	v_pk_add_f32 v[156:157], v[146:147], v[152:153] neg_lo:[0,1] neg_hi:[0,1]
	v_pk_add_f32 v[140:141], v[140:141], v[154:155]
	v_pk_add_f32 v[142:143], v[142:143], v[156:157]
	v_mov_b32_e32 v168, 0x3f000000
	v_mov_b32_e32 v169, 0x3e800000
	v_cndmask_b32_e64 v164, v168, v169, s[94:95]
	v_pk_fma_f32 v[158:159], v[164:165], v[140:141], v[144:145] op_sel_hi:[0,1,1] neg_lo:[0,0,1] neg_hi:[0,0,1]
	v_pk_fma_f32 v[160:161], v[164:165], v[142:143], v[146:147] op_sel_hi:[0,1,1] neg_lo:[0,0,1] neg_hi:[0,0,1]
	v_cvt_pk_bf16_f32 v162, v158, v159
	v_cvt_pk_bf16_f32 v163, v160, v161
	global_store_dwordx2 v36, v[162:163], s[96:97] offset:1024
	s_waitcnt vmcnt(31)
	v_lshlrev_b32_e32 v144, 16, v92
	v_and_b32_e32 v145, 0xffff0000, v92
	v_lshlrev_b32_e32 v146, 16, v93
	v_and_b32_e32 v147, 0xffff0000, v93
	v_cndmask_b32_e64 v148, v88, v84, s[94:95]
	v_cndmask_b32_e64 v149, v89, v85, s[94:95]
	v_lshlrev_b32_e32 v150, 16, v148
	v_and_b32_e32 v151, 0xffff0000, v148
	v_lshlrev_b32_e32 v152, 16, v149
	v_and_b32_e32 v153, 0xffff0000, v149
	v_pk_add_f32 v[154:155], v[144:145], v[150:151] neg_lo:[0,1] neg_hi:[0,1]
	v_pk_add_f32 v[156:157], v[146:147], v[152:153] neg_lo:[0,1] neg_hi:[0,1]
	v_pk_add_f32 v[140:141], v[140:141], v[154:155]
	v_pk_add_f32 v[142:143], v[142:143], v[156:157]
	v_mov_b32_e32 v168, 0x3f000000
	v_mov_b32_e32 v169, 0x3e800000
	v_cndmask_b32_e64 v164, v168, v169, s[94:95]
	v_pk_fma_f32 v[158:159], v[164:165], v[140:141], v[144:145] op_sel_hi:[0,1,1] neg_lo:[0,0,1] neg_hi:[0,0,1]
	v_pk_fma_f32 v[160:161], v[164:165], v[142:143], v[146:147] op_sel_hi:[0,1,1] neg_lo:[0,0,1] neg_hi:[0,0,1]
	v_cvt_pk_bf16_f32 v162, v158, v159
	v_cvt_pk_bf16_f32 v163, v160, v161
	global_store_dwordx2 v36, v[162:163], s[96:97] offset:1536
	s_waitcnt vmcnt(31)
	v_lshlrev_b32_e32 v144, 16, v94
	v_and_b32_e32 v145, 0xffff0000, v94
	v_lshlrev_b32_e32 v146, 16, v95
	v_and_b32_e32 v147, 0xffff0000, v95
	v_cndmask_b32_e64 v148, v90, v86, s[94:95]
	v_cndmask_b32_e64 v149, v91, v87, s[94:95]
	v_lshlrev_b32_e32 v150, 16, v148
	v_and_b32_e32 v151, 0xffff0000, v148
	v_lshlrev_b32_e32 v152, 16, v149
	v_and_b32_e32 v153, 0xffff0000, v149
	v_pk_add_f32 v[154:155], v[144:145], v[150:151] neg_lo:[0,1] neg_hi:[0,1]
	v_pk_add_f32 v[156:157], v[146:147], v[152:153] neg_lo:[0,1] neg_hi:[0,1]
	v_pk_add_f32 v[140:141], v[140:141], v[154:155]
	v_pk_add_f32 v[142:143], v[142:143], v[156:157]
	v_mov_b32_e32 v168, 0x3f000000
	v_mov_b32_e32 v169, 0x3e800000
	v_cndmask_b32_e64 v164, v168, v169, s[94:95]
	v_pk_fma_f32 v[158:159], v[164:165], v[140:141], v[144:145] op_sel_hi:[0,1,1] neg_lo:[0,0,1] neg_hi:[0,0,1]
	v_pk_fma_f32 v[160:161], v[164:165], v[142:143], v[146:147] op_sel_hi:[0,1,1] neg_lo:[0,0,1] neg_hi:[0,0,1]
	v_cvt_pk_bf16_f32 v162, v158, v159
	v_cvt_pk_bf16_f32 v163, v160, v161
	global_store_dwordx2 v36, v[162:163], s[96:97] offset:2048
	s_waitcnt vmcnt(31)
	v_lshlrev_b32_e32 v144, 16, v96
	v_and_b32_e32 v145, 0xffff0000, v96
	v_lshlrev_b32_e32 v146, 16, v97
	v_and_b32_e32 v147, 0xffff0000, v97
	v_cndmask_b32_e64 v148, v92, v88, s[94:95]
	v_cndmask_b32_e64 v149, v93, v89, s[94:95]
	v_lshlrev_b32_e32 v150, 16, v148
	v_and_b32_e32 v151, 0xffff0000, v148
	v_lshlrev_b32_e32 v152, 16, v149
	v_and_b32_e32 v153, 0xffff0000, v149
	v_pk_add_f32 v[154:155], v[144:145], v[150:151] neg_lo:[0,1] neg_hi:[0,1]
	v_pk_add_f32 v[156:157], v[146:147], v[152:153] neg_lo:[0,1] neg_hi:[0,1]
	v_pk_add_f32 v[140:141], v[140:141], v[154:155]
	v_pk_add_f32 v[142:143], v[142:143], v[156:157]
	v_mov_b32_e32 v168, 0x3f000000
	v_mov_b32_e32 v169, 0x3e800000
	v_cndmask_b32_e64 v164, v168, v169, s[94:95]
	v_pk_fma_f32 v[158:159], v[164:165], v[140:141], v[144:145] op_sel_hi:[0,1,1] neg_lo:[0,0,1] neg_hi:[0,0,1]
	v_pk_fma_f32 v[160:161], v[164:165], v[142:143], v[146:147] op_sel_hi:[0,1,1] neg_lo:[0,0,1] neg_hi:[0,0,1]
	v_cvt_pk_bf16_f32 v162, v158, v159
	v_cvt_pk_bf16_f32 v163, v160, v161
	global_store_dwordx2 v36, v[162:163], s[96:97] offset:2560
	s_waitcnt vmcnt(31)
; #define GAS __attribute__((address_space(1)))
; __device__ __forceinline__ unsigned pk2(float lo, float hi) { f32x2_t v = {lo, hi}; bf16x2_t b = __builtin_convertvector(v, bf16x2_t); return __builtin_bit_cast(unsigned, b); }
; #define U_LD(p) ({ const v2u w_ = *(const v2u*)(p); (f32x4){bflo(w_.x), bfhi(w_.x), bflo(w_.y), bfhi(w_.y)}; })
; __device__ __forceinline__ void p3_pool(Frame& F) {
;     ...
;         for (int i = 0; i < nsteps; ++i) {
;             const int s = s0 - 15 + i;
;             const int so = s - w;
;             f32x4 n0 = (f32x4){0.f, 0.f, 0.f, 0.f}, o0 = n0;
;             if (isP) {
;                 if (s >= 0) n0 = U_LD(U + (mbase + s) * 512 + c0);
;                 if (i >= w && so >= 0) o0 = U_LD(U + (mbase + so) * 512 + c0);
;             } else {
;                 if (s >= 0) n0 = U_LD(U + (mbase + s) * 512 + c0); else n0 = *(const f32x4*)(state_pool + ((size_t)b * 15 + (s + 15)) * 512 + c0);
;                 if (i >= w) { if (so >= 0) o0 = U_LD(U + (mbase + so) * 512 + c0); else o0 = *(const f32x4*)(state_pool + ((size_t)b * 15 + (so + 15)) * 512 + c0); }
;             }
;             S0 += n0 - o0;
;             if (i >= 15) {
;                 const int cnt = isP ? (w < s + 1 ? w : s + 1) : w; const float inv = 1.f / (float)cnt;
;                 const f32x4 d0 = S0 * inv - n0;
;                 v2u wv; wv.x = pk2(d0[0], d0[1]); wv.y = pk2(d0[2], d0[3]);
;                 *(GAS v2u*)(D + (size_t)(c0 >> 8) * ((size_t)MT * 256) + (mbase + s) * 256 + (c0 & 255)) = wv;
	v_lshlrev_b32_e32 v144, 16, v98
	v_and_b32_e32 v145, 0xffff0000, v98
	v_lshlrev_b32_e32 v146, 16, v99
	v_and_b32_e32 v147, 0xffff0000, v99
	v_cndmask_b32_e64 v148, v94, v90, s[94:95]
	v_cndmask_b32_e64 v149, v95, v91, s[94:95]
	v_lshlrev_b32_e32 v150, 16, v148
	v_and_b32_e32 v151, 0xffff0000, v148
	v_lshlrev_b32_e32 v152, 16, v149
	v_and_b32_e32 v153, 0xffff0000, v149
	v_pk_add_f32 v[154:155], v[144:145], v[150:151] neg_lo:[0,1] neg_hi:[0,1]
	v_pk_add_f32 v[156:157], v[146:147], v[152:153] neg_lo:[0,1] neg_hi:[0,1]
	v_pk_add_f32 v[140:141], v[140:141], v[154:155]
	v_pk_add_f32 v[142:143], v[142:143], v[156:157]
	v_mov_b32_e32 v168, 0x3f000000
	v_mov_b32_e32 v169, 0x3e800000
	v_cndmask_b32_e64 v164, v168, v169, s[94:95]
	v_pk_fma_f32 v[158:159], v[164:165], v[140:141], v[144:145] op_sel_hi:[0,1,1] neg_lo:[0,0,1] neg_hi:[0,0,1]
	v_pk_fma_f32 v[160:161], v[164:165], v[142:143], v[146:147] op_sel_hi:[0,1,1] neg_lo:[0,0,1] neg_hi:[0,0,1]
	v_cvt_pk_bf16_f32 v162, v158, v159
	v_cvt_pk_bf16_f32 v163, v160, v161
	global_store_dwordx2 v36, v[162:163], s[96:97] offset:3072
	s_waitcnt vmcnt(31)
	v_lshlrev_b32_e32 v144, 16, v100
	v_and_b32_e32 v145, 0xffff0000, v100
	v_lshlrev_b32_e32 v146, 16, v101
	v_and_b32_e32 v147, 0xffff0000, v101
	v_cndmask_b32_e64 v148, v96, v92, s[94:95]
	v_cndmask_b32_e64 v149, v97, v93, s[94:95]
	v_lshlrev_b32_e32 v150, 16, v148
	v_and_b32_e32 v151, 0xffff0000, v148
	v_lshlrev_b32_e32 v152, 16, v149
	v_and_b32_e32 v153, 0xffff0000, v149
	v_pk_add_f32 v[154:155], v[144:145], v[150:151] neg_lo:[0,1] neg_hi:[0,1]
	v_pk_add_f32 v[156:157], v[146:147], v[152:153] neg_lo:[0,1] neg_hi:[0,1]
	v_pk_add_f32 v[140:141], v[140:141], v[154:155]
	v_pk_add_f32 v[142:143], v[142:143], v[156:157]
	v_mov_b32_e32 v168, 0x3f000000
	v_mov_b32_e32 v169, 0x3e800000
	v_cndmask_b32_e64 v164, v168, v169, s[94:95]
	v_pk_fma_f32 v[158:159], v[164:165], v[140:141], v[144:145] op_sel_hi:[0,1,1] neg_lo:[0,0,1] neg_hi:[0,0,1]
	v_pk_fma_f32 v[160:161], v[164:165], v[142:143], v[146:147] op_sel_hi:[0,1,1] neg_lo:[0,0,1] neg_hi:[0,0,1]
	v_cvt_pk_bf16_f32 v162, v158, v159
	v_cvt_pk_bf16_f32 v163, v160, v161
	global_store_dwordx2 v36, v[162:163], s[96:97] offset:3584
	s_add_u32 s96, s96, 0x1000
	s_addc_u32 s97, s97, 0
	s_waitcnt vmcnt(31)
	v_lshlrev_b32_e32 v144, 16, v102
	v_and_b32_e32 v145, 0xffff0000, v102
	v_lshlrev_b32_e32 v146, 16, v103
	v_and_b32_e32 v147, 0xffff0000, v103
	v_cndmask_b32_e64 v148, v98, v94, s[94:95]
	v_cndmask_b32_e64 v149, v99, v95, s[94:95]
	v_lshlrev_b32_e32 v150, 16, v148
	v_and_b32_e32 v151, 0xffff0000, v148
	v_lshlrev_b32_e32 v152, 16, v149
	v_and_b32_e32 v153, 0xffff0000, v149
	v_pk_add_f32 v[154:155], v[144:145], v[150:151] neg_lo:[0,1] neg_hi:[0,1]
	v_pk_add_f32 v[156:157], v[146:147], v[152:153] neg_lo:[0,1] neg_hi:[0,1]
	v_pk_add_f32 v[140:141], v[140:141], v[154:155]
	v_pk_add_f32 v[142:143], v[142:143], v[156:157]
	v_pk_fma_f32 v[158:159], v[164:165], v[140:141], v[144:145] op_sel_hi:[0,1,1] neg_lo:[0,0,1] neg_hi:[0,0,1]
	v_pk_fma_f32 v[160:161], v[164:165], v[142:143], v[146:147] op_sel_hi:[0,1,1] neg_lo:[0,0,1] neg_hi:[0,0,1]
	v_cvt_pk_bf16_f32 v162, v158, v159
	v_cvt_pk_bf16_f32 v163, v160, v161
	global_store_dwordx2 v36, v[162:163], s[96:97]
	s_waitcnt vmcnt(31)
	v_lshlrev_b32_e32 v144, 16, v104
	v_and_b32_e32 v145, 0xffff0000, v104
	v_lshlrev_b32_e32 v146, 16, v105
	v_and_b32_e32 v147, 0xffff0000, v105
	v_cndmask_b32_e64 v148, v100, v96, s[94:95]
	v_cndmask_b32_e64 v149, v101, v97, s[94:95]
	v_lshlrev_b32_e32 v150, 16, v148
	v_and_b32_e32 v151, 0xffff0000, v148
	v_lshlrev_b32_e32 v152, 16, v149
	v_and_b32_e32 v153, 0xffff0000, v149
	v_pk_add_f32 v[154:155], v[144:145], v[150:151] neg_lo:[0,1] neg_hi:[0,1]
	v_pk_add_f32 v[156:157], v[146:147], v[152:153] neg_lo:[0,1] neg_hi:[0,1]
	v_pk_add_f32 v[140:141], v[140:141], v[154:155]
	v_pk_add_f32 v[142:143], v[142:143], v[156:157]
	v_pk_fma_f32 v[158:159], v[164:165], v[140:141], v[144:145] op_sel_hi:[0,1,1] neg_lo:[0,0,1] neg_hi:[0,0,1]
	v_pk_fma_f32 v[160:161], v[164:165], v[142:143], v[146:147] op_sel_hi:[0,1,1] neg_lo:[0,0,1] neg_hi:[0,0,1]
	v_cvt_pk_bf16_f32 v162, v158, v159
	v_cvt_pk_bf16_f32 v163, v160, v161
	global_store_dwordx2 v36, v[162:163], s[96:97] offset:512
	s_waitcnt vmcnt(31)
	v_lshlrev_b32_e32 v144, 16, v106
	v_and_b32_e32 v145, 0xffff0000, v106
	v_lshlrev_b32_e32 v146, 16, v107
	v_and_b32_e32 v147, 0xffff0000, v107
	v_cndmask_b32_e64 v148, v102, v98, s[94:95]
	v_cndmask_b32_e64 v149, v103, v99, s[94:95]
	v_lshlrev_b32_e32 v150, 16, v148
	v_and_b32_e32 v151, 0xffff0000, v148
	v_lshlrev_b32_e32 v152, 16, v149
	v_and_b32_e32 v153, 0xffff0000, v149
	v_pk_add_f32 v[154:155], v[144:145], v[150:151] neg_lo:[0,1] neg_hi:[0,1]
	v_pk_add_f32 v[156:157], v[146:147], v[152:153] neg_lo:[0,1] neg_hi:[0,1]
	v_pk_add_f32 v[140:141], v[140:141], v[154:155]
	v_pk_add_f32 v[142:143], v[142:143], v[156:157]
	v_pk_fma_f32 v[158:159], v[164:165], v[140:141], v[144:145] op_sel_hi:[0,1,1] neg_lo:[0,0,1] neg_hi:[0,0,1]
	v_pk_fma_f32 v[160:161], v[164:165], v[142:143], v[146:147] op_sel_hi:[0,1,1] neg_lo:[0,0,1] neg_hi:[0,0,1]
	v_cvt_pk_bf16_f32 v162, v158, v159
	v_cvt_pk_bf16_f32 v163, v160, v161
	global_store_dwordx2 v36, v[162:163], s[96:97] offset:1024
	s_waitcnt vmcnt(31)
; #define GAS __attribute__((address_space(1)))
; __device__ __forceinline__ unsigned pk2(float lo, float hi) { f32x2_t v = {lo, hi}; bf16x2_t b = __builtin_convertvector(v, bf16x2_t); return __builtin_bit_cast(unsigned, b); }
; #define U_LD(p) ({ const v2u w_ = *(const v2u*)(p); (f32x4){bflo(w_.x), bfhi(w_.x), bflo(w_.y), bfhi(w_.y)}; })
; __device__ __forceinline__ void p3_pool(Frame& F) {
;     ...
;         for (int i = 0; i < nsteps; ++i) {
;             const int s = s0 - 15 + i;
;             const int so = s - w;
;             f32x4 n0 = (f32x4){0.f, 0.f, 0.f, 0.f}, o0 = n0;
;             if (isP) {
;                 if (s >= 0) n0 = U_LD(U + (mbase + s) * 512 + c0);
;                 if (i >= w && so >= 0) o0 = U_LD(U + (mbase + so) * 512 + c0);
;             } else {
;                 if (s >= 0) n0 = U_LD(U + (mbase + s) * 512 + c0); else n0 = *(const f32x4*)(state_pool + ((size_t)b * 15 + (s + 15)) * 512 + c0);
;                 if (i >= w) { if (so >= 0) o0 = U_LD(U + (mbase + so) * 512 + c0); else o0 = *(const f32x4*)(state_pool + ((size_t)b * 15 + (so + 15)) * 512 + c0); }
;             }
;             S0 += n0 - o0;
;             if (i >= 15) {
;                 const int cnt = isP ? (w < s + 1 ? w : s + 1) : w; const float inv = 1.f / (float)cnt;
;                 const f32x4 d0 = S0 * inv - n0;
;                 v2u wv; wv.x = pk2(d0[0], d0[1]); wv.y = pk2(d0[2], d0[3]);
;                 *(GAS v2u*)(D + (size_t)(c0 >> 8) * ((size_t)MT * 256) + (mbase + s) * 256 + (c0 & 255)) = wv;
	v_lshlrev_b32_e32 v144, 16, v108
	v_and_b32_e32 v145, 0xffff0000, v108
	v_lshlrev_b32_e32 v146, 16, v109
	v_and_b32_e32 v147, 0xffff0000, v109
	v_cndmask_b32_e64 v148, v104, v100, s[94:95]
	v_cndmask_b32_e64 v149, v105, v101, s[94:95]
	v_lshlrev_b32_e32 v150, 16, v148
	v_and_b32_e32 v151, 0xffff0000, v148
	v_lshlrev_b32_e32 v152, 16, v149
	v_and_b32_e32 v153, 0xffff0000, v149
	v_pk_add_f32 v[154:155], v[144:145], v[150:151] neg_lo:[0,1] neg_hi:[0,1]
	v_pk_add_f32 v[156:157], v[146:147], v[152:153] neg_lo:[0,1] neg_hi:[0,1]
	v_pk_add_f32 v[140:141], v[140:141], v[154:155]
	v_pk_add_f32 v[142:143], v[142:143], v[156:157]
	v_pk_fma_f32 v[158:159], v[164:165], v[140:141], v[144:145] op_sel_hi:[0,1,1] neg_lo:[0,0,1] neg_hi:[0,0,1]
	v_pk_fma_f32 v[160:161], v[164:165], v[142:143], v[146:147] op_sel_hi:[0,1,1] neg_lo:[0,0,1] neg_hi:[0,0,1]
	v_cvt_pk_bf16_f32 v162, v158, v159
	v_cvt_pk_bf16_f32 v163, v160, v161
	global_store_dwordx2 v36, v[162:163], s[96:97] offset:1536
	s_waitcnt vmcnt(31)
	v_lshlrev_b32_e32 v144, 16, v110
	v_and_b32_e32 v145, 0xffff0000, v110
	v_lshlrev_b32_e32 v146, 16, v111
	v_and_b32_e32 v147, 0xffff0000, v111
	v_cndmask_b32_e64 v148, v106, v102, s[94:95]
	v_cndmask_b32_e64 v149, v107, v103, s[94:95]
	v_lshlrev_b32_e32 v150, 16, v148
	v_and_b32_e32 v151, 0xffff0000, v148
	v_lshlrev_b32_e32 v152, 16, v149
	v_and_b32_e32 v153, 0xffff0000, v149
	v_pk_add_f32 v[154:155], v[144:145], v[150:151] neg_lo:[0,1] neg_hi:[0,1]
	v_pk_add_f32 v[156:157], v[146:147], v[152:153] neg_lo:[0,1] neg_hi:[0,1]
	v_pk_add_f32 v[140:141], v[140:141], v[154:155]
	v_pk_add_f32 v[142:143], v[142:143], v[156:157]
	v_pk_fma_f32 v[158:159], v[164:165], v[140:141], v[144:145] op_sel_hi:[0,1,1] neg_lo:[0,0,1] neg_hi:[0,0,1]
	v_pk_fma_f32 v[160:161], v[164:165], v[142:143], v[146:147] op_sel_hi:[0,1,1] neg_lo:[0,0,1] neg_hi:[0,0,1]
	v_cvt_pk_bf16_f32 v162, v158, v159
	v_cvt_pk_bf16_f32 v163, v160, v161
	global_store_dwordx2 v36, v[162:163], s[96:97] offset:2048
	s_waitcnt vmcnt(31)
	v_lshlrev_b32_e32 v144, 16, v112
	v_and_b32_e32 v145, 0xffff0000, v112
	v_lshlrev_b32_e32 v146, 16, v113
	v_and_b32_e32 v147, 0xffff0000, v113
	v_cndmask_b32_e64 v148, v108, v104, s[94:95]
	v_cndmask_b32_e64 v149, v109, v105, s[94:95]
	v_lshlrev_b32_e32 v150, 16, v148
	v_and_b32_e32 v151, 0xffff0000, v148
	v_lshlrev_b32_e32 v152, 16, v149
	v_and_b32_e32 v153, 0xffff0000, v149
	v_pk_add_f32 v[154:155], v[144:145], v[150:151] neg_lo:[0,1] neg_hi:[0,1]
	v_pk_add_f32 v[156:157], v[146:147], v[152:153] neg_lo:[0,1] neg_hi:[0,1]
	v_pk_add_f32 v[140:141], v[140:141], v[154:155]
	v_pk_add_f32 v[142:143], v[142:143], v[156:157]
	v_pk_fma_f32 v[158:159], v[164:165], v[140:141], v[144:145] op_sel_hi:[0,1,1] neg_lo:[0,0,1] neg_hi:[0,0,1]
	v_pk_fma_f32 v[160:161], v[164:165], v[142:143], v[146:147] op_sel_hi:[0,1,1] neg_lo:[0,0,1] neg_hi:[0,0,1]
	v_cvt_pk_bf16_f32 v162, v158, v159
	v_cvt_pk_bf16_f32 v163, v160, v161
	global_store_dwordx2 v36, v[162:163], s[96:97] offset:2560
	s_waitcnt vmcnt(31)
	v_lshlrev_b32_e32 v144, 16, v114
	v_and_b32_e32 v145, 0xffff0000, v114
	v_lshlrev_b32_e32 v146, 16, v115
	v_and_b32_e32 v147, 0xffff0000, v115
	v_cndmask_b32_e64 v148, v110, v106, s[94:95]
	v_cndmask_b32_e64 v149, v111, v107, s[94:95]
	v_lshlrev_b32_e32 v150, 16, v148
	v_and_b32_e32 v151, 0xffff0000, v148
	v_lshlrev_b32_e32 v152, 16, v149
	v_and_b32_e32 v153, 0xffff0000, v149
	v_pk_add_f32 v[154:155], v[144:145], v[150:151] neg_lo:[0,1] neg_hi:[0,1]
	v_pk_add_f32 v[156:157], v[146:147], v[152:153] neg_lo:[0,1] neg_hi:[0,1]
	v_pk_add_f32 v[140:141], v[140:141], v[154:155]
	v_pk_add_f32 v[142:143], v[142:143], v[156:157]
	v_pk_fma_f32 v[158:159], v[164:165], v[140:141], v[144:145] op_sel_hi:[0,1,1] neg_lo:[0,0,1] neg_hi:[0,0,1]
	v_pk_fma_f32 v[160:161], v[164:165], v[142:143], v[146:147] op_sel_hi:[0,1,1] neg_lo:[0,0,1] neg_hi:[0,0,1]
	v_cvt_pk_bf16_f32 v162, v158, v159
	v_cvt_pk_bf16_f32 v163, v160, v161
	global_store_dwordx2 v36, v[162:163], s[96:97] offset:3072
	s_waitcnt vmcnt(31)
	v_lshlrev_b32_e32 v144, 16, v116
	v_and_b32_e32 v145, 0xffff0000, v116
	v_lshlrev_b32_e32 v146, 16, v117
	v_and_b32_e32 v147, 0xffff0000, v117
	v_cndmask_b32_e64 v148, v112, v108, s[94:95]
	v_cndmask_b32_e64 v149, v113, v109, s[94:95]
	v_lshlrev_b32_e32 v150, 16, v148
	v_and_b32_e32 v151, 0xffff0000, v148
	v_lshlrev_b32_e32 v152, 16, v149
	v_and_b32_e32 v153, 0xffff0000, v149
	v_pk_add_f32 v[154:155], v[144:145], v[150:151] neg_lo:[0,1] neg_hi:[0,1]
	v_pk_add_f32 v[156:157], v[146:147], v[152:153] neg_lo:[0,1] neg_hi:[0,1]
	v_pk_add_f32 v[140:141], v[140:141], v[154:155]
	v_pk_add_f32 v[142:143], v[142:143], v[156:157]
	v_pk_fma_f32 v[158:159], v[164:165], v[140:141], v[144:145] op_sel_hi:[0,1,1] neg_lo:[0,0,1] neg_hi:[0,0,1]
	v_pk_fma_f32 v[160:161], v[164:165], v[142:143], v[146:147] op_sel_hi:[0,1,1] neg_lo:[0,0,1] neg_hi:[0,0,1]
	v_cvt_pk_bf16_f32 v162, v158, v159
	v_cvt_pk_bf16_f32 v163, v160, v161
	global_store_dwordx2 v36, v[162:163], s[96:97] offset:3584
	s_add_u32 s96, s96, 0x1000
	s_addc_u32 s97, s97, 0
	s_waitcnt vmcnt(31)
	v_lshlrev_b32_e32 v144, 16, v118
	v_and_b32_e32 v145, 0xffff0000, v118
	v_lshlrev_b32_e32 v146, 16, v119
	v_and_b32_e32 v147, 0xffff0000, v119
	v_cndmask_b32_e64 v148, v114, v110, s[94:95]
	v_cndmask_b32_e64 v149, v115, v111, s[94:95]
	v_lshlrev_b32_e32 v150, 16, v148
	v_and_b32_e32 v151, 0xffff0000, v148
	v_lshlrev_b32_e32 v152, 16, v149
	v_and_b32_e32 v153, 0xffff0000, v149
	v_pk_add_f32 v[154:155], v[144:145], v[150:151] neg_lo:[0,1] neg_hi:[0,1]
	v_pk_add_f32 v[156:157], v[146:147], v[152:153] neg_lo:[0,1] neg_hi:[0,1]
	v_pk_add_f32 v[140:141], v[140:141], v[154:155]
	v_pk_add_f32 v[142:143], v[142:143], v[156:157]
	v_pk_fma_f32 v[158:159], v[164:165], v[140:141], v[144:145] op_sel_hi:[0,1,1] neg_lo:[0,0,1] neg_hi:[0,0,1]
	v_pk_fma_f32 v[160:161], v[164:165], v[142:143], v[146:147] op_sel_hi:[0,1,1] neg_lo:[0,0,1] neg_hi:[0,0,1]
	v_cvt_pk_bf16_f32 v162, v158, v159
	v_cvt_pk_bf16_f32 v163, v160, v161
	global_store_dwordx2 v36, v[162:163], s[96:97]
	s_waitcnt vmcnt(31)
; #define GAS __attribute__((address_space(1)))
; __device__ __forceinline__ unsigned pk2(float lo, float hi) { f32x2_t v = {lo, hi}; bf16x2_t b = __builtin_convertvector(v, bf16x2_t); return __builtin_bit_cast(unsigned, b); }
; #define U_LD(p) ({ const v2u w_ = *(const v2u*)(p); (f32x4){bflo(w_.x), bfhi(w_.x), bflo(w_.y), bfhi(w_.y)}; })
; __device__ __forceinline__ void p3_pool(Frame& F) {
;     ...
;         for (int i = 0; i < nsteps; ++i) {
;             const int s = s0 - 15 + i;
;             const int so = s - w;
;             f32x4 n0 = (f32x4){0.f, 0.f, 0.f, 0.f}, o0 = n0;
;             if (isP) {
;                 if (s >= 0) n0 = U_LD(U + (mbase + s) * 512 + c0);
;                 if (i >= w && so >= 0) o0 = U_LD(U + (mbase + so) * 512 + c0);
;             } else {
;                 if (s >= 0) n0 = U_LD(U + (mbase + s) * 512 + c0); else n0 = *(const f32x4*)(state_pool + ((size_t)b * 15 + (s + 15)) * 512 + c0);
;                 if (i >= w) { if (so >= 0) o0 = U_LD(U + (mbase + so) * 512 + c0); else o0 = *(const f32x4*)(state_pool + ((size_t)b * 15 + (so + 15)) * 512 + c0); }
;             }
;             S0 += n0 - o0;
;             if (i >= 15) {
;                 const int cnt = isP ? (w < s + 1 ? w : s + 1) : w; const float inv = 1.f / (float)cnt;
;                 const f32x4 d0 = S0 * inv - n0;
;                 v2u wv; wv.x = pk2(d0[0], d0[1]); wv.y = pk2(d0[2], d0[3]);
;                 *(GAS v2u*)(D + (size_t)(c0 >> 8) * ((size_t)MT * 256) + (mbase + s) * 256 + (c0 & 255)) = wv;
	v_lshlrev_b32_e32 v144, 16, v120
	v_and_b32_e32 v145, 0xffff0000, v120
	v_lshlrev_b32_e32 v146, 16, v121
	v_and_b32_e32 v147, 0xffff0000, v121
	v_cndmask_b32_e64 v148, v116, v112, s[94:95]
	v_cndmask_b32_e64 v149, v117, v113, s[94:95]
	v_lshlrev_b32_e32 v150, 16, v148
	v_and_b32_e32 v151, 0xffff0000, v148
	v_lshlrev_b32_e32 v152, 16, v149
	v_and_b32_e32 v153, 0xffff0000, v149
	v_pk_add_f32 v[154:155], v[144:145], v[150:151] neg_lo:[0,1] neg_hi:[0,1]
	v_pk_add_f32 v[156:157], v[146:147], v[152:153] neg_lo:[0,1] neg_hi:[0,1]
	v_pk_add_f32 v[140:141], v[140:141], v[154:155]
	v_pk_add_f32 v[142:143], v[142:143], v[156:157]
	v_pk_fma_f32 v[158:159], v[164:165], v[140:141], v[144:145] op_sel_hi:[0,1,1] neg_lo:[0,0,1] neg_hi:[0,0,1]
	v_pk_fma_f32 v[160:161], v[164:165], v[142:143], v[146:147] op_sel_hi:[0,1,1] neg_lo:[0,0,1] neg_hi:[0,0,1]
	v_cvt_pk_bf16_f32 v162, v158, v159
	v_cvt_pk_bf16_f32 v163, v160, v161
	global_store_dwordx2 v36, v[162:163], s[96:97] offset:512
	s_waitcnt vmcnt(31)
	v_lshlrev_b32_e32 v144, 16, v122
	v_and_b32_e32 v145, 0xffff0000, v122
	v_lshlrev_b32_e32 v146, 16, v123
	v_and_b32_e32 v147, 0xffff0000, v123
	v_cndmask_b32_e64 v148, v118, v114, s[94:95]
	v_cndmask_b32_e64 v149, v119, v115, s[94:95]
	v_lshlrev_b32_e32 v150, 16, v148
	v_and_b32_e32 v151, 0xffff0000, v148
	v_lshlrev_b32_e32 v152, 16, v149
	v_and_b32_e32 v153, 0xffff0000, v149
	v_pk_add_f32 v[154:155], v[144:145], v[150:151] neg_lo:[0,1] neg_hi:[0,1]
	v_pk_add_f32 v[156:157], v[146:147], v[152:153] neg_lo:[0,1] neg_hi:[0,1]
	v_pk_add_f32 v[140:141], v[140:141], v[154:155]
	v_pk_add_f32 v[142:143], v[142:143], v[156:157]
	v_pk_fma_f32 v[158:159], v[164:165], v[140:141], v[144:145] op_sel_hi:[0,1,1] neg_lo:[0,0,1] neg_hi:[0,0,1]
	v_pk_fma_f32 v[160:161], v[164:165], v[142:143], v[146:147] op_sel_hi:[0,1,1] neg_lo:[0,0,1] neg_hi:[0,0,1]
	v_cvt_pk_bf16_f32 v162, v158, v159
	v_cvt_pk_bf16_f32 v163, v160, v161
	global_store_dwordx2 v36, v[162:163], s[96:97] offset:1024
	s_waitcnt vmcnt(31)
	v_lshlrev_b32_e32 v144, 16, v124
	v_and_b32_e32 v145, 0xffff0000, v124
	v_lshlrev_b32_e32 v146, 16, v125
	v_and_b32_e32 v147, 0xffff0000, v125
	v_cndmask_b32_e64 v148, v120, v116, s[94:95]
	v_cndmask_b32_e64 v149, v121, v117, s[94:95]
	v_lshlrev_b32_e32 v150, 16, v148
	v_and_b32_e32 v151, 0xffff0000, v148
	v_lshlrev_b32_e32 v152, 16, v149
	v_and_b32_e32 v153, 0xffff0000, v149
	v_pk_add_f32 v[154:155], v[144:145], v[150:151] neg_lo:[0,1] neg_hi:[0,1]
	v_pk_add_f32 v[156:157], v[146:147], v[152:153] neg_lo:[0,1] neg_hi:[0,1]
	v_pk_add_f32 v[140:141], v[140:141], v[154:155]
	v_pk_add_f32 v[142:143], v[142:143], v[156:157]
	v_pk_fma_f32 v[158:159], v[164:165], v[140:141], v[144:145] op_sel_hi:[0,1,1] neg_lo:[0,0,1] neg_hi:[0,0,1]
	v_pk_fma_f32 v[160:161], v[164:165], v[142:143], v[146:147] op_sel_hi:[0,1,1] neg_lo:[0,0,1] neg_hi:[0,0,1]
	v_cvt_pk_bf16_f32 v162, v158, v159
	v_cvt_pk_bf16_f32 v163, v160, v161
	global_store_dwordx2 v36, v[162:163], s[96:97] offset:1536
	s_waitcnt vmcnt(31)
	v_lshlrev_b32_e32 v144, 16, v126
	v_and_b32_e32 v145, 0xffff0000, v126
	v_lshlrev_b32_e32 v146, 16, v127
	v_and_b32_e32 v147, 0xffff0000, v127
	v_cndmask_b32_e64 v148, v122, v118, s[94:95]
	v_cndmask_b32_e64 v149, v123, v119, s[94:95]
	v_lshlrev_b32_e32 v150, 16, v148
	v_and_b32_e32 v151, 0xffff0000, v148
	v_lshlrev_b32_e32 v152, 16, v149
	v_and_b32_e32 v153, 0xffff0000, v149
	v_pk_add_f32 v[154:155], v[144:145], v[150:151] neg_lo:[0,1] neg_hi:[0,1]
	v_pk_add_f32 v[156:157], v[146:147], v[152:153] neg_lo:[0,1] neg_hi:[0,1]
	v_pk_add_f32 v[140:141], v[140:141], v[154:155]
	v_pk_add_f32 v[142:143], v[142:143], v[156:157]
	v_pk_fma_f32 v[158:159], v[164:165], v[140:141], v[144:145] op_sel_hi:[0,1,1] neg_lo:[0,0,1] neg_hi:[0,0,1]
	v_pk_fma_f32 v[160:161], v[164:165], v[142:143], v[146:147] op_sel_hi:[0,1,1] neg_lo:[0,0,1] neg_hi:[0,0,1]
	v_cvt_pk_bf16_f32 v162, v158, v159
	v_cvt_pk_bf16_f32 v163, v160, v161
	global_store_dwordx2 v36, v[162:163], s[96:97] offset:2048
	s_waitcnt vmcnt(31)
	v_lshlrev_b32_e32 v144, 16, v128
	v_and_b32_e32 v145, 0xffff0000, v128
	v_lshlrev_b32_e32 v146, 16, v129
	v_and_b32_e32 v147, 0xffff0000, v129
	v_cndmask_b32_e64 v148, v124, v120, s[94:95]
	v_cndmask_b32_e64 v149, v125, v121, s[94:95]
	v_lshlrev_b32_e32 v150, 16, v148
	v_and_b32_e32 v151, 0xffff0000, v148
	v_lshlrev_b32_e32 v152, 16, v149
	v_and_b32_e32 v153, 0xffff0000, v149
	v_pk_add_f32 v[154:155], v[144:145], v[150:151] neg_lo:[0,1] neg_hi:[0,1]
	v_pk_add_f32 v[156:157], v[146:147], v[152:153] neg_lo:[0,1] neg_hi:[0,1]
	v_pk_add_f32 v[140:141], v[140:141], v[154:155]
	v_pk_add_f32 v[142:143], v[142:143], v[156:157]
	v_pk_fma_f32 v[158:159], v[164:165], v[140:141], v[144:145] op_sel_hi:[0,1,1] neg_lo:[0,0,1] neg_hi:[0,0,1]
	v_pk_fma_f32 v[160:161], v[164:165], v[142:143], v[146:147] op_sel_hi:[0,1,1] neg_lo:[0,0,1] neg_hi:[0,0,1]
	v_cvt_pk_bf16_f32 v162, v158, v159
	v_cvt_pk_bf16_f32 v163, v160, v161
	global_store_dwordx2 v36, v[162:163], s[96:97] offset:2560
	s_waitcnt vmcnt(31)
	v_lshlrev_b32_e32 v144, 16, v130
	v_and_b32_e32 v145, 0xffff0000, v130
	v_lshlrev_b32_e32 v146, 16, v131
	v_and_b32_e32 v147, 0xffff0000, v131
	v_cndmask_b32_e64 v148, v126, v122, s[94:95]
	v_cndmask_b32_e64 v149, v127, v123, s[94:95]
	v_lshlrev_b32_e32 v150, 16, v148
	v_and_b32_e32 v151, 0xffff0000, v148
	v_lshlrev_b32_e32 v152, 16, v149
	v_and_b32_e32 v153, 0xffff0000, v149
	v_pk_add_f32 v[154:155], v[144:145], v[150:151] neg_lo:[0,1] neg_hi:[0,1]
	v_pk_add_f32 v[156:157], v[146:147], v[152:153] neg_lo:[0,1] neg_hi:[0,1]
	v_pk_add_f32 v[140:141], v[140:141], v[154:155]
	v_pk_add_f32 v[142:143], v[142:143], v[156:157]
	v_pk_fma_f32 v[158:159], v[164:165], v[140:141], v[144:145] op_sel_hi:[0,1,1] neg_lo:[0,0,1] neg_hi:[0,0,1]
	v_pk_fma_f32 v[160:161], v[164:165], v[142:143], v[146:147] op_sel_hi:[0,1,1] neg_lo:[0,0,1] neg_hi:[0,0,1]
	v_cvt_pk_bf16_f32 v162, v158, v159
	v_cvt_pk_bf16_f32 v163, v160, v161
	global_store_dwordx2 v36, v[162:163], s[96:97] offset:3072
	s_waitcnt vmcnt(31)
	v_lshlrev_b32_e32 v144, 16, v132
	v_and_b32_e32 v145, 0xffff0000, v132
	v_lshlrev_b32_e32 v146, 16, v133
	v_and_b32_e32 v147, 0xffff0000, v133
	v_cndmask_b32_e64 v148, v128, v124, s[94:95]
	v_cndmask_b32_e64 v149, v129, v125, s[94:95]
	v_lshlrev_b32_e32 v150, 16, v148
	v_and_b32_e32 v151, 0xffff0000, v148
	v_lshlrev_b32_e32 v152, 16, v149
	v_and_b32_e32 v153, 0xffff0000, v149
	v_pk_add_f32 v[154:155], v[144:145], v[150:151] neg_lo:[0,1] neg_hi:[0,1]
	v_pk_add_f32 v[156:157], v[146:147], v[152:153] neg_lo:[0,1] neg_hi:[0,1]
	v_pk_add_f32 v[140:141], v[140:141], v[154:155]
	v_pk_add_f32 v[142:143], v[142:143], v[156:157]
	v_pk_fma_f32 v[158:159], v[164:165], v[140:141], v[144:145] op_sel_hi:[0,1,1] neg_lo:[0,0,1] neg_hi:[0,0,1]
	v_pk_fma_f32 v[160:161], v[164:165], v[142:143], v[146:147] op_sel_hi:[0,1,1] neg_lo:[0,0,1] neg_hi:[0,0,1]
	v_cvt_pk_bf16_f32 v162, v158, v159
	v_cvt_pk_bf16_f32 v163, v160, v161
	global_store_dwordx2 v36, v[162:163], s[96:97] offset:3584
	s_branch .LBB0_515
; #define GAS __attribute__((address_space(1)))
; __device__ __forceinline__ unsigned pk2(float lo, float hi) { f32x2_t v = {lo, hi}; bf16x2_t b = __builtin_convertvector(v, bf16x2_t); return __builtin_bit_cast(unsigned, b); }
; #define U_LD(p) ({ const v2u w_ = *(const v2u*)(p); (f32x4){bflo(w_.x), bfhi(w_.x), bflo(w_.y), bfhi(w_.y)}; })
; __device__ __forceinline__ void p3_pool(Frame& F) {
;     ...
;         for (int i = 0; i < nsteps; ++i) {
;             const int s = s0 - 15 + i;
;             const int so = s - w;
;             f32x4 n0 = (f32x4){0.f, 0.f, 0.f, 0.f}, o0 = n0;
;             if (isP) {
;                 if (s >= 0) n0 = U_LD(U + (mbase + s) * 512 + c0);
;                 if (i >= w && so >= 0) o0 = U_LD(U + (mbase + so) * 512 + c0);
;             } else {
;                 if (s >= 0) n0 = U_LD(U + (mbase + s) * 512 + c0); else n0 = *(const f32x4*)(state_pool + ((size_t)b * 15 + (s + 15)) * 512 + c0);
;                 if (i >= w) { if (so >= 0) o0 = U_LD(U + (mbase + so) * 512 + c0); else o0 = *(const f32x4*)(state_pool + ((size_t)b * 15 + (so + 15)) * 512 + c0); }
;             }
;             S0 += n0 - o0;
;             if (i >= 15) {
;                 const int cnt = isP ? (w < s + 1 ? w : s + 1) : w; const float inv = 1.f / (float)cnt;
;                 const f32x4 d0 = S0 * inv - n0;
;                 v2u wv; wv.x = pk2(d0[0], d0[1]); wv.y = pk2(d0[2], d0[3]);
;                 *(GAS v2u*)(D + (size_t)(c0 >> 8) * ((size_t)MT * 256) + (mbase + s) * 256 + (c0 & 255)) = wv;
.Lp3f_f1:
	v_mov_b32_e32 v140, 0
	v_mov_b32_e32 v141, 0
	v_mov_b32_e32 v142, 0
	v_mov_b32_e32 v143, 0
	v_mov_b32_e32 v166, 0
	v_mov_b32_e32 v167, 0
	s_mov_b64 s[96:97], s[90:91]
	s_waitcnt vmcnt(31)
	v_lshlrev_b32_e32 v144, 16, v70
	v_and_b32_e32 v145, 0xffff0000, v70
	v_lshlrev_b32_e32 v146, 16, v71
	v_and_b32_e32 v147, 0xffff0000, v71
	v_pk_add_f32 v[140:141], v[140:141], v[144:145]
	v_pk_add_f32 v[142:143], v[142:143], v[146:147]
	v_mov_b32_e32 v164, 0x3f800000
	v_pk_fma_f32 v[158:159], v[164:165], v[140:141], v[144:145] op_sel_hi:[0,1,1] neg_lo:[0,0,1] neg_hi:[0,0,1]
	v_pk_fma_f32 v[160:161], v[164:165], v[142:143], v[146:147] op_sel_hi:[0,1,1] neg_lo:[0,0,1] neg_hi:[0,0,1]
	v_cvt_pk_bf16_f32 v162, v158, v159
	v_cvt_pk_bf16_f32 v163, v160, v161
	global_store_dwordx2 v36, v[162:163], s[96:97]
	s_waitcnt vmcnt(31)
	v_lshlrev_b32_e32 v144, 16, v72
	v_and_b32_e32 v145, 0xffff0000, v72
	v_lshlrev_b32_e32 v146, 16, v73
	v_and_b32_e32 v147, 0xffff0000, v73
	v_pk_add_f32 v[140:141], v[140:141], v[144:145]
	v_pk_add_f32 v[142:143], v[142:143], v[146:147]
	v_mov_b32_e32 v164, 0x3f000000
	v_pk_fma_f32 v[158:159], v[164:165], v[140:141], v[144:145] op_sel_hi:[0,1,1] neg_lo:[0,0,1] neg_hi:[0,0,1]
	v_pk_fma_f32 v[160:161], v[164:165], v[142:143], v[146:147] op_sel_hi:[0,1,1] neg_lo:[0,0,1] neg_hi:[0,0,1]
	v_cvt_pk_bf16_f32 v162, v158, v159
	v_cvt_pk_bf16_f32 v163, v160, v161
	global_store_dwordx2 v36, v[162:163], s[96:97] offset:512
	s_waitcnt vmcnt(31)
	v_lshlrev_b32_e32 v144, 16, v74
	v_and_b32_e32 v145, 0xffff0000, v74
	v_lshlrev_b32_e32 v146, 16, v75
	v_and_b32_e32 v147, 0xffff0000, v75
	v_pk_add_f32 v[140:141], v[140:141], v[144:145]
	v_pk_add_f32 v[142:143], v[142:143], v[146:147]
	v_mov_b32_e32 v164, 0x3eaaaaab
	v_pk_fma_f32 v[158:159], v[164:165], v[140:141], v[144:145] op_sel_hi:[0,1,1] neg_lo:[0,0,1] neg_hi:[0,0,1]
	v_pk_fma_f32 v[160:161], v[164:165], v[142:143], v[146:147] op_sel_hi:[0,1,1] neg_lo:[0,0,1] neg_hi:[0,0,1]
	v_cvt_pk_bf16_f32 v162, v158, v159
	v_cvt_pk_bf16_f32 v163, v160, v161
	global_store_dwordx2 v36, v[162:163], s[96:97] offset:1024
	s_waitcnt vmcnt(31)
	v_lshlrev_b32_e32 v144, 16, v76
	v_and_b32_e32 v145, 0xffff0000, v76
	v_lshlrev_b32_e32 v146, 16, v77
	v_and_b32_e32 v147, 0xffff0000, v77
	v_pk_add_f32 v[140:141], v[140:141], v[144:145]
	v_pk_add_f32 v[142:143], v[142:143], v[146:147]
	v_mov_b32_e32 v164, 0x3e800000
	v_pk_fma_f32 v[158:159], v[164:165], v[140:141], v[144:145] op_sel_hi:[0,1,1] neg_lo:[0,0,1] neg_hi:[0,0,1]
	v_pk_fma_f32 v[160:161], v[164:165], v[142:143], v[146:147] op_sel_hi:[0,1,1] neg_lo:[0,0,1] neg_hi:[0,0,1]
	v_cvt_pk_bf16_f32 v162, v158, v159
	v_cvt_pk_bf16_f32 v163, v160, v161
	global_store_dwordx2 v36, v[162:163], s[96:97] offset:1536
	s_waitcnt vmcnt(31)
	v_lshlrev_b32_e32 v144, 16, v78
	v_and_b32_e32 v145, 0xffff0000, v78
	v_lshlrev_b32_e32 v146, 16, v79
	v_and_b32_e32 v147, 0xffff0000, v79
	v_pk_add_f32 v[140:141], v[140:141], v[144:145]
	v_pk_add_f32 v[142:143], v[142:143], v[146:147]
	v_mov_b32_e32 v164, 0x3e4ccccd
	v_pk_fma_f32 v[158:159], v[164:165], v[140:141], v[144:145] op_sel_hi:[0,1,1] neg_lo:[0,0,1] neg_hi:[0,0,1]
	v_pk_fma_f32 v[160:161], v[164:165], v[142:143], v[146:147] op_sel_hi:[0,1,1] neg_lo:[0,0,1] neg_hi:[0,0,1]
	v_cvt_pk_bf16_f32 v162, v158, v159
	v_cvt_pk_bf16_f32 v163, v160, v161
	global_store_dwordx2 v36, v[162:163], s[96:97] offset:2048
	s_waitcnt vmcnt(31)
	v_lshlrev_b32_e32 v144, 16, v80
	v_and_b32_e32 v145, 0xffff0000, v80
	v_lshlrev_b32_e32 v146, 16, v81
	v_and_b32_e32 v147, 0xffff0000, v81
	v_pk_add_f32 v[140:141], v[140:141], v[144:145]
	v_pk_add_f32 v[142:143], v[142:143], v[146:147]
	v_mov_b32_e32 v164, 0x3e2aaaab
	v_pk_fma_f32 v[158:159], v[164:165], v[140:141], v[144:145] op_sel_hi:[0,1,1] neg_lo:[0,0,1] neg_hi:[0,0,1]
	v_pk_fma_f32 v[160:161], v[164:165], v[142:143], v[146:147] op_sel_hi:[0,1,1] neg_lo:[0,0,1] neg_hi:[0,0,1]
	v_cvt_pk_bf16_f32 v162, v158, v159
	v_cvt_pk_bf16_f32 v163, v160, v161
	global_store_dwordx2 v36, v[162:163], s[96:97] offset:2560
	s_waitcnt vmcnt(31)
	v_lshlrev_b32_e32 v144, 16, v82
	v_and_b32_e32 v145, 0xffff0000, v82
	v_lshlrev_b32_e32 v146, 16, v83
	v_and_b32_e32 v147, 0xffff0000, v83
	v_pk_add_f32 v[140:141], v[140:141], v[144:145]
	v_pk_add_f32 v[142:143], v[142:143], v[146:147]
	v_mov_b32_e32 v164, 0x3e124925
	v_pk_fma_f32 v[158:159], v[164:165], v[140:141], v[144:145] op_sel_hi:[0,1,1] neg_lo:[0,0,1] neg_hi:[0,0,1]
	v_pk_fma_f32 v[160:161], v[164:165], v[142:143], v[146:147] op_sel_hi:[0,1,1] neg_lo:[0,0,1] neg_hi:[0,0,1]
	v_cvt_pk_bf16_f32 v162, v158, v159
	v_cvt_pk_bf16_f32 v163, v160, v161
	global_store_dwordx2 v36, v[162:163], s[96:97] offset:3072
	s_waitcnt vmcnt(31)
	v_lshlrev_b32_e32 v144, 16, v84
	v_and_b32_e32 v145, 0xffff0000, v84
	v_lshlrev_b32_e32 v146, 16, v85
	v_and_b32_e32 v147, 0xffff0000, v85
	v_pk_add_f32 v[140:141], v[140:141], v[144:145]
	v_pk_add_f32 v[142:143], v[142:143], v[146:147]
	v_mov_b32_e32 v164, 0x3e000000
	v_pk_fma_f32 v[158:159], v[164:165], v[140:141], v[144:145] op_sel_hi:[0,1,1] neg_lo:[0,0,1] neg_hi:[0,0,1]
	v_pk_fma_f32 v[160:161], v[164:165], v[142:143], v[146:147] op_sel_hi:[0,1,1] neg_lo:[0,0,1] neg_hi:[0,0,1]
	v_cvt_pk_bf16_f32 v162, v158, v159
	v_cvt_pk_bf16_f32 v163, v160, v161
	global_store_dwordx2 v36, v[162:163], s[96:97] offset:3584
	s_add_u32 s96, s96, 0x1000
	s_addc_u32 s97, s97, 0
	s_waitcnt vmcnt(31)
; #define GAS __attribute__((address_space(1)))
; __device__ __forceinline__ unsigned pk2(float lo, float hi) { f32x2_t v = {lo, hi}; bf16x2_t b = __builtin_convertvector(v, bf16x2_t); return __builtin_bit_cast(unsigned, b); }
; #define U_LD(p) ({ const v2u w_ = *(const v2u*)(p); (f32x4){bflo(w_.x), bfhi(w_.x), bflo(w_.y), bfhi(w_.y)}; })
; __device__ __forceinline__ void p3_pool(Frame& F) {
;     ...
;         for (int i = 0; i < nsteps; ++i) {
;             const int s = s0 - 15 + i;
;             const int so = s - w;
;             f32x4 n0 = (f32x4){0.f, 0.f, 0.f, 0.f}, o0 = n0;
;             if (isP) {
;                 if (s >= 0) n0 = U_LD(U + (mbase + s) * 512 + c0);
;                 if (i >= w && so >= 0) o0 = U_LD(U + (mbase + so) * 512 + c0);
;             } else {
;                 if (s >= 0) n0 = U_LD(U + (mbase + s) * 512 + c0); else n0 = *(const f32x4*)(state_pool + ((size_t)b * 15 + (s + 15)) * 512 + c0);
;                 if (i >= w) { if (so >= 0) o0 = U_LD(U + (mbase + so) * 512 + c0); else o0 = *(const f32x4*)(state_pool + ((size_t)b * 15 + (so + 15)) * 512 + c0); }
;             }
;             S0 += n0 - o0;
;             if (i >= 15) {
;                 const int cnt = isP ? (w < s + 1 ? w : s + 1) : w; const float inv = 1.f / (float)cnt;
;                 const f32x4 d0 = S0 * inv - n0;
;                 v2u wv; wv.x = pk2(d0[0], d0[1]); wv.y = pk2(d0[2], d0[3]);
;                 *(GAS v2u*)(D + (size_t)(c0 >> 8) * ((size_t)MT * 256) + (mbase + s) * 256 + (c0 & 255)) = wv;
	v_lshlrev_b32_e32 v144, 16, v86
	v_and_b32_e32 v145, 0xffff0000, v86
	v_lshlrev_b32_e32 v146, 16, v87
	v_and_b32_e32 v147, 0xffff0000, v87
	v_cndmask_b32_e64 v148, v70, v166, s[94:95]
	v_cndmask_b32_e64 v149, v71, v167, s[94:95]
	v_lshlrev_b32_e32 v150, 16, v148
	v_and_b32_e32 v151, 0xffff0000, v148
	v_lshlrev_b32_e32 v152, 16, v149
	v_and_b32_e32 v153, 0xffff0000, v149
	v_pk_add_f32 v[154:155], v[144:145], v[150:151] neg_lo:[0,1] neg_hi:[0,1]
	v_pk_add_f32 v[156:157], v[146:147], v[152:153] neg_lo:[0,1] neg_hi:[0,1]
	v_pk_add_f32 v[140:141], v[140:141], v[154:155]
	v_pk_add_f32 v[142:143], v[142:143], v[156:157]
	v_mov_b32_e32 v168, 0x3e000000
	v_mov_b32_e32 v169, 0x3de38e39
	v_cndmask_b32_e64 v164, v168, v169, s[94:95]
	v_pk_fma_f32 v[158:159], v[164:165], v[140:141], v[144:145] op_sel_hi:[0,1,1] neg_lo:[0,0,1] neg_hi:[0,0,1]
	v_pk_fma_f32 v[160:161], v[164:165], v[142:143], v[146:147] op_sel_hi:[0,1,1] neg_lo:[0,0,1] neg_hi:[0,0,1]
	v_cvt_pk_bf16_f32 v162, v158, v159
	v_cvt_pk_bf16_f32 v163, v160, v161
	global_store_dwordx2 v36, v[162:163], s[96:97]
	s_waitcnt vmcnt(31)
	v_lshlrev_b32_e32 v144, 16, v88
	v_and_b32_e32 v145, 0xffff0000, v88
	v_lshlrev_b32_e32 v146, 16, v89
	v_and_b32_e32 v147, 0xffff0000, v89
	v_cndmask_b32_e64 v148, v72, v166, s[94:95]
	v_cndmask_b32_e64 v149, v73, v167, s[94:95]
	v_lshlrev_b32_e32 v150, 16, v148
	v_and_b32_e32 v151, 0xffff0000, v148
	v_lshlrev_b32_e32 v152, 16, v149
	v_and_b32_e32 v153, 0xffff0000, v149
	v_pk_add_f32 v[154:155], v[144:145], v[150:151] neg_lo:[0,1] neg_hi:[0,1]
	v_pk_add_f32 v[156:157], v[146:147], v[152:153] neg_lo:[0,1] neg_hi:[0,1]
	v_pk_add_f32 v[140:141], v[140:141], v[154:155]
	v_pk_add_f32 v[142:143], v[142:143], v[156:157]
	v_mov_b32_e32 v168, 0x3e000000
	v_mov_b32_e32 v169, 0x3dcccccd
	v_cndmask_b32_e64 v164, v168, v169, s[94:95]
	v_pk_fma_f32 v[158:159], v[164:165], v[140:141], v[144:145] op_sel_hi:[0,1,1] neg_lo:[0,0,1] neg_hi:[0,0,1]
	v_pk_fma_f32 v[160:161], v[164:165], v[142:143], v[146:147] op_sel_hi:[0,1,1] neg_lo:[0,0,1] neg_hi:[0,0,1]
	v_cvt_pk_bf16_f32 v162, v158, v159
	v_cvt_pk_bf16_f32 v163, v160, v161
	global_store_dwordx2 v36, v[162:163], s[96:97] offset:512
	s_waitcnt vmcnt(31)
	v_lshlrev_b32_e32 v144, 16, v90
	v_and_b32_e32 v145, 0xffff0000, v90
	v_lshlrev_b32_e32 v146, 16, v91
	v_and_b32_e32 v147, 0xffff0000, v91
	v_cndmask_b32_e64 v148, v74, v166, s[94:95]
	v_cndmask_b32_e64 v149, v75, v167, s[94:95]
	v_lshlrev_b32_e32 v150, 16, v148
	v_and_b32_e32 v151, 0xffff0000, v148
	v_lshlrev_b32_e32 v152, 16, v149
	v_and_b32_e32 v153, 0xffff0000, v149
	v_pk_add_f32 v[154:155], v[144:145], v[150:151] neg_lo:[0,1] neg_hi:[0,1]
	v_pk_add_f32 v[156:157], v[146:147], v[152:153] neg_lo:[0,1] neg_hi:[0,1]
	v_pk_add_f32 v[140:141], v[140:141], v[154:155]
	v_pk_add_f32 v[142:143], v[142:143], v[156:157]
	v_mov_b32_e32 v168, 0x3e000000
	v_mov_b32_e32 v169, 0x3dba2e8c
	v_cndmask_b32_e64 v164, v168, v169, s[94:95]
	v_pk_fma_f32 v[158:159], v[164:165], v[140:141], v[144:145] op_sel_hi:[0,1,1] neg_lo:[0,0,1] neg_hi:[0,0,1]
	v_pk_fma_f32 v[160:161], v[164:165], v[142:143], v[146:147] op_sel_hi:[0,1,1] neg_lo:[0,0,1] neg_hi:[0,0,1]
	v_cvt_pk_bf16_f32 v162, v158, v159
	v_cvt_pk_bf16_f32 v163, v160, v161
	global_store_dwordx2 v36, v[162:163], s[96:97] offset:1024
	s_waitcnt vmcnt(31)
	v_lshlrev_b32_e32 v144, 16, v92
	v_and_b32_e32 v145, 0xffff0000, v92
	v_lshlrev_b32_e32 v146, 16, v93
	v_and_b32_e32 v147, 0xffff0000, v93
	v_cndmask_b32_e64 v148, v76, v166, s[94:95]
	v_cndmask_b32_e64 v149, v77, v167, s[94:95]
	v_lshlrev_b32_e32 v150, 16, v148
	v_and_b32_e32 v151, 0xffff0000, v148
	v_lshlrev_b32_e32 v152, 16, v149
	v_and_b32_e32 v153, 0xffff0000, v149
	v_pk_add_f32 v[154:155], v[144:145], v[150:151] neg_lo:[0,1] neg_hi:[0,1]
	v_pk_add_f32 v[156:157], v[146:147], v[152:153] neg_lo:[0,1] neg_hi:[0,1]
	v_pk_add_f32 v[140:141], v[140:141], v[154:155]
	v_pk_add_f32 v[142:143], v[142:143], v[156:157]
	v_mov_b32_e32 v168, 0x3e000000
	v_mov_b32_e32 v169, 0x3daaaaab
	v_cndmask_b32_e64 v164, v168, v169, s[94:95]
	v_pk_fma_f32 v[158:159], v[164:165], v[140:141], v[144:145] op_sel_hi:[0,1,1] neg_lo:[0,0,1] neg_hi:[0,0,1]
	v_pk_fma_f32 v[160:161], v[164:165], v[142:143], v[146:147] op_sel_hi:[0,1,1] neg_lo:[0,0,1] neg_hi:[0,0,1]
	v_cvt_pk_bf16_f32 v162, v158, v159
	v_cvt_pk_bf16_f32 v163, v160, v161
	global_store_dwordx2 v36, v[162:163], s[96:97] offset:1536
	s_waitcnt vmcnt(31)
	v_lshlrev_b32_e32 v144, 16, v94
	v_and_b32_e32 v145, 0xffff0000, v94
	v_lshlrev_b32_e32 v146, 16, v95
	v_and_b32_e32 v147, 0xffff0000, v95
	v_cndmask_b32_e64 v148, v78, v166, s[94:95]
	v_cndmask_b32_e64 v149, v79, v167, s[94:95]
	v_lshlrev_b32_e32 v150, 16, v148
	v_and_b32_e32 v151, 0xffff0000, v148
	v_lshlrev_b32_e32 v152, 16, v149
	v_and_b32_e32 v153, 0xffff0000, v149
	v_pk_add_f32 v[154:155], v[144:145], v[150:151] neg_lo:[0,1] neg_hi:[0,1]
	v_pk_add_f32 v[156:157], v[146:147], v[152:153] neg_lo:[0,1] neg_hi:[0,1]
	v_pk_add_f32 v[140:141], v[140:141], v[154:155]
	v_pk_add_f32 v[142:143], v[142:143], v[156:157]
	v_mov_b32_e32 v168, 0x3e000000
	v_mov_b32_e32 v169, 0x3d9d89d9
	v_cndmask_b32_e64 v164, v168, v169, s[94:95]
	v_pk_fma_f32 v[158:159], v[164:165], v[140:141], v[144:145] op_sel_hi:[0,1,1] neg_lo:[0,0,1] neg_hi:[0,0,1]
	v_pk_fma_f32 v[160:161], v[164:165], v[142:143], v[146:147] op_sel_hi:[0,1,1] neg_lo:[0,0,1] neg_hi:[0,0,1]
	v_cvt_pk_bf16_f32 v162, v158, v159
	v_cvt_pk_bf16_f32 v163, v160, v161
	global_store_dwordx2 v36, v[162:163], s[96:97] offset:2048
	s_waitcnt vmcnt(31)
; #define GAS __attribute__((address_space(1)))
; __device__ __forceinline__ unsigned pk2(float lo, float hi) { f32x2_t v = {lo, hi}; bf16x2_t b = __builtin_convertvector(v, bf16x2_t); return __builtin_bit_cast(unsigned, b); }
; #define U_LD(p) ({ const v2u w_ = *(const v2u*)(p); (f32x4){bflo(w_.x), bfhi(w_.x), bflo(w_.y), bfhi(w_.y)}; })
; __device__ __forceinline__ void p3_pool(Frame& F) {
;     ...
;         for (int i = 0; i < nsteps; ++i) {
;             const int s = s0 - 15 + i;
;             const int so = s - w;
;             f32x4 n0 = (f32x4){0.f, 0.f, 0.f, 0.f}, o0 = n0;
;             if (isP) {
;                 if (s >= 0) n0 = U_LD(U + (mbase + s) * 512 + c0);
;                 if (i >= w && so >= 0) o0 = U_LD(U + (mbase + so) * 512 + c0);
;             } else {
;                 if (s >= 0) n0 = U_LD(U + (mbase + s) * 512 + c0); else n0 = *(const f32x4*)(state_pool + ((size_t)b * 15 + (s + 15)) * 512 + c0);
;                 if (i >= w) { if (so >= 0) o0 = U_LD(U + (mbase + so) * 512 + c0); else o0 = *(const f32x4*)(state_pool + ((size_t)b * 15 + (so + 15)) * 512 + c0); }
;             }
;             S0 += n0 - o0;
;             if (i >= 15) {
;                 const int cnt = isP ? (w < s + 1 ? w : s + 1) : w; const float inv = 1.f / (float)cnt;
;                 const f32x4 d0 = S0 * inv - n0;
;                 v2u wv; wv.x = pk2(d0[0], d0[1]); wv.y = pk2(d0[2], d0[3]);
;                 *(GAS v2u*)(D + (size_t)(c0 >> 8) * ((size_t)MT * 256) + (mbase + s) * 256 + (c0 & 255)) = wv;
	v_lshlrev_b32_e32 v144, 16, v96
	v_and_b32_e32 v145, 0xffff0000, v96
	v_lshlrev_b32_e32 v146, 16, v97
	v_and_b32_e32 v147, 0xffff0000, v97
	v_cndmask_b32_e64 v148, v80, v166, s[94:95]
	v_cndmask_b32_e64 v149, v81, v167, s[94:95]
	v_lshlrev_b32_e32 v150, 16, v148
	v_and_b32_e32 v151, 0xffff0000, v148
	v_lshlrev_b32_e32 v152, 16, v149
	v_and_b32_e32 v153, 0xffff0000, v149
	v_pk_add_f32 v[154:155], v[144:145], v[150:151] neg_lo:[0,1] neg_hi:[0,1]
	v_pk_add_f32 v[156:157], v[146:147], v[152:153] neg_lo:[0,1] neg_hi:[0,1]
	v_pk_add_f32 v[140:141], v[140:141], v[154:155]
	v_pk_add_f32 v[142:143], v[142:143], v[156:157]
	v_mov_b32_e32 v168, 0x3e000000
	v_mov_b32_e32 v169, 0x3d924925
	v_cndmask_b32_e64 v164, v168, v169, s[94:95]
	v_pk_fma_f32 v[158:159], v[164:165], v[140:141], v[144:145] op_sel_hi:[0,1,1] neg_lo:[0,0,1] neg_hi:[0,0,1]
	v_pk_fma_f32 v[160:161], v[164:165], v[142:143], v[146:147] op_sel_hi:[0,1,1] neg_lo:[0,0,1] neg_hi:[0,0,1]
	v_cvt_pk_bf16_f32 v162, v158, v159
	v_cvt_pk_bf16_f32 v163, v160, v161
	global_store_dwordx2 v36, v[162:163], s[96:97] offset:2560
	s_waitcnt vmcnt(31)
	v_lshlrev_b32_e32 v144, 16, v98
	v_and_b32_e32 v145, 0xffff0000, v98
	v_lshlrev_b32_e32 v146, 16, v99
	v_and_b32_e32 v147, 0xffff0000, v99
	v_cndmask_b32_e64 v148, v82, v166, s[94:95]
	v_cndmask_b32_e64 v149, v83, v167, s[94:95]
	v_lshlrev_b32_e32 v150, 16, v148
	v_and_b32_e32 v151, 0xffff0000, v148
	v_lshlrev_b32_e32 v152, 16, v149
	v_and_b32_e32 v153, 0xffff0000, v149
	v_pk_add_f32 v[154:155], v[144:145], v[150:151] neg_lo:[0,1] neg_hi:[0,1]
	v_pk_add_f32 v[156:157], v[146:147], v[152:153] neg_lo:[0,1] neg_hi:[0,1]
	v_pk_add_f32 v[140:141], v[140:141], v[154:155]
	v_pk_add_f32 v[142:143], v[142:143], v[156:157]
	v_mov_b32_e32 v168, 0x3e000000
	v_mov_b32_e32 v169, 0x3d888889
	v_cndmask_b32_e64 v164, v168, v169, s[94:95]
	v_pk_fma_f32 v[158:159], v[164:165], v[140:141], v[144:145] op_sel_hi:[0,1,1] neg_lo:[0,0,1] neg_hi:[0,0,1]
	v_pk_fma_f32 v[160:161], v[164:165], v[142:143], v[146:147] op_sel_hi:[0,1,1] neg_lo:[0,0,1] neg_hi:[0,0,1]
	v_cvt_pk_bf16_f32 v162, v158, v159
	v_cvt_pk_bf16_f32 v163, v160, v161
	global_store_dwordx2 v36, v[162:163], s[96:97] offset:3072
	s_waitcnt vmcnt(31)
	v_lshlrev_b32_e32 v144, 16, v100
	v_and_b32_e32 v145, 0xffff0000, v100
	v_lshlrev_b32_e32 v146, 16, v101
	v_and_b32_e32 v147, 0xffff0000, v101
	v_cndmask_b32_e64 v148, v84, v166, s[94:95]
	v_cndmask_b32_e64 v149, v85, v167, s[94:95]
	v_lshlrev_b32_e32 v150, 16, v148
	v_and_b32_e32 v151, 0xffff0000, v148
	v_lshlrev_b32_e32 v152, 16, v149
	v_and_b32_e32 v153, 0xffff0000, v149
	v_pk_add_f32 v[154:155], v[144:145], v[150:151] neg_lo:[0,1] neg_hi:[0,1]
	v_pk_add_f32 v[156:157], v[146:147], v[152:153] neg_lo:[0,1] neg_hi:[0,1]
	v_pk_add_f32 v[140:141], v[140:141], v[154:155]
	v_pk_add_f32 v[142:143], v[142:143], v[156:157]
	v_mov_b32_e32 v168, 0x3e000000
	v_mov_b32_e32 v169, 0x3d800000
	v_cndmask_b32_e64 v164, v168, v169, s[94:95]
	v_pk_fma_f32 v[158:159], v[164:165], v[140:141], v[144:145] op_sel_hi:[0,1,1] neg_lo:[0,0,1] neg_hi:[0,0,1]
	v_pk_fma_f32 v[160:161], v[164:165], v[142:143], v[146:147] op_sel_hi:[0,1,1] neg_lo:[0,0,1] neg_hi:[0,0,1]
	v_cvt_pk_bf16_f32 v162, v158, v159
	v_cvt_pk_bf16_f32 v163, v160, v161
	global_store_dwordx2 v36, v[162:163], s[96:97] offset:3584
	s_add_u32 s96, s96, 0x1000
	s_addc_u32 s97, s97, 0
	s_waitcnt vmcnt(31)
	v_lshlrev_b32_e32 v144, 16, v102
	v_and_b32_e32 v145, 0xffff0000, v102
	v_lshlrev_b32_e32 v146, 16, v103
	v_and_b32_e32 v147, 0xffff0000, v103
	v_cndmask_b32_e64 v148, v86, v70, s[94:95]
	v_cndmask_b32_e64 v149, v87, v71, s[94:95]
	v_lshlrev_b32_e32 v150, 16, v148
	v_and_b32_e32 v151, 0xffff0000, v148
	v_lshlrev_b32_e32 v152, 16, v149
	v_and_b32_e32 v153, 0xffff0000, v149
	v_pk_add_f32 v[154:155], v[144:145], v[150:151] neg_lo:[0,1] neg_hi:[0,1]
	v_pk_add_f32 v[156:157], v[146:147], v[152:153] neg_lo:[0,1] neg_hi:[0,1]
	v_pk_add_f32 v[140:141], v[140:141], v[154:155]
	v_pk_add_f32 v[142:143], v[142:143], v[156:157]
	v_pk_fma_f32 v[158:159], v[164:165], v[140:141], v[144:145] op_sel_hi:[0,1,1] neg_lo:[0,0,1] neg_hi:[0,0,1]
	v_pk_fma_f32 v[160:161], v[164:165], v[142:143], v[146:147] op_sel_hi:[0,1,1] neg_lo:[0,0,1] neg_hi:[0,0,1]
	v_cvt_pk_bf16_f32 v162, v158, v159
	v_cvt_pk_bf16_f32 v163, v160, v161
	global_store_dwordx2 v36, v[162:163], s[96:97]
	s_waitcnt vmcnt(31)
	v_lshlrev_b32_e32 v144, 16, v104
	v_and_b32_e32 v145, 0xffff0000, v104
	v_lshlrev_b32_e32 v146, 16, v105
	v_and_b32_e32 v147, 0xffff0000, v105
	v_cndmask_b32_e64 v148, v88, v72, s[94:95]
	v_cndmask_b32_e64 v149, v89, v73, s[94:95]
	v_lshlrev_b32_e32 v150, 16, v148
	v_and_b32_e32 v151, 0xffff0000, v148
	v_lshlrev_b32_e32 v152, 16, v149
	v_and_b32_e32 v153, 0xffff0000, v149
	v_pk_add_f32 v[154:155], v[144:145], v[150:151] neg_lo:[0,1] neg_hi:[0,1]
	v_pk_add_f32 v[156:157], v[146:147], v[152:153] neg_lo:[0,1] neg_hi:[0,1]
	v_pk_add_f32 v[140:141], v[140:141], v[154:155]
	v_pk_add_f32 v[142:143], v[142:143], v[156:157]
	v_pk_fma_f32 v[158:159], v[164:165], v[140:141], v[144:145] op_sel_hi:[0,1,1] neg_lo:[0,0,1] neg_hi:[0,0,1]
	v_pk_fma_f32 v[160:161], v[164:165], v[142:143], v[146:147] op_sel_hi:[0,1,1] neg_lo:[0,0,1] neg_hi:[0,0,1]
	v_cvt_pk_bf16_f32 v162, v158, v159
	v_cvt_pk_bf16_f32 v163, v160, v161
	global_store_dwordx2 v36, v[162:163], s[96:97] offset:512
	s_waitcnt vmcnt(31)
; #define GAS __attribute__((address_space(1)))
; __device__ __forceinline__ unsigned pk2(float lo, float hi) { f32x2_t v = {lo, hi}; bf16x2_t b = __builtin_convertvector(v, bf16x2_t); return __builtin_bit_cast(unsigned, b); }
; #define U_LD(p) ({ const v2u w_ = *(const v2u*)(p); (f32x4){bflo(w_.x), bfhi(w_.x), bflo(w_.y), bfhi(w_.y)}; })
; __device__ __forceinline__ void p3_pool(Frame& F) {
;     ...
;         for (int i = 0; i < nsteps; ++i) {
;             const int s = s0 - 15 + i;
;             const int so = s - w;
;             f32x4 n0 = (f32x4){0.f, 0.f, 0.f, 0.f}, o0 = n0;
;             if (isP) {
;                 if (s >= 0) n0 = U_LD(U + (mbase + s) * 512 + c0);
;                 if (i >= w && so >= 0) o0 = U_LD(U + (mbase + so) * 512 + c0);
;             } else {
;                 if (s >= 0) n0 = U_LD(U + (mbase + s) * 512 + c0); else n0 = *(const f32x4*)(state_pool + ((size_t)b * 15 + (s + 15)) * 512 + c0);
;                 if (i >= w) { if (so >= 0) o0 = U_LD(U + (mbase + so) * 512 + c0); else o0 = *(const f32x4*)(state_pool + ((size_t)b * 15 + (so + 15)) * 512 + c0); }
;             }
;             S0 += n0 - o0;
;             if (i >= 15) {
;                 const int cnt = isP ? (w < s + 1 ? w : s + 1) : w; const float inv = 1.f / (float)cnt;
;                 const f32x4 d0 = S0 * inv - n0;
;                 v2u wv; wv.x = pk2(d0[0], d0[1]); wv.y = pk2(d0[2], d0[3]);
;                 *(GAS v2u*)(D + (size_t)(c0 >> 8) * ((size_t)MT * 256) + (mbase + s) * 256 + (c0 & 255)) = wv;
	v_lshlrev_b32_e32 v144, 16, v106
	v_and_b32_e32 v145, 0xffff0000, v106
	v_lshlrev_b32_e32 v146, 16, v107
	v_and_b32_e32 v147, 0xffff0000, v107
	v_cndmask_b32_e64 v148, v90, v74, s[94:95]
	v_cndmask_b32_e64 v149, v91, v75, s[94:95]
	v_lshlrev_b32_e32 v150, 16, v148
	v_and_b32_e32 v151, 0xffff0000, v148
	v_lshlrev_b32_e32 v152, 16, v149
	v_and_b32_e32 v153, 0xffff0000, v149
	v_pk_add_f32 v[154:155], v[144:145], v[150:151] neg_lo:[0,1] neg_hi:[0,1]
	v_pk_add_f32 v[156:157], v[146:147], v[152:153] neg_lo:[0,1] neg_hi:[0,1]
	v_pk_add_f32 v[140:141], v[140:141], v[154:155]
	v_pk_add_f32 v[142:143], v[142:143], v[156:157]
	v_pk_fma_f32 v[158:159], v[164:165], v[140:141], v[144:145] op_sel_hi:[0,1,1] neg_lo:[0,0,1] neg_hi:[0,0,1]
	v_pk_fma_f32 v[160:161], v[164:165], v[142:143], v[146:147] op_sel_hi:[0,1,1] neg_lo:[0,0,1] neg_hi:[0,0,1]
	v_cvt_pk_bf16_f32 v162, v158, v159
	v_cvt_pk_bf16_f32 v163, v160, v161
	global_store_dwordx2 v36, v[162:163], s[96:97] offset:1024
	s_waitcnt vmcnt(31)
	v_lshlrev_b32_e32 v144, 16, v108
	v_and_b32_e32 v145, 0xffff0000, v108
	v_lshlrev_b32_e32 v146, 16, v109
	v_and_b32_e32 v147, 0xffff0000, v109
	v_cndmask_b32_e64 v148, v92, v76, s[94:95]
	v_cndmask_b32_e64 v149, v93, v77, s[94:95]
	v_lshlrev_b32_e32 v150, 16, v148
	v_and_b32_e32 v151, 0xffff0000, v148
	v_lshlrev_b32_e32 v152, 16, v149
	v_and_b32_e32 v153, 0xffff0000, v149
	v_pk_add_f32 v[154:155], v[144:145], v[150:151] neg_lo:[0,1] neg_hi:[0,1]
	v_pk_add_f32 v[156:157], v[146:147], v[152:153] neg_lo:[0,1] neg_hi:[0,1]
	v_pk_add_f32 v[140:141], v[140:141], v[154:155]
	v_pk_add_f32 v[142:143], v[142:143], v[156:157]
	v_pk_fma_f32 v[158:159], v[164:165], v[140:141], v[144:145] op_sel_hi:[0,1,1] neg_lo:[0,0,1] neg_hi:[0,0,1]
	v_pk_fma_f32 v[160:161], v[164:165], v[142:143], v[146:147] op_sel_hi:[0,1,1] neg_lo:[0,0,1] neg_hi:[0,0,1]
	v_cvt_pk_bf16_f32 v162, v158, v159
	v_cvt_pk_bf16_f32 v163, v160, v161
	global_store_dwordx2 v36, v[162:163], s[96:97] offset:1536
	s_waitcnt vmcnt(31)
	v_lshlrev_b32_e32 v144, 16, v110
	v_and_b32_e32 v145, 0xffff0000, v110
	v_lshlrev_b32_e32 v146, 16, v111
	v_and_b32_e32 v147, 0xffff0000, v111
	v_cndmask_b32_e64 v148, v94, v78, s[94:95]
	v_cndmask_b32_e64 v149, v95, v79, s[94:95]
	v_lshlrev_b32_e32 v150, 16, v148
	v_and_b32_e32 v151, 0xffff0000, v148
	v_lshlrev_b32_e32 v152, 16, v149
	v_and_b32_e32 v153, 0xffff0000, v149
	v_pk_add_f32 v[154:155], v[144:145], v[150:151] neg_lo:[0,1] neg_hi:[0,1]
	v_pk_add_f32 v[156:157], v[146:147], v[152:153] neg_lo:[0,1] neg_hi:[0,1]
	v_pk_add_f32 v[140:141], v[140:141], v[154:155]
	v_pk_add_f32 v[142:143], v[142:143], v[156:157]
	v_pk_fma_f32 v[158:159], v[164:165], v[140:141], v[144:145] op_sel_hi:[0,1,1] neg_lo:[0,0,1] neg_hi:[0,0,1]
	v_pk_fma_f32 v[160:161], v[164:165], v[142:143], v[146:147] op_sel_hi:[0,1,1] neg_lo:[0,0,1] neg_hi:[0,0,1]
	v_cvt_pk_bf16_f32 v162, v158, v159
	v_cvt_pk_bf16_f32 v163, v160, v161
	global_store_dwordx2 v36, v[162:163], s[96:97] offset:2048
	s_waitcnt vmcnt(31)
	v_lshlrev_b32_e32 v144, 16, v112
	v_and_b32_e32 v145, 0xffff0000, v112
	v_lshlrev_b32_e32 v146, 16, v113
	v_and_b32_e32 v147, 0xffff0000, v113
	v_cndmask_b32_e64 v148, v96, v80, s[94:95]
	v_cndmask_b32_e64 v149, v97, v81, s[94:95]
	v_lshlrev_b32_e32 v150, 16, v148
	v_and_b32_e32 v151, 0xffff0000, v148
	v_lshlrev_b32_e32 v152, 16, v149
	v_and_b32_e32 v153, 0xffff0000, v149
	v_pk_add_f32 v[154:155], v[144:145], v[150:151] neg_lo:[0,1] neg_hi:[0,1]
	v_pk_add_f32 v[156:157], v[146:147], v[152:153] neg_lo:[0,1] neg_hi:[0,1]
	v_pk_add_f32 v[140:141], v[140:141], v[154:155]
	v_pk_add_f32 v[142:143], v[142:143], v[156:157]
	v_pk_fma_f32 v[158:159], v[164:165], v[140:141], v[144:145] op_sel_hi:[0,1,1] neg_lo:[0,0,1] neg_hi:[0,0,1]
	v_pk_fma_f32 v[160:161], v[164:165], v[142:143], v[146:147] op_sel_hi:[0,1,1] neg_lo:[0,0,1] neg_hi:[0,0,1]
	v_cvt_pk_bf16_f32 v162, v158, v159
	v_cvt_pk_bf16_f32 v163, v160, v161
	global_store_dwordx2 v36, v[162:163], s[96:97] offset:2560
	s_waitcnt vmcnt(31)
	v_lshlrev_b32_e32 v144, 16, v114
	v_and_b32_e32 v145, 0xffff0000, v114
	v_lshlrev_b32_e32 v146, 16, v115
	v_and_b32_e32 v147, 0xffff0000, v115
	v_cndmask_b32_e64 v148, v98, v82, s[94:95]
	v_cndmask_b32_e64 v149, v99, v83, s[94:95]
	v_lshlrev_b32_e32 v150, 16, v148
	v_and_b32_e32 v151, 0xffff0000, v148
	v_lshlrev_b32_e32 v152, 16, v149
	v_and_b32_e32 v153, 0xffff0000, v149
	v_pk_add_f32 v[154:155], v[144:145], v[150:151] neg_lo:[0,1] neg_hi:[0,1]
	v_pk_add_f32 v[156:157], v[146:147], v[152:153] neg_lo:[0,1] neg_hi:[0,1]
	v_pk_add_f32 v[140:141], v[140:141], v[154:155]
	v_pk_add_f32 v[142:143], v[142:143], v[156:157]
	v_pk_fma_f32 v[158:159], v[164:165], v[140:141], v[144:145] op_sel_hi:[0,1,1] neg_lo:[0,0,1] neg_hi:[0,0,1]
	v_pk_fma_f32 v[160:161], v[164:165], v[142:143], v[146:147] op_sel_hi:[0,1,1] neg_lo:[0,0,1] neg_hi:[0,0,1]
	v_cvt_pk_bf16_f32 v162, v158, v159
	v_cvt_pk_bf16_f32 v163, v160, v161
	global_store_dwordx2 v36, v[162:163], s[96:97] offset:3072
	s_waitcnt vmcnt(31)
	v_lshlrev_b32_e32 v144, 16, v116
	v_and_b32_e32 v145, 0xffff0000, v116
	v_lshlrev_b32_e32 v146, 16, v117
	v_and_b32_e32 v147, 0xffff0000, v117
	v_cndmask_b32_e64 v148, v100, v84, s[94:95]
	v_cndmask_b32_e64 v149, v101, v85, s[94:95]
	v_lshlrev_b32_e32 v150, 16, v148
	v_and_b32_e32 v151, 0xffff0000, v148
	v_lshlrev_b32_e32 v152, 16, v149
	v_and_b32_e32 v153, 0xffff0000, v149
	v_pk_add_f32 v[154:155], v[144:145], v[150:151] neg_lo:[0,1] neg_hi:[0,1]
	v_pk_add_f32 v[156:157], v[146:147], v[152:153] neg_lo:[0,1] neg_hi:[0,1]
	v_pk_add_f32 v[140:141], v[140:141], v[154:155]
	v_pk_add_f32 v[142:143], v[142:143], v[156:157]
	v_pk_fma_f32 v[158:159], v[164:165], v[140:141], v[144:145] op_sel_hi:[0,1,1] neg_lo:[0,0,1] neg_hi:[0,0,1]
	v_pk_fma_f32 v[160:161], v[164:165], v[142:143], v[146:147] op_sel_hi:[0,1,1] neg_lo:[0,0,1] neg_hi:[0,0,1]
	v_cvt_pk_bf16_f32 v162, v158, v159
	v_cvt_pk_bf16_f32 v163, v160, v161
	global_store_dwordx2 v36, v[162:163], s[96:97] offset:3584
	s_add_u32 s96, s96, 0x1000
	s_addc_u32 s97, s97, 0
	s_waitcnt vmcnt(31)
; #define GAS __attribute__((address_space(1)))
; __device__ __forceinline__ unsigned pk2(float lo, float hi) { f32x2_t v = {lo, hi}; bf16x2_t b = __builtin_convertvector(v, bf16x2_t); return __builtin_bit_cast(unsigned, b); }
; #define U_LD(p) ({ const v2u w_ = *(const v2u*)(p); (f32x4){bflo(w_.x), bfhi(w_.x), bflo(w_.y), bfhi(w_.y)}; })
; __device__ __forceinline__ void p3_pool(Frame& F) {
;     ...
;         for (int i = 0; i < nsteps; ++i) {
;             const int s = s0 - 15 + i;
;             const int so = s - w;
;             f32x4 n0 = (f32x4){0.f, 0.f, 0.f, 0.f}, o0 = n0;
;             if (isP) {
;                 if (s >= 0) n0 = U_LD(U + (mbase + s) * 512 + c0);
;                 if (i >= w && so >= 0) o0 = U_LD(U + (mbase + so) * 512 + c0);
;             } else {
;                 if (s >= 0) n0 = U_LD(U + (mbase + s) * 512 + c0); else n0 = *(const f32x4*)(state_pool + ((size_t)b * 15 + (s + 15)) * 512 + c0);
;                 if (i >= w) { if (so >= 0) o0 = U_LD(U + (mbase + so) * 512 + c0); else o0 = *(const f32x4*)(state_pool + ((size_t)b * 15 + (so + 15)) * 512 + c0); }
;             }
;             S0 += n0 - o0;
;             if (i >= 15) {
;                 const int cnt = isP ? (w < s + 1 ? w : s + 1) : w; const float inv = 1.f / (float)cnt;
;                 const f32x4 d0 = S0 * inv - n0;
;                 v2u wv; wv.x = pk2(d0[0], d0[1]); wv.y = pk2(d0[2], d0[3]);
;                 *(GAS v2u*)(D + (size_t)(c0 >> 8) * ((size_t)MT * 256) + (mbase + s) * 256 + (c0 & 255)) = wv;
	v_lshlrev_b32_e32 v144, 16, v118
	v_and_b32_e32 v145, 0xffff0000, v118
	v_lshlrev_b32_e32 v146, 16, v119
	v_and_b32_e32 v147, 0xffff0000, v119
	v_cndmask_b32_e64 v148, v102, v86, s[94:95]
	v_cndmask_b32_e64 v149, v103, v87, s[94:95]
	v_lshlrev_b32_e32 v150, 16, v148
	v_and_b32_e32 v151, 0xffff0000, v148
	v_lshlrev_b32_e32 v152, 16, v149
	v_and_b32_e32 v153, 0xffff0000, v149
	v_pk_add_f32 v[154:155], v[144:145], v[150:151] neg_lo:[0,1] neg_hi:[0,1]
	v_pk_add_f32 v[156:157], v[146:147], v[152:153] neg_lo:[0,1] neg_hi:[0,1]
	v_pk_add_f32 v[140:141], v[140:141], v[154:155]
	v_pk_add_f32 v[142:143], v[142:143], v[156:157]
	v_pk_fma_f32 v[158:159], v[164:165], v[140:141], v[144:145] op_sel_hi:[0,1,1] neg_lo:[0,0,1] neg_hi:[0,0,1]
	v_pk_fma_f32 v[160:161], v[164:165], v[142:143], v[146:147] op_sel_hi:[0,1,1] neg_lo:[0,0,1] neg_hi:[0,0,1]
	v_cvt_pk_bf16_f32 v162, v158, v159
	v_cvt_pk_bf16_f32 v163, v160, v161
	global_store_dwordx2 v36, v[162:163], s[96:97]
	s_waitcnt vmcnt(31)
	v_lshlrev_b32_e32 v144, 16, v120
	v_and_b32_e32 v145, 0xffff0000, v120
	v_lshlrev_b32_e32 v146, 16, v121
	v_and_b32_e32 v147, 0xffff0000, v121
	v_cndmask_b32_e64 v148, v104, v88, s[94:95]
	v_cndmask_b32_e64 v149, v105, v89, s[94:95]
	v_lshlrev_b32_e32 v150, 16, v148
	v_and_b32_e32 v151, 0xffff0000, v148
	v_lshlrev_b32_e32 v152, 16, v149
	v_and_b32_e32 v153, 0xffff0000, v149
	v_pk_add_f32 v[154:155], v[144:145], v[150:151] neg_lo:[0,1] neg_hi:[0,1]
	v_pk_add_f32 v[156:157], v[146:147], v[152:153] neg_lo:[0,1] neg_hi:[0,1]
	v_pk_add_f32 v[140:141], v[140:141], v[154:155]
	v_pk_add_f32 v[142:143], v[142:143], v[156:157]
	v_pk_fma_f32 v[158:159], v[164:165], v[140:141], v[144:145] op_sel_hi:[0,1,1] neg_lo:[0,0,1] neg_hi:[0,0,1]
	v_pk_fma_f32 v[160:161], v[164:165], v[142:143], v[146:147] op_sel_hi:[0,1,1] neg_lo:[0,0,1] neg_hi:[0,0,1]
	v_cvt_pk_bf16_f32 v162, v158, v159
	v_cvt_pk_bf16_f32 v163, v160, v161
	global_store_dwordx2 v36, v[162:163], s[96:97] offset:512
	s_waitcnt vmcnt(31)
	v_lshlrev_b32_e32 v144, 16, v122
	v_and_b32_e32 v145, 0xffff0000, v122
	v_lshlrev_b32_e32 v146, 16, v123
	v_and_b32_e32 v147, 0xffff0000, v123
	v_cndmask_b32_e64 v148, v106, v90, s[94:95]
	v_cndmask_b32_e64 v149, v107, v91, s[94:95]
	v_lshlrev_b32_e32 v150, 16, v148
	v_and_b32_e32 v151, 0xffff0000, v148
	v_lshlrev_b32_e32 v152, 16, v149
	v_and_b32_e32 v153, 0xffff0000, v149
	v_pk_add_f32 v[154:155], v[144:145], v[150:151] neg_lo:[0,1] neg_hi:[0,1]
	v_pk_add_f32 v[156:157], v[146:147], v[152:153] neg_lo:[0,1] neg_hi:[0,1]
	v_pk_add_f32 v[140:141], v[140:141], v[154:155]
	v_pk_add_f32 v[142:143], v[142:143], v[156:157]
	v_pk_fma_f32 v[158:159], v[164:165], v[140:141], v[144:145] op_sel_hi:[0,1,1] neg_lo:[0,0,1] neg_hi:[0,0,1]
	v_pk_fma_f32 v[160:161], v[164:165], v[142:143], v[146:147] op_sel_hi:[0,1,1] neg_lo:[0,0,1] neg_hi:[0,0,1]
	v_cvt_pk_bf16_f32 v162, v158, v159
	v_cvt_pk_bf16_f32 v163, v160, v161
	global_store_dwordx2 v36, v[162:163], s[96:97] offset:1024
	s_waitcnt vmcnt(31)
	v_lshlrev_b32_e32 v144, 16, v124
	v_and_b32_e32 v145, 0xffff0000, v124
	v_lshlrev_b32_e32 v146, 16, v125
	v_and_b32_e32 v147, 0xffff0000, v125
	v_cndmask_b32_e64 v148, v108, v92, s[94:95]
	v_cndmask_b32_e64 v149, v109, v93, s[94:95]
	v_lshlrev_b32_e32 v150, 16, v148
	v_and_b32_e32 v151, 0xffff0000, v148
	v_lshlrev_b32_e32 v152, 16, v149
	v_and_b32_e32 v153, 0xffff0000, v149
	v_pk_add_f32 v[154:155], v[144:145], v[150:151] neg_lo:[0,1] neg_hi:[0,1]
	v_pk_add_f32 v[156:157], v[146:147], v[152:153] neg_lo:[0,1] neg_hi:[0,1]
	v_pk_add_f32 v[140:141], v[140:141], v[154:155]
	v_pk_add_f32 v[142:143], v[142:143], v[156:157]
	v_pk_fma_f32 v[158:159], v[164:165], v[140:141], v[144:145] op_sel_hi:[0,1,1] neg_lo:[0,0,1] neg_hi:[0,0,1]
	v_pk_fma_f32 v[160:161], v[164:165], v[142:143], v[146:147] op_sel_hi:[0,1,1] neg_lo:[0,0,1] neg_hi:[0,0,1]
	v_cvt_pk_bf16_f32 v162, v158, v159
	v_cvt_pk_bf16_f32 v163, v160, v161
	global_store_dwordx2 v36, v[162:163], s[96:97] offset:1536
	s_waitcnt vmcnt(31)
; #define GAS __attribute__((address_space(1)))
; __device__ __forceinline__ unsigned pk2(float lo, float hi) { f32x2_t v = {lo, hi}; bf16x2_t b = __builtin_convertvector(v, bf16x2_t); return __builtin_bit_cast(unsigned, b); }
; #define U_LD(p) ({ const v2u w_ = *(const v2u*)(p); (f32x4){bflo(w_.x), bfhi(w_.x), bflo(w_.y), bfhi(w_.y)}; })
; __device__ __forceinline__ void p3_pool(Frame& F) {
;     ...
;         for (int i = 0; i < nsteps; ++i) {
;             const int s = s0 - 15 + i;
;             const int so = s - w;
;             f32x4 n0 = (f32x4){0.f, 0.f, 0.f, 0.f}, o0 = n0;
;             if (isP) {
;                 if (s >= 0) n0 = U_LD(U + (mbase + s) * 512 + c0);
;                 if (i >= w && so >= 0) o0 = U_LD(U + (mbase + so) * 512 + c0);
;             } else {
;                 if (s >= 0) n0 = U_LD(U + (mbase + s) * 512 + c0); else n0 = *(const f32x4*)(state_pool + ((size_t)b * 15 + (s + 15)) * 512 + c0);
;                 if (i >= w) { if (so >= 0) o0 = U_LD(U + (mbase + so) * 512 + c0); else o0 = *(const f32x4*)(state_pool + ((size_t)b * 15 + (so + 15)) * 512 + c0); }
;             }
;             S0 += n0 - o0;
;             if (i >= 15) {
;                 const int cnt = isP ? (w < s + 1 ? w : s + 1) : w; const float inv = 1.f / (float)cnt;
;                 const f32x4 d0 = S0 * inv - n0;
;                 v2u wv; wv.x = pk2(d0[0], d0[1]); wv.y = pk2(d0[2], d0[3]);
;                 *(GAS v2u*)(D + (size_t)(c0 >> 8) * ((size_t)MT * 256) + (mbase + s) * 256 + (c0 & 255)) = wv;
	v_lshlrev_b32_e32 v144, 16, v126
	v_and_b32_e32 v145, 0xffff0000, v126
	v_lshlrev_b32_e32 v146, 16, v127
	v_and_b32_e32 v147, 0xffff0000, v127
	v_cndmask_b32_e64 v148, v110, v94, s[94:95]
	v_cndmask_b32_e64 v149, v111, v95, s[94:95]
	v_lshlrev_b32_e32 v150, 16, v148
	v_and_b32_e32 v151, 0xffff0000, v148
	v_lshlrev_b32_e32 v152, 16, v149
	v_and_b32_e32 v153, 0xffff0000, v149
	v_pk_add_f32 v[154:155], v[144:145], v[150:151] neg_lo:[0,1] neg_hi:[0,1]
	v_pk_add_f32 v[156:157], v[146:147], v[152:153] neg_lo:[0,1] neg_hi:[0,1]
	v_pk_add_f32 v[140:141], v[140:141], v[154:155]
	v_pk_add_f32 v[142:143], v[142:143], v[156:157]
	v_pk_fma_f32 v[158:159], v[164:165], v[140:141], v[144:145] op_sel_hi:[0,1,1] neg_lo:[0,0,1] neg_hi:[0,0,1]
	v_pk_fma_f32 v[160:161], v[164:165], v[142:143], v[146:147] op_sel_hi:[0,1,1] neg_lo:[0,0,1] neg_hi:[0,0,1]
	v_cvt_pk_bf16_f32 v162, v158, v159
	v_cvt_pk_bf16_f32 v163, v160, v161
	global_store_dwordx2 v36, v[162:163], s[96:97] offset:2048
	s_waitcnt vmcnt(31)
	v_lshlrev_b32_e32 v144, 16, v128
	v_and_b32_e32 v145, 0xffff0000, v128
	v_lshlrev_b32_e32 v146, 16, v129
	v_and_b32_e32 v147, 0xffff0000, v129
	v_cndmask_b32_e64 v148, v112, v96, s[94:95]
	v_cndmask_b32_e64 v149, v113, v97, s[94:95]
	v_lshlrev_b32_e32 v150, 16, v148
	v_and_b32_e32 v151, 0xffff0000, v148
	v_lshlrev_b32_e32 v152, 16, v149
	v_and_b32_e32 v153, 0xffff0000, v149
	v_pk_add_f32 v[154:155], v[144:145], v[150:151] neg_lo:[0,1] neg_hi:[0,1]
	v_pk_add_f32 v[156:157], v[146:147], v[152:153] neg_lo:[0,1] neg_hi:[0,1]
	v_pk_add_f32 v[140:141], v[140:141], v[154:155]
	v_pk_add_f32 v[142:143], v[142:143], v[156:157]
	v_pk_fma_f32 v[158:159], v[164:165], v[140:141], v[144:145] op_sel_hi:[0,1,1] neg_lo:[0,0,1] neg_hi:[0,0,1]
	v_pk_fma_f32 v[160:161], v[164:165], v[142:143], v[146:147] op_sel_hi:[0,1,1] neg_lo:[0,0,1] neg_hi:[0,0,1]
	v_cvt_pk_bf16_f32 v162, v158, v159
	v_cvt_pk_bf16_f32 v163, v160, v161
	global_store_dwordx2 v36, v[162:163], s[96:97] offset:2560
	s_waitcnt vmcnt(31)
	v_lshlrev_b32_e32 v144, 16, v130
	v_and_b32_e32 v145, 0xffff0000, v130
	v_lshlrev_b32_e32 v146, 16, v131
	v_and_b32_e32 v147, 0xffff0000, v131
	v_cndmask_b32_e64 v148, v114, v98, s[94:95]
	v_cndmask_b32_e64 v149, v115, v99, s[94:95]
	v_lshlrev_b32_e32 v150, 16, v148
	v_and_b32_e32 v151, 0xffff0000, v148
	v_lshlrev_b32_e32 v152, 16, v149
	v_and_b32_e32 v153, 0xffff0000, v149
	v_pk_add_f32 v[154:155], v[144:145], v[150:151] neg_lo:[0,1] neg_hi:[0,1]
	v_pk_add_f32 v[156:157], v[146:147], v[152:153] neg_lo:[0,1] neg_hi:[0,1]
	v_pk_add_f32 v[140:141], v[140:141], v[154:155]
	v_pk_add_f32 v[142:143], v[142:143], v[156:157]
	v_pk_fma_f32 v[158:159], v[164:165], v[140:141], v[144:145] op_sel_hi:[0,1,1] neg_lo:[0,0,1] neg_hi:[0,0,1]
	v_pk_fma_f32 v[160:161], v[164:165], v[142:143], v[146:147] op_sel_hi:[0,1,1] neg_lo:[0,0,1] neg_hi:[0,0,1]
	v_cvt_pk_bf16_f32 v162, v158, v159
	v_cvt_pk_bf16_f32 v163, v160, v161
	global_store_dwordx2 v36, v[162:163], s[96:97] offset:3072
	s_waitcnt vmcnt(31)
	v_lshlrev_b32_e32 v144, 16, v132
	v_and_b32_e32 v145, 0xffff0000, v132
	v_lshlrev_b32_e32 v146, 16, v133
	v_and_b32_e32 v147, 0xffff0000, v133
	v_cndmask_b32_e64 v148, v116, v100, s[94:95]
	v_cndmask_b32_e64 v149, v117, v101, s[94:95]
	v_lshlrev_b32_e32 v150, 16, v148
	v_and_b32_e32 v151, 0xffff0000, v148
	v_lshlrev_b32_e32 v152, 16, v149
	v_and_b32_e32 v153, 0xffff0000, v149
	v_pk_add_f32 v[154:155], v[144:145], v[150:151] neg_lo:[0,1] neg_hi:[0,1]
	v_pk_add_f32 v[156:157], v[146:147], v[152:153] neg_lo:[0,1] neg_hi:[0,1]
	v_pk_add_f32 v[140:141], v[140:141], v[154:155]
	v_pk_add_f32 v[142:143], v[142:143], v[156:157]
	v_pk_fma_f32 v[158:159], v[164:165], v[140:141], v[144:145] op_sel_hi:[0,1,1] neg_lo:[0,0,1] neg_hi:[0,0,1]
	v_pk_fma_f32 v[160:161], v[164:165], v[142:143], v[146:147] op_sel_hi:[0,1,1] neg_lo:[0,0,1] neg_hi:[0,0,1]
	v_cvt_pk_bf16_f32 v162, v158, v159
	v_cvt_pk_bf16_f32 v163, v160, v161
	global_store_dwordx2 v36, v[162:163], s[96:97] offset:3584
	s_branch .LBB0_515
